# gelu constant folding (scale merged into polynomial coefficients, same f32 math) + PEER fold software-pipelined: next item's 12 global loads issued before the f32-MFMA compute, deferred bf16 stores
# baseline (speedup 1.0000x reference)
.LBB0_202:
	v_cvt_scalef32_pk_f16_fp8 v146, v30, 1.0
	v_cvt_scalef32_pk_f16_fp8 v30, v30, 1.0 op_sel:[1,0,0]
	v_pk_fma_f16 v30, v30, s49, v165
	v_cvt_scalef32_pk_f16_fp8 v147, v31, 1.0
	v_cvt_scalef32_pk_f16_fp8 v31, v31, 1.0 op_sel:[1,0,0]
	v_cvt_scalef32_pk_f16_fp8 v150, v26, 1.0
	v_cvt_scalef32_pk_f16_fp8 v26, v26, 1.0 op_sel:[1,0,0]
	v_pk_fma_f16 v31, v31, s49, v163
	v_cvt_scalef32_pk_f16_fp8 v148, v32, 1.0
	v_cvt_scalef32_pk_f16_fp8 v32, v32, 1.0 op_sel:[1,0,0]
	v_pk_fma_f16 v26, v26, s48, v30
	v_cvt_scalef32_pk_f16_fp8 v30, v27, 1.0
	v_cvt_scalef32_pk_f16_fp8 v27, v27, 1.0 op_sel:[1,0,0]
	v_pk_fma_f16 v32, v32, s49, v161
	v_cvt_scalef32_pk_f16_fp8 v149, v33, 1.0
	v_cvt_scalef32_pk_f16_fp8 v33, v33, 1.0 op_sel:[1,0,0]
	v_pk_fma_f16 v27, v27, s48, v31
	v_cvt_scalef32_pk_f16_fp8 v31, v28, 1.0
	v_cvt_scalef32_pk_f16_fp8 v28, v28, 1.0 op_sel:[1,0,0]
	v_pk_fma_f16 v33, v33, s49, v159
	v_pk_fma_f16 v28, v28, s48, v32
	v_cvt_scalef32_pk_f16_fp8 v32, v29, 1.0
	v_cvt_scalef32_pk_f16_fp8 v29, v29, 1.0 op_sel:[1,0,0]
	v_pk_fma_f16 v29, v29, s48, v33
	v_cvt_scalef32_pk_f16_fp8 v33, v22, 1.0
	v_cvt_scalef32_pk_f16_fp8 v22, v22, 1.0 op_sel:[1,0,0]
	v_pk_fma_f16 v22, v22, s47, v26
	v_cvt_scalef32_pk_f16_fp8 v26, v23, 1.0
	v_cvt_scalef32_pk_f16_fp8 v23, v23, 1.0 op_sel:[1,0,0]
	v_pk_fma_f16 v23, v23, s47, v27
	v_cvt_scalef32_pk_f16_fp8 v27, v24, 1.0
	v_cvt_scalef32_pk_f16_fp8 v24, v24, 1.0 op_sel:[1,0,0]
	v_pk_fma_f16 v147, v147, s49, v164
	v_pk_fma_f16 v24, v24, s47, v28
	v_cvt_scalef32_pk_f16_fp8 v28, v25, 1.0
	v_cvt_scalef32_pk_f16_fp8 v25, v25, 1.0 op_sel:[1,0,0]
	v_pk_fma_f16 v30, v30, s48, v147
	v_pk_fma_f16 v25, v25, s47, v29
	v_cvt_scalef32_pk_f16_fp8 v29, v18, 1.0
	v_cvt_scalef32_pk_f16_fp8 v18, v18, 1.0 op_sel:[1,0,0]
	v_pk_fma_f16 v148, v148, s49, v162
	v_pk_fma_f16 v26, v26, s47, v30
	v_pk_fma_f16 v147, v18, s46, v22
	v_cvt_scalef32_pk_f16_fp8 v18, v19, 1.0
	v_pk_fma_f16 v149, v149, s49, v160
	v_pk_fma_f16 v31, v31, s48, v148
	v_pk_fma_f16 v148, v18, s46, v26
	v_cvt_scalef32_pk_f16_fp8 v18, v19, 1.0 op_sel:[1,0,0]
	v_pk_fma_f16 v146, v146, s49, v166
	v_pk_fma_f16 v32, v32, s48, v149
	v_pk_fma_f16 v27, v27, s47, v31
	v_pk_fma_f16 v149, v18, s46, v23
	v_cvt_scalef32_pk_f16_fp8 v18, v20, 1.0
	v_pk_fma_f16 v146, v150, s48, v146
	v_pk_fma_f16 v150, v18, s46, v27
	v_cvt_scalef32_pk_f16_fp8 v18, v20, 1.0 op_sel:[1,0,0]
	v_pk_fma_f16 v28, v28, s47, v32
	v_pk_fma_f16 v151, v18, s46, v24
	v_cvt_scalef32_pk_f16_fp8 v18, v21, 1.0
	v_pk_fma_f16 v152, v18, s46, v28
	v_cvt_scalef32_pk_f16_fp8 v18, v21, 1.0 op_sel:[1,0,0]
	v_pk_fma_f16 v153, v18, s46, v25
	s_waitcnt vmcnt(7)
	v_mfma_f32_16x16x32_fp8_fp8 v[18:21], v[78:79], v[126:127], 0
	v_pk_fma_f16 v33, v33, s47, v146
	v_cmp_eq_u32_e32 vcc, 1, v100
	v_pk_fma_f16 v146, v29, s46, v33
	s_waitcnt vmcnt(5)
	v_mfma_f32_16x16x32_fp8_fp8 v[22:25], v[74:75], v[126:127], 0
	v_cmp_eq_u32_e64 s[94:95], 2, v100
	v_cmp_eq_u32_e64 s[96:97], 3, v100
	s_add_i32 s27, s27, 2
	s_waitcnt vmcnt(3)
	v_mfma_f32_16x16x32_fp8_fp8 v[26:29], v[70:71], v[126:127], 0
	v_add_u32_e32 v144, 32, v144
	s_add_i32 s43, s43, 8
	s_waitcnt vmcnt(1)
	v_mfma_f32_16x16x32_fp8_fp8 v[30:33], v[66:67], v[126:127], 0
	ds_bpermute_b32 v66, v168, v8
	s_waitcnt lgkmcnt(0)
	v_cvt_f32_f16_e32 v66, v66
	v_mfma_f32_16x16x32_fp8_fp8 v[18:21], v[80:81], v[128:129], v[18:21]
	v_mfma_f32_16x16x32_fp8_fp8 v[22:25], v[76:77], v[128:129], v[22:25]
	v_mfma_f32_16x16x32_fp8_fp8 v[26:29], v[72:73], v[128:129], v[26:29]
	s_nop 5
	v_cndmask_b32_e32 v18, v18, v19, vcc
	v_cndmask_b32_e64 v18, v18, v20, s[94:95]
	v_cndmask_b32_e64 v18, v18, v21, s[96:97]
	v_mfma_f32_16x16x32_fp8_fp8 v[30:33], v[68:69], v[128:129], v[30:33]
	v_cndmask_b32_e32 v19, v22, v23, vcc
	v_cndmask_b32_e32 v20, v26, v27, vcc
	v_cndmask_b32_e64 v19, v19, v24, s[94:95]
	v_cndmask_b32_e64 v20, v20, v28, s[94:95]
	v_cndmask_b32_e64 v19, v19, v25, s[96:97]
	s_nop 2
	v_cndmask_b32_e32 v21, v30, v31, vcc
	v_cndmask_b32_e64 v21, v21, v32, s[94:95]
	v_cndmask_b32_e64 v20, v20, v29, s[96:97]
	v_cndmask_b32_e64 v21, v21, v33, s[96:97]
	v_cndmask_b32_e64 v18, 0, v18, s[36:37]
	v_cndmask_b32_e64 v19, 0, v19, s[36:37]
	v_cndmask_b32_e64 v20, 0, v20, s[36:37]
	v_cndmask_b32_e64 v21, 0, v21, s[36:37]
	v_permlane32_swap_b32_e32 v18, v19
	s_nop 0
	v_permlane32_swap_b32_e32 v20, v21
	v_add_f32_e32 v18, v18, v19
	v_add_f32_e32 v19, v20, v21
	s_nop 1
	v_permlane16_swap_b32_e32 v18, v19
	v_add_f32_e32 v18, v18, v19
	v_cvt_scalef32_pk_f16_fp8 v20, v62, 1.0 op_sel:[1,0,0]
	v_cvt_scalef32_pk_f16_fp8 v21, v63, 1.0
	v_add_f32_dpp v18, v18, v18 quad_perm:[1,0,3,2] row_mask:0xf bank_mask:0xf bound_ctrl:1
	v_cvt_scalef32_pk_f16_fp8 v22, v63, 1.0 op_sel:[1,0,0]
	v_cvt_scalef32_pk_f16_fp8 v23, v64, 1.0
	v_add_f32_dpp v18, v18, v18 quad_perm:[2,3,0,1] row_mask:0xf bank_mask:0xf bound_ctrl:1
	v_cvt_scalef32_pk_f16_fp8 v24, v64, 1.0 op_sel:[1,0,0]
	v_cvt_scalef32_pk_f16_fp8 v25, v65, 1.0
	v_add_f32_dpp v18, v18, v18 row_half_mirror row_mask:0xf bank_mask:0xf bound_ctrl:1
	v_cvt_scalef32_pk_f16_fp8 v26, v65, 1.0 op_sel:[1,0,0]
	v_cvt_scalef32_pk_f16_fp8 v27, v58, 1.0
	v_add_f32_dpp v18, v18, v18 row_mirror row_mask:0xf bank_mask:0xf bound_ctrl:1
	v_mul_f32_e32 v18, 0x3c800000, v18
	v_mul_f32_e32 v19, 0xbdd2d3e7, v18
	v_fmaak_f32 v19, v18, v19, 0xc0135761
	v_mul_f32_e32 v19, v18, v19
	v_exp_f32_e32 v19, v19
	s_and_b64 vcc, exec, s[86:87]
	v_add_f32_e32 v19, 1.0, v19
	v_rcp_f32_e32 v19, v19
	s_nop 0
	v_mul_f32_e32 v18, v18, v19
	v_mul_f32_e32 v18, v18, v66
	v_mul_f32_e32 v18, 4.0, v18
	v_cvt_pk_f16_f32 v18, v18, v18
	v_cvt_scalef32_pk_f16_fp8 v19, v62, 1.0
	v_readlane_b32 s4, v18, s54
	s_nop 1
	v_pk_fma_f16 v19, v19, s4, v146
	v_pk_fma_f16 v20, v20, s4, v147
	v_pk_fma_f16 v21, v21, s4, v148
	v_pk_fma_f16 v22, v22, s4, v149
	v_pk_fma_f16 v23, v23, s4, v150
	v_pk_fma_f16 v24, v24, s4, v151
	v_pk_fma_f16 v25, v25, s4, v152
	v_pk_fma_f16 v26, v26, s4, v153
	v_readlane_b32 s4, v18, s55
	s_nop 1
	v_pk_fma_f16 v19, v27, s4, v19
	v_cvt_scalef32_pk_f16_fp8 v27, v58, 1.0 op_sel:[1,0,0]
	v_pk_fma_f16 v20, v27, s4, v20
	v_cvt_scalef32_pk_f16_fp8 v27, v59, 1.0
	v_pk_fma_f16 v21, v27, s4, v21
	v_cvt_scalef32_pk_f16_fp8 v27, v59, 1.0 op_sel:[1,0,0]
	v_pk_fma_f16 v22, v27, s4, v22
	v_cvt_scalef32_pk_f16_fp8 v27, v60, 1.0
	v_pk_fma_f16 v23, v27, s4, v23
	v_cvt_scalef32_pk_f16_fp8 v27, v60, 1.0 op_sel:[1,0,0]
	v_pk_fma_f16 v24, v27, s4, v24
	v_cvt_scalef32_pk_f16_fp8 v27, v61, 1.0
	v_pk_fma_f16 v25, v27, s4, v25
	v_cvt_scalef32_pk_f16_fp8 v27, v61, 1.0 op_sel:[1,0,0]
	v_pk_fma_f16 v26, v27, s4, v26
	v_readlane_b32 s4, v18, s56
	v_cvt_scalef32_pk_f16_fp8 v27, v54, 1.0
	s_nop 0
	v_pk_fma_f16 v19, v27, s4, v19
	v_cvt_scalef32_pk_f16_fp8 v27, v54, 1.0 op_sel:[1,0,0]
	v_pk_fma_f16 v20, v27, s4, v20
	v_cvt_scalef32_pk_f16_fp8 v27, v55, 1.0
	v_pk_fma_f16 v21, v27, s4, v21
	v_cvt_scalef32_pk_f16_fp8 v27, v55, 1.0 op_sel:[1,0,0]
	v_pk_fma_f16 v22, v27, s4, v22
	v_cvt_scalef32_pk_f16_fp8 v27, v56, 1.0
	v_pk_fma_f16 v23, v27, s4, v23
	v_cvt_scalef32_pk_f16_fp8 v27, v56, 1.0 op_sel:[1,0,0]
	v_pk_fma_f16 v24, v27, s4, v24
	v_cvt_scalef32_pk_f16_fp8 v27, v57, 1.0
	v_pk_fma_f16 v25, v27, s4, v25
	v_cvt_scalef32_pk_f16_fp8 v27, v57, 1.0 op_sel:[1,0,0]
	v_pk_fma_f16 v26, v27, s4, v26
	v_readlane_b32 s4, v18, s57
	s_waitcnt vmcnt(0)
	v_cvt_scalef32_pk_f16_fp8 v18, v50, 1.0
	v_pk_fma_f16 v166, v18, s4, v19
	v_cvt_scalef32_pk_f16_fp8 v18, v50, 1.0 op_sel:[1,0,0]
	v_pk_fma_f16 v165, v18, s4, v20
	v_cvt_scalef32_pk_f16_fp8 v18, v51, 1.0
	v_pk_fma_f16 v164, v18, s4, v21
	v_cvt_scalef32_pk_f16_fp8 v18, v51, 1.0 op_sel:[1,0,0]
	v_pk_fma_f16 v163, v18, s4, v22
	v_cvt_scalef32_pk_f16_fp8 v18, v52, 1.0
	v_pk_fma_f16 v162, v18, s4, v23
	v_cvt_scalef32_pk_f16_fp8 v18, v52, 1.0 op_sel:[1,0,0]
	v_pk_fma_f16 v161, v18, s4, v24
	v_cvt_scalef32_pk_f16_fp8 v18, v53, 1.0
	v_pk_fma_f16 v160, v18, s4, v25
	v_cvt_scalef32_pk_f16_fp8 v18, v53, 1.0 op_sel:[1,0,0]
	v_pk_fma_f16 v159, v18, s4, v26
	s_cbranch_vccnz .LBB0_239

.LBB0_205:
	s_waitcnt vmcnt(3)
	v_mfma_f32_16x16x32_fp8_fp8 v[18:21], v[34:35], v[86:87], 0
	s_add_i32 s46, s43, -11
	v_readlane_b32 s4, v1, s46
	s_add_i32 s47, s43, -10
	v_mfma_f32_16x16x32_fp8_fp8 v[50:53], v[36:37], v[82:83], v[18:21]
	v_mov_b32_e32 v54, v92
	s_bfe_u32 s4, s4, 0x100010
	v_readlane_b32 s5, v1, s47
	s_waitcnt vmcnt(2)
	v_mfma_f32_16x16x32_fp8_fp8 v[18:21], v[38:39], v[86:87], 0
	s_lshl_b32 s4, s4, 10
	s_mov_b32 s10, s14
	s_mov_b32 s11, s15
	s_bfe_u32 s5, s5, 0x100010
	v_mfma_f32_16x16x32_fp8_fp8 v[36:39], v[40:41], v[82:83], v[18:21]
	s_add_i32 s48, s43, -9
	s_lshl_b32 s5, s5, 10
	buffer_load_dwordx4 v[26:29], v54, s[8:11], s4 offen
	buffer_load_dwordx4 v[22:25], v54, s[8:11], s5 offen
	s_waitcnt vmcnt(3)
	v_mfma_f32_16x16x32_fp8_fp8 v[18:21], v[42:43], v[86:87], 0
	v_readlane_b32 s4, v1, s48
	s_add_i32 s49, s43, -8
	s_bfe_u32 s4, s4, 0x100010
	v_readlane_b32 s5, v1, s49
	s_lshl_b32 s4, s4, 10
	s_bfe_u32 s5, s5, 0x100010
	v_mfma_f32_16x16x32_fp8_fp8 v[40:43], v[44:45], v[82:83], v[18:21]
	s_lshl_b32 s5, s5, 10
	buffer_load_dwordx4 v[30:33], v54, s[8:11], s4 offen
	s_nop 0
	buffer_load_dwordx4 v[18:21], v54, s[8:11], s5 offen
	v_cmp_eq_u32_e32 vcc, 1, v100
	s_waitcnt vmcnt(4)
	v_mfma_f32_16x16x32_fp8_fp8 v[44:47], v[46:47], v[86:87], 0
	v_cmp_eq_u32_e64 s[94:95], 2, v100
	v_cndmask_b32_e32 v36, v36, v37, vcc
	v_cndmask_b32_e32 v35, v50, v51, vcc
	v_mfma_f32_16x16x32_fp8_fp8 v[44:47], v[48:49], v[82:83], v[44:47]
	v_cndmask_b32_e64 v36, v36, v38, s[94:95]
	v_cndmask_b32_e32 v37, v40, v41, vcc
	v_cndmask_b32_e64 v35, v35, v52, s[94:95]
	v_cmp_eq_u32_e64 s[96:97], 3, v100
	v_cndmask_b32_e64 v37, v37, v42, s[94:95]
	s_nop 2
	v_cndmask_b32_e32 v38, v44, v45, vcc
	v_cndmask_b32_e64 v38, v38, v46, s[94:95]
	v_cndmask_b32_e64 v35, v35, v53, s[96:97]
	v_cndmask_b32_e64 v36, v36, v39, s[96:97]
	v_cndmask_b32_e64 v37, v37, v43, s[96:97]
	v_cndmask_b32_e64 v38, v38, v47, s[96:97]
	v_cndmask_b32_e64 v35, 0, v35, s[36:37]
	v_cndmask_b32_e64 v36, 0, v36, s[36:37]
	v_cndmask_b32_e64 v37, 0, v37, s[36:37]
	v_cndmask_b32_e64 v38, 0, v38, s[36:37]
	v_permlane32_swap_b32_e32 v35, v36
	s_nop 0
	v_permlane32_swap_b32_e32 v37, v38
	v_add_f32_e32 v35, v35, v36
	v_add_f32_e32 v36, v37, v38
	s_nop 1
	v_permlane16_swap_b32_e32 v35, v36
	ds_bpermute_b32 v34, v144, v0
	v_add_f32_e32 v35, v35, v36
	v_add_u32_e32 v167, s42, v144
	s_nop 0
	v_add_f32_dpp v35, v35, v35 quad_perm:[1,0,3,2] row_mask:0xf bank_mask:0xf bound_ctrl:1
	s_nop 1
	v_add_f32_dpp v35, v35, v35 quad_perm:[2,3,0,1] row_mask:0xf bank_mask:0xf bound_ctrl:1
	s_nop 1
	v_add_f32_dpp v35, v35, v35 row_half_mirror row_mask:0xf bank_mask:0xf bound_ctrl:1
	s_nop 1
	v_mov_b32_dpp v36, v35 row_mirror row_mask:0xf bank_mask:0xf bound_ctrl:1
	s_and_saveexec_b64 s[4:5], s[92:93]
	s_cbranch_execz .LBB0_207
	v_add_f32_e32 v35, v35, v36
	v_mul_f32_e32 v35, 0x3c800000, v35
	v_mul_f32_e32 v36, 0xbdd2d3e7, v35
	v_fmaak_f32 v36, v35, v36, 0xc0135761
	v_mul_f32_e32 v36, v35, v36
	v_exp_f32_e32 v36, v36
	s_waitcnt lgkmcnt(0)
	v_cvt_f32_f16_e32 v34, v34
	v_add_f32_e32 v36, 1.0, v36
	v_rcp_f32_e32 v36, v36
	s_nop 0
	v_mul_f32_e32 v35, v35, v36
	v_mul_f32_e32 v34, v35, v34
	v_mul_f32_e32 v34, 4.0, v34
	v_cvt_pk_f16_f32 v34, v34, v34
	ds_write_b32 v167, v34
.LBB0_207:
	s_or_b64 exec, exec, s[4:5]
	s_waitcnt vmcnt(2)
	v_mfma_f32_16x16x32_fp8_fp8 v[44:47], v[22:23], v[84:85], 0
	v_readlane_b32 s4, v2, s46
	v_mov_b32_e32 v38, v92
	s_bfe_u32 s4, s4, 0x100010
	s_waitcnt lgkmcnt(0)
	v_mfma_f32_16x16x32_fp8_fp8 v[34:37], v[26:27], v[84:85], 0
	v_readlane_b32 s5, v2, s47
	s_lshl_b32 s4, s4, 10
	s_bfe_u32 s5, s5, 0x100010
	v_mfma_f32_16x16x32_fp8_fp8 v[44:47], v[24:25], v[88:89], v[44:47]
	s_lshl_b32 s5, s5, 10
	v_cmp_eq_u32_e32 vcc, 1, v100
	v_cmp_eq_u32_e64 s[94:95], 2, v100
	s_waitcnt vmcnt(1)
	v_mfma_f32_16x16x32_fp8_fp8 v[22:25], v[30:31], v[84:85], 0
	v_cmp_eq_u32_e64 s[96:97], 3, v100
	v_mfma_f32_16x16x32_fp8_fp8 v[40:43], v[28:29], v[88:89], v[34:37]
	s_nop 2
	buffer_load_dwordx4 v[34:37], v38, s[8:11], s4 offen
	buffer_load_dwordx4 v[26:29], v38, s[8:11], s5 offen
	v_readlane_b32 s4, v2, s48
	s_bfe_u32 s4, s4, 0x100010
	v_readlane_b32 s5, v2, s49
	s_lshl_b32 s4, s4, 10
	s_bfe_u32 s5, s5, 0x100010
	s_lshl_b32 s5, s5, 10
	v_mfma_f32_16x16x32_fp8_fp8 v[48:51], v[32:33], v[88:89], v[22:25]
	buffer_load_dwordx4 v[30:33], v38, s[8:11], s4 offen
	s_nop 1
	buffer_load_dwordx4 v[22:25], v38, s[8:11], s5 offen
	ds_bpermute_b32 v38, v144, v1
	s_waitcnt vmcnt(4)
	v_mfma_f32_16x16x32_fp8_fp8 v[52:55], v[18:19], v[84:85], 0
	v_cndmask_b32_e32 v18, v40, v41, vcc
	v_cndmask_b32_e64 v39, v18, v42, s[94:95]
	v_cndmask_b32_e32 v40, v44, v45, vcc
	v_mfma_f32_16x16x32_fp8_fp8 v[18:21], v[20:21], v[88:89], v[52:55]
	v_cndmask_b32_e32 v41, v48, v49, vcc
	v_cndmask_b32_e64 v40, v40, v46, s[94:95]
	v_cndmask_b32_e64 v41, v41, v50, s[94:95]
	v_cndmask_b32_e64 v39, v39, v43, s[96:97]
	v_cndmask_b32_e64 v40, v40, v47, s[96:97]
	s_nop 2
	v_cndmask_b32_e32 v18, v18, v19, vcc
	v_cndmask_b32_e64 v18, v18, v20, s[94:95]
	v_cndmask_b32_e64 v41, v41, v51, s[96:97]
	v_cndmask_b32_e64 v18, v18, v21, s[96:97]
	v_cndmask_b32_e64 v39, 0, v39, s[36:37]
	v_cndmask_b32_e64 v40, 0, v40, s[36:37]
	v_cndmask_b32_e64 v41, 0, v41, s[36:37]
	v_cndmask_b32_e64 v18, 0, v18, s[36:37]
	v_permlane32_swap_b32_e32 v39, v40
	s_nop 0
	v_permlane32_swap_b32_e32 v41, v18
	v_add_f32_e32 v19, v39, v40
	v_add_f32_e32 v18, v41, v18
	s_nop 1
	v_permlane16_swap_b32_e32 v19, v18
	v_add_f32_e32 v18, v19, v18
	s_nop 1
	v_add_f32_dpp v18, v18, v18 quad_perm:[1,0,3,2] row_mask:0xf bank_mask:0xf bound_ctrl:1
	s_nop 1
	v_add_f32_dpp v18, v18, v18 quad_perm:[2,3,0,1] row_mask:0xf bank_mask:0xf bound_ctrl:1
	s_nop 1
	v_add_f32_dpp v18, v18, v18 row_half_mirror row_mask:0xf bank_mask:0xf bound_ctrl:1
	s_nop 1
	v_mov_b32_dpp v19, v18 row_mirror row_mask:0xf bank_mask:0xf bound_ctrl:1
	s_and_saveexec_b64 s[4:5], s[92:93]
	s_cbranch_execz .LBB0_209
	v_add_f32_e32 v18, v18, v19
	v_mul_f32_e32 v18, 0x3c800000, v18
	v_mul_f32_e32 v19, 0xbdd2d3e7, v18
	v_fmaak_f32 v19, v18, v19, 0xc0135761
	v_mul_f32_e32 v19, v18, v19
	v_exp_f32_e32 v19, v19
	s_waitcnt lgkmcnt(0)
	v_cvt_f32_f16_e32 v20, v38
	v_add_f32_e32 v19, 1.0, v19
	v_rcp_f32_e32 v19, v19
	s_nop 0
	v_mul_f32_e32 v18, v18, v19
	v_mul_f32_e32 v18, v18, v20
	v_mul_f32_e32 v18, 4.0, v18
	v_cvt_pk_f16_f32 v18, v18, v18
	ds_write_b32 v167, v18 offset:512
.LBB0_209:
	s_or_b64 exec, exec, s[4:5]
	s_waitcnt vmcnt(3)
	v_mfma_f32_16x16x32_fp8_fp8 v[18:21], v[34:35], v[102:103], 0
	v_readlane_b32 s4, v3, s46
	v_mov_b32_e32 v50, v92
	s_bfe_u32 s4, s4, 0x100010
	v_mfma_f32_16x16x32_fp8_fp8 v[42:45], v[36:37], v[104:105], v[18:21]
	v_readlane_b32 s5, v3, s47
	s_lshl_b32 s4, s4, 10
	s_waitcnt vmcnt(2)
	v_mfma_f32_16x16x32_fp8_fp8 v[18:21], v[26:27], v[102:103], 0
	s_mov_b32 s10, s14
	s_mov_b32 s11, s15
	s_bfe_u32 s5, s5, 0x100010
	v_mfma_f32_16x16x32_fp8_fp8 v[26:29], v[28:29], v[104:105], v[18:21]
	s_lshl_b32 s5, s5, 10
	s_waitcnt lgkmcnt(0)
	buffer_load_dwordx4 v[38:41], v50, s[8:11], s4 offen
	buffer_load_dwordx4 v[34:37], v50, s[8:11], s5 offen
	v_readlane_b32 s4, v3, s48
	s_waitcnt vmcnt(3)
	v_mfma_f32_16x16x32_fp8_fp8 v[18:21], v[30:31], v[102:103], 0
	s_bfe_u32 s4, s4, 0x100010
	v_readlane_b32 s5, v3, s49
	s_lshl_b32 s4, s4, 10
	s_bfe_u32 s5, s5, 0x100010
	s_lshl_b32 s5, s5, 10
	v_mfma_f32_16x16x32_fp8_fp8 v[46:49], v[32:33], v[104:105], v[18:21]
	buffer_load_dwordx4 v[30:33], v50, s[8:11], s4 offen
	s_nop 1
	buffer_load_dwordx4 v[18:21], v50, s[8:11], s5 offen
	v_cmp_eq_u32_e32 vcc, 1, v100
	v_cmp_eq_u32_e64 s[94:95], 2, v100
	s_waitcnt vmcnt(4)
	v_mfma_f32_16x16x32_fp8_fp8 v[50:53], v[22:23], v[102:103], 0
	v_cndmask_b32_e32 v23, v42, v43, vcc
	v_cndmask_b32_e64 v23, v23, v44, s[94:95]
	v_cmp_eq_u32_e64 s[96:97], 3, v100
	v_mfma_f32_16x16x32_fp8_fp8 v[50:53], v[24:25], v[104:105], v[50:53]
	v_cndmask_b32_e32 v24, v26, v27, vcc
	v_cndmask_b32_e32 v25, v46, v47, vcc
	v_cndmask_b32_e64 v24, v24, v28, s[94:95]
	v_cndmask_b32_e64 v25, v25, v48, s[94:95]
	v_cndmask_b32_e64 v23, v23, v45, s[96:97]
	s_nop 2
	v_cndmask_b32_e32 v26, v50, v51, vcc
	v_cndmask_b32_e64 v26, v26, v52, s[94:95]
	v_cndmask_b32_e64 v24, v24, v29, s[96:97]
	v_cndmask_b32_e64 v25, v25, v49, s[96:97]
	v_cndmask_b32_e64 v26, v26, v53, s[96:97]
	v_cndmask_b32_e64 v23, 0, v23, s[36:37]
	v_cndmask_b32_e64 v24, 0, v24, s[36:37]
	v_cndmask_b32_e64 v25, 0, v25, s[36:37]
	v_cndmask_b32_e64 v26, 0, v26, s[36:37]
	v_permlane32_swap_b32_e32 v23, v24
	s_nop 0
	v_permlane32_swap_b32_e32 v25, v26
	v_add_f32_e32 v23, v23, v24
	v_add_f32_e32 v24, v25, v26
	s_nop 1
	v_permlane16_swap_b32_e32 v23, v24
	ds_bpermute_b32 v22, v144, v2
	v_add_f32_e32 v23, v23, v24
	s_nop 1
	v_add_f32_dpp v23, v23, v23 quad_perm:[1,0,3,2] row_mask:0xf bank_mask:0xf bound_ctrl:1
	s_nop 1
	v_add_f32_dpp v23, v23, v23 quad_perm:[2,3,0,1] row_mask:0xf bank_mask:0xf bound_ctrl:1
	s_nop 1
	v_add_f32_dpp v23, v23, v23 row_half_mirror row_mask:0xf bank_mask:0xf bound_ctrl:1
	s_nop 1
	v_mov_b32_dpp v24, v23 row_mirror row_mask:0xf bank_mask:0xf bound_ctrl:1
	s_and_saveexec_b64 s[4:5], s[92:93]
	s_cbranch_execz .LBB0_211
	v_add_f32_e32 v23, v23, v24
	v_mul_f32_e32 v23, 0x3c800000, v23
	v_mul_f32_e32 v24, 0xbdd2d3e7, v23
	v_fmaak_f32 v24, v23, v24, 0xc0135761
	v_mul_f32_e32 v24, v23, v24
	v_exp_f32_e32 v24, v24
	s_waitcnt lgkmcnt(0)
	v_cvt_f32_f16_e32 v22, v22
	v_add_f32_e32 v24, 1.0, v24
	v_rcp_f32_e32 v24, v24
	s_nop 0
	v_mul_f32_e32 v23, v23, v24
	v_mul_f32_e32 v22, v23, v22
	v_mul_f32_e32 v22, 4.0, v22
	v_cvt_pk_f16_f32 v22, v22, v22
	ds_write_b32 v167, v22 offset:1024
.LBB0_211:
	s_or_b64 exec, exec, s[4:5]
	s_waitcnt vmcnt(3) lgkmcnt(0)
	v_mfma_f32_16x16x32_fp8_fp8 v[22:25], v[38:39], v[106:107], 0
	v_readlane_b32 s4, v4, s46
	v_mov_b32_e32 v54, v92
	s_bfe_u32 s4, s4, 0x100010
	v_mfma_f32_16x16x32_fp8_fp8 v[42:45], v[40:41], v[108:109], v[22:25]
	v_readlane_b32 s5, v4, s47
	s_lshl_b32 s4, s4, 10
	s_waitcnt vmcnt(2)
	v_mfma_f32_16x16x32_fp8_fp8 v[22:25], v[34:35], v[106:107], 0
	s_bfe_u32 s5, s5, 0x100010
	s_lshl_b32 s5, s5, 10
	buffer_load_dwordx4 v[38:41], v54, s[8:11], s4 offen
	buffer_load_dwordx4 v[26:29], v54, s[8:11], s5 offen
	v_mfma_f32_16x16x32_fp8_fp8 v[46:49], v[36:37], v[108:109], v[22:25]
	v_readlane_b32 s4, v4, s48
	s_bfe_u32 s4, s4, 0x100010
	v_readlane_b32 s5, v4, s49
	s_waitcnt vmcnt(3)
	v_mfma_f32_16x16x32_fp8_fp8 v[22:25], v[30:31], v[106:107], 0
	s_lshl_b32 s4, s4, 10
	s_bfe_u32 s5, s5, 0x100010
	s_lshl_b32 s5, s5, 10
	v_mfma_f32_16x16x32_fp8_fp8 v[50:53], v[32:33], v[108:109], v[22:25]
	buffer_load_dwordx4 v[30:33], v54, s[8:11], s4 offen
	s_nop 2
	buffer_load_dwordx4 v[22:25], v54, s[8:11], s5 offen
	v_cmp_eq_u32_e32 vcc, 1, v100
	v_cmp_eq_u32_e64 s[94:95], 2, v100
	s_waitcnt vmcnt(4)
	v_mfma_f32_16x16x32_fp8_fp8 v[54:57], v[18:19], v[106:107], 0
	v_cndmask_b32_e32 v18, v42, v43, vcc
	v_cndmask_b32_e64 v35, v18, v44, s[94:95]
	v_cndmask_b32_e32 v36, v46, v47, vcc
	v_mfma_f32_16x16x32_fp8_fp8 v[18:21], v[20:21], v[108:109], v[54:57]
	v_cndmask_b32_e32 v37, v50, v51, vcc
	v_cmp_eq_u32_e64 s[96:97], 3, v100
	v_cndmask_b32_e64 v36, v36, v48, s[94:95]
	v_cndmask_b32_e64 v37, v37, v52, s[94:95]
	v_cndmask_b32_e64 v35, v35, v45, s[96:97]
	s_nop 2
	v_cndmask_b32_e32 v18, v18, v19, vcc
	v_cndmask_b32_e64 v18, v18, v20, s[94:95]
	v_cndmask_b32_e64 v36, v36, v49, s[96:97]
	v_cndmask_b32_e64 v37, v37, v53, s[96:97]
	v_cndmask_b32_e64 v18, v18, v21, s[96:97]
	v_cndmask_b32_e64 v35, 0, v35, s[36:37]
	v_cndmask_b32_e64 v36, 0, v36, s[36:37]
	v_cndmask_b32_e64 v37, 0, v37, s[36:37]
	v_cndmask_b32_e64 v18, 0, v18, s[36:37]
	v_permlane32_swap_b32_e32 v35, v36
	s_nop 0
	v_permlane32_swap_b32_e32 v37, v18
	v_add_f32_e32 v19, v35, v36
	v_add_f32_e32 v18, v37, v18
	s_nop 1
	v_permlane16_swap_b32_e32 v19, v18
	ds_bpermute_b32 v34, v144, v3
	v_add_f32_e32 v18, v19, v18
	s_nop 1
	v_add_f32_dpp v18, v18, v18 quad_perm:[1,0,3,2] row_mask:0xf bank_mask:0xf bound_ctrl:1
	s_nop 1
	v_add_f32_dpp v18, v18, v18 quad_perm:[2,3,0,1] row_mask:0xf bank_mask:0xf bound_ctrl:1
	s_nop 1
	v_add_f32_dpp v18, v18, v18 row_half_mirror row_mask:0xf bank_mask:0xf bound_ctrl:1
	s_nop 1
	v_mov_b32_dpp v19, v18 row_mirror row_mask:0xf bank_mask:0xf bound_ctrl:1
	s_and_saveexec_b64 s[4:5], s[92:93]
	s_cbranch_execz .LBB0_213
	v_add_f32_e32 v18, v18, v19
	v_mul_f32_e32 v18, 0x3c800000, v18
	v_mul_f32_e32 v19, 0xbdd2d3e7, v18
	v_fmaak_f32 v19, v18, v19, 0xc0135761
	v_mul_f32_e32 v19, v18, v19
	v_exp_f32_e32 v19, v19
	s_waitcnt lgkmcnt(0)
	v_cvt_f32_f16_e32 v20, v34
	v_add_f32_e32 v19, 1.0, v19
	v_rcp_f32_e32 v19, v19
	s_nop 0
	v_mul_f32_e32 v18, v18, v19
	v_mul_f32_e32 v18, v18, v20
	v_mul_f32_e32 v18, 4.0, v18
	v_cvt_pk_f16_f32 v18, v18, v18
	ds_write_b32 v167, v18 offset:1536
.LBB0_213:
	s_or_b64 exec, exec, s[4:5]
	s_waitcnt vmcnt(3)
	v_mfma_f32_16x16x32_fp8_fp8 v[18:21], v[38:39], v[110:111], 0
	v_readlane_b32 s4, v5, s46
	v_mov_b32_e32 v50, v92
	s_bfe_u32 s4, s4, 0x100010
	v_mfma_f32_16x16x32_fp8_fp8 v[42:45], v[40:41], v[112:113], v[18:21]
	v_readlane_b32 s5, v5, s47
	s_lshl_b32 s4, s4, 10
	s_waitcnt vmcnt(2)
	v_mfma_f32_16x16x32_fp8_fp8 v[18:21], v[26:27], v[110:111], 0
	s_mov_b32 s10, s14
	s_mov_b32 s11, s15
	s_bfe_u32 s5, s5, 0x100010
	v_mfma_f32_16x16x32_fp8_fp8 v[26:29], v[28:29], v[112:113], v[18:21]
	s_lshl_b32 s5, s5, 10
	buffer_load_dwordx4 v[38:41], v50, s[8:11], s4 offen
	s_waitcnt lgkmcnt(0)
	buffer_load_dwordx4 v[34:37], v50, s[8:11], s5 offen
	v_readlane_b32 s4, v5, s48
	s_waitcnt vmcnt(3)
	v_mfma_f32_16x16x32_fp8_fp8 v[18:21], v[30:31], v[110:111], 0
	s_bfe_u32 s4, s4, 0x100010
	v_readlane_b32 s5, v5, s49
	s_lshl_b32 s4, s4, 10
	s_bfe_u32 s5, s5, 0x100010
	s_lshl_b32 s5, s5, 10
	v_mfma_f32_16x16x32_fp8_fp8 v[46:49], v[32:33], v[112:113], v[18:21]
	buffer_load_dwordx4 v[30:33], v50, s[8:11], s4 offen
	s_nop 1
	buffer_load_dwordx4 v[18:21], v50, s[8:11], s5 offen
	v_cmp_eq_u32_e32 vcc, 1, v100
	v_cmp_eq_u32_e64 s[94:95], 2, v100
	s_waitcnt vmcnt(4)
	v_mfma_f32_16x16x32_fp8_fp8 v[50:53], v[22:23], v[110:111], 0
	v_cndmask_b32_e32 v23, v42, v43, vcc
	v_cndmask_b32_e64 v23, v23, v44, s[94:95]
	v_cmp_eq_u32_e64 s[96:97], 3, v100
	v_mfma_f32_16x16x32_fp8_fp8 v[50:53], v[24:25], v[112:113], v[50:53]
	v_cndmask_b32_e32 v24, v26, v27, vcc
	v_cndmask_b32_e32 v25, v46, v47, vcc
	v_cndmask_b32_e64 v24, v24, v28, s[94:95]
	v_cndmask_b32_e64 v25, v25, v48, s[94:95]
	v_cndmask_b32_e64 v23, v23, v45, s[96:97]
	s_nop 2
	v_cndmask_b32_e32 v26, v50, v51, vcc
	v_cndmask_b32_e64 v26, v26, v52, s[94:95]
	v_cndmask_b32_e64 v24, v24, v29, s[96:97]
	v_cndmask_b32_e64 v25, v25, v49, s[96:97]
	v_cndmask_b32_e64 v26, v26, v53, s[96:97]
	v_cndmask_b32_e64 v23, 0, v23, s[36:37]
	v_cndmask_b32_e64 v24, 0, v24, s[36:37]
	v_cndmask_b32_e64 v25, 0, v25, s[36:37]
	v_cndmask_b32_e64 v26, 0, v26, s[36:37]
	v_permlane32_swap_b32_e32 v23, v24
	s_nop 0
	v_permlane32_swap_b32_e32 v25, v26
	v_add_f32_e32 v23, v23, v24
	v_add_f32_e32 v24, v25, v26
	s_nop 1
	v_permlane16_swap_b32_e32 v23, v24
	ds_bpermute_b32 v22, v144, v4
	v_add_f32_e32 v23, v23, v24
	s_nop 1
	v_add_f32_dpp v23, v23, v23 quad_perm:[1,0,3,2] row_mask:0xf bank_mask:0xf bound_ctrl:1
	s_nop 1
	v_add_f32_dpp v23, v23, v23 quad_perm:[2,3,0,1] row_mask:0xf bank_mask:0xf bound_ctrl:1
	s_nop 1
	v_add_f32_dpp v23, v23, v23 row_half_mirror row_mask:0xf bank_mask:0xf bound_ctrl:1
	s_nop 1
	v_mov_b32_dpp v24, v23 row_mirror row_mask:0xf bank_mask:0xf bound_ctrl:1
	s_and_saveexec_b64 s[4:5], s[92:93]
	s_cbranch_execz .LBB0_215
	v_add_f32_e32 v23, v23, v24
	v_mul_f32_e32 v23, 0x3c800000, v23
	v_mul_f32_e32 v24, 0xbdd2d3e7, v23
	v_fmaak_f32 v24, v23, v24, 0xc0135761
	v_mul_f32_e32 v24, v23, v24
	v_exp_f32_e32 v24, v24
	s_waitcnt lgkmcnt(0)
	v_cvt_f32_f16_e32 v22, v22
	v_add_f32_e32 v24, 1.0, v24
	v_rcp_f32_e32 v24, v24
	s_nop 0
	v_mul_f32_e32 v23, v23, v24
	v_mul_f32_e32 v22, v23, v22
	v_mul_f32_e32 v22, 4.0, v22
	v_cvt_pk_f16_f32 v22, v22, v22
	ds_write_b32 v167, v22 offset:2048
.LBB0_215:
	s_or_b64 exec, exec, s[4:5]
	s_waitcnt vmcnt(3) lgkmcnt(0)
	v_mfma_f32_16x16x32_fp8_fp8 v[22:25], v[38:39], v[114:115], 0
	v_readlane_b32 s4, v6, s46
	v_mov_b32_e32 v54, v92
	s_bfe_u32 s4, s4, 0x100010
	v_mfma_f32_16x16x32_fp8_fp8 v[42:45], v[40:41], v[116:117], v[22:25]
	v_readlane_b32 s5, v6, s47
	s_lshl_b32 s4, s4, 10
	s_waitcnt vmcnt(2)
	v_mfma_f32_16x16x32_fp8_fp8 v[22:25], v[34:35], v[114:115], 0
	s_bfe_u32 s5, s5, 0x100010
	s_lshl_b32 s5, s5, 10
	buffer_load_dwordx4 v[38:41], v54, s[8:11], s4 offen
	buffer_load_dwordx4 v[26:29], v54, s[8:11], s5 offen
	v_mfma_f32_16x16x32_fp8_fp8 v[46:49], v[36:37], v[116:117], v[22:25]
	v_readlane_b32 s4, v6, s48
	s_bfe_u32 s4, s4, 0x100010
	v_readlane_b32 s5, v6, s49
	s_waitcnt vmcnt(3)
	v_mfma_f32_16x16x32_fp8_fp8 v[22:25], v[30:31], v[114:115], 0
	s_lshl_b32 s4, s4, 10
	s_bfe_u32 s5, s5, 0x100010
	s_lshl_b32 s5, s5, 10
	v_mfma_f32_16x16x32_fp8_fp8 v[50:53], v[32:33], v[116:117], v[22:25]
	buffer_load_dwordx4 v[30:33], v54, s[8:11], s4 offen
	s_nop 2
	buffer_load_dwordx4 v[22:25], v54, s[8:11], s5 offen
	v_cmp_eq_u32_e32 vcc, 1, v100
	v_cmp_eq_u32_e64 s[94:95], 2, v100
	s_waitcnt vmcnt(4)
	v_mfma_f32_16x16x32_fp8_fp8 v[54:57], v[18:19], v[114:115], 0
	v_cndmask_b32_e32 v18, v42, v43, vcc
	v_cndmask_b32_e64 v35, v18, v44, s[94:95]
	v_cndmask_b32_e32 v36, v46, v47, vcc
	v_mfma_f32_16x16x32_fp8_fp8 v[18:21], v[20:21], v[116:117], v[54:57]
	v_cndmask_b32_e32 v37, v50, v51, vcc
	v_cmp_eq_u32_e64 s[96:97], 3, v100
	v_cndmask_b32_e64 v36, v36, v48, s[94:95]
	v_cndmask_b32_e64 v37, v37, v52, s[94:95]
	v_cndmask_b32_e64 v35, v35, v45, s[96:97]
	s_nop 2
	v_cndmask_b32_e32 v18, v18, v19, vcc
	v_cndmask_b32_e64 v18, v18, v20, s[94:95]
	v_cndmask_b32_e64 v36, v36, v49, s[96:97]
	v_cndmask_b32_e64 v37, v37, v53, s[96:97]
	v_cndmask_b32_e64 v18, v18, v21, s[96:97]
	v_cndmask_b32_e64 v35, 0, v35, s[36:37]
	v_cndmask_b32_e64 v36, 0, v36, s[36:37]
	v_cndmask_b32_e64 v37, 0, v37, s[36:37]
	v_cndmask_b32_e64 v18, 0, v18, s[36:37]
	v_permlane32_swap_b32_e32 v35, v36
	s_nop 0
	v_permlane32_swap_b32_e32 v37, v18
	v_add_f32_e32 v19, v35, v36
	v_add_f32_e32 v18, v37, v18
	s_nop 1
	v_permlane16_swap_b32_e32 v19, v18
	ds_bpermute_b32 v34, v144, v5
	v_add_f32_e32 v18, v19, v18
	s_nop 1
	v_add_f32_dpp v18, v18, v18 quad_perm:[1,0,3,2] row_mask:0xf bank_mask:0xf bound_ctrl:1
	s_nop 1
	v_add_f32_dpp v18, v18, v18 quad_perm:[2,3,0,1] row_mask:0xf bank_mask:0xf bound_ctrl:1
	s_nop 1
	v_add_f32_dpp v18, v18, v18 row_half_mirror row_mask:0xf bank_mask:0xf bound_ctrl:1
	s_nop 1
	v_mov_b32_dpp v19, v18 row_mirror row_mask:0xf bank_mask:0xf bound_ctrl:1
	s_and_saveexec_b64 s[4:5], s[92:93]
	s_cbranch_execz .LBB0_217
	v_add_f32_e32 v18, v18, v19
	v_mul_f32_e32 v18, 0x3c800000, v18
	v_mul_f32_e32 v19, 0xbdd2d3e7, v18
	v_fmaak_f32 v19, v18, v19, 0xc0135761
	v_mul_f32_e32 v19, v18, v19
	v_exp_f32_e32 v19, v19
	s_waitcnt lgkmcnt(0)
	v_cvt_f32_f16_e32 v20, v34
	v_add_f32_e32 v19, 1.0, v19
	v_rcp_f32_e32 v19, v19
	s_nop 0
	v_mul_f32_e32 v18, v18, v19
	v_mul_f32_e32 v18, v18, v20
	v_mul_f32_e32 v18, 4.0, v18
	v_cvt_pk_f16_f32 v18, v18, v18
	ds_write_b32 v167, v18 offset:2560
.LBB0_217:
	s_or_b64 exec, exec, s[4:5]
	v_readlane_b32 s4, v7, s46
	v_mov_b32_e32 v42, v92
	s_bfe_u32 s4, s4, 0x100010
	v_readlane_b32 s5, v7, s47
	s_lshl_b32 s4, s4, 10
	s_mov_b32 s10, s14
	s_mov_b32 s11, s15
	s_bfe_u32 s5, s5, 0x100010
	s_lshl_b32 s5, s5, 10
	buffer_load_dwordx4 v[62:65], v42, s[8:11], s4 offen
	buffer_load_dwordx4 v[58:61], v42, s[8:11], s5 offen
	v_readlane_b32 s4, v7, s48
	s_bfe_u32 s4, s4, 0x100010
	v_readlane_b32 s5, v7, s49
	s_lshl_b32 s4, s4, 10
	s_bfe_u32 s5, s5, 0x100010
	s_lshl_b32 s5, s5, 10
	buffer_load_dwordx4 v[54:57], v42, s[8:11], s4 offen
	s_nop 0
	buffer_load_dwordx4 v[50:53], v42, s[8:11], s5 offen
	s_waitcnt vmcnt(7)
	v_mfma_f32_16x16x32_fp8_fp8 v[18:21], v[38:39], v[118:119], 0
	v_cmp_eq_u32_e32 vcc, 1, v100
	v_cmp_eq_u32_e64 s[94:95], 2, v100
	v_cmp_eq_u32_e64 s[96:97], 3, v100
	s_waitcnt lgkmcnt(0)
	v_mfma_f32_16x16x32_fp8_fp8 v[34:37], v[40:41], v[120:121], v[18:21]
	s_waitcnt vmcnt(6)
	v_mfma_f32_16x16x32_fp8_fp8 v[18:21], v[26:27], v[118:119], 0
	v_mfma_f32_16x16x32_fp8_fp8 v[26:29], v[28:29], v[120:121], v[18:21]
	s_waitcnt vmcnt(5)
	v_mfma_f32_16x16x32_fp8_fp8 v[18:21], v[30:31], v[118:119], 0
	v_mfma_f32_16x16x32_fp8_fp8 v[30:33], v[32:33], v[120:121], v[18:21]
	s_waitcnt vmcnt(4)
	v_mfma_f32_16x16x32_fp8_fp8 v[20:23], v[22:23], v[118:119], 0
	s_nop 4
	v_cndmask_b32_e32 v19, v34, v35, vcc
	v_cndmask_b32_e64 v19, v19, v36, s[94:95]
	v_cndmask_b32_e64 v19, v19, v37, s[96:97]
	v_mfma_f32_16x16x32_fp8_fp8 v[20:23], v[24:25], v[120:121], v[20:23]
	v_cndmask_b32_e32 v24, v26, v27, vcc
	v_cndmask_b32_e32 v25, v30, v31, vcc
	v_cndmask_b32_e64 v24, v24, v28, s[94:95]
	v_cndmask_b32_e64 v25, v25, v32, s[94:95]
	v_cndmask_b32_e64 v24, v24, v29, s[96:97]
	s_nop 2
	v_cndmask_b32_e32 v20, v20, v21, vcc
	v_cndmask_b32_e64 v20, v20, v22, s[94:95]
	v_cndmask_b32_e64 v25, v25, v33, s[96:97]
	v_cndmask_b32_e64 v20, v20, v23, s[96:97]
	v_cndmask_b32_e64 v19, 0, v19, s[36:37]
	v_cndmask_b32_e64 v24, 0, v24, s[36:37]
	v_cndmask_b32_e64 v25, 0, v25, s[36:37]
	v_cndmask_b32_e64 v20, 0, v20, s[36:37]
	v_permlane32_swap_b32_e32 v19, v24
	s_nop 0
	v_permlane32_swap_b32_e32 v25, v20
	v_add_f32_e32 v19, v19, v24
	v_add_f32_e32 v20, v25, v20
	s_nop 1
	v_permlane16_swap_b32_e32 v19, v20
	ds_bpermute_b32 v18, v144, v6
	v_add_f32_e32 v19, v19, v20
	s_nop 1
	v_add_f32_dpp v19, v19, v19 quad_perm:[1,0,3,2] row_mask:0xf bank_mask:0xf bound_ctrl:1
	s_nop 1
	v_add_f32_dpp v19, v19, v19 quad_perm:[2,3,0,1] row_mask:0xf bank_mask:0xf bound_ctrl:1
	s_nop 1
	v_add_f32_dpp v19, v19, v19 row_half_mirror row_mask:0xf bank_mask:0xf bound_ctrl:1
	s_nop 1
	v_mov_b32_dpp v20, v19 row_mirror row_mask:0xf bank_mask:0xf bound_ctrl:1
	s_and_saveexec_b64 s[4:5], s[92:93]
	s_cbranch_execz .LBB0_219
	v_add_f32_e32 v19, v19, v20
	v_mul_f32_e32 v19, 0x3c800000, v19
	v_mul_f32_e32 v20, 0xbdd2d3e7, v19
	v_fmaak_f32 v20, v19, v20, 0xc0135761
	v_mul_f32_e32 v20, v19, v20
	v_exp_f32_e32 v20, v20
	s_waitcnt lgkmcnt(0)
	v_cvt_f32_f16_e32 v18, v18
	v_add_f32_e32 v20, 1.0, v20
	v_rcp_f32_e32 v20, v20
	s_nop 0
	v_mul_f32_e32 v19, v19, v20
	v_mul_f32_e32 v18, v19, v18
	v_mul_f32_e32 v18, 4.0, v18
	v_cvt_pk_f16_f32 v18, v18, v18
	ds_write_b32 v167, v18 offset:3072
.LBB0_219:
	s_or_b64 exec, exec, s[4:5]
	v_readlane_b32 s4, v8, s46
	s_waitcnt lgkmcnt(0)
	v_mov_b32_e32 v18, v92
	s_bfe_u32 s4, s4, 0x100010
	s_lshl_b32 s4, s4, 10
	s_nop 0
	buffer_load_dwordx4 v[34:37], v18, s[8:11], s4 offen
	buffer_load_dwordx4 v[30:33], v18, s[12:15], s4 offen
	v_readlane_b32 s4, v8, s47
	s_bfe_u32 s4, s4, 0x100010
	s_lshl_b32 s4, s4, 10
	s_nop 2
	buffer_load_dwordx4 v[38:41], v18, s[8:11], s4 offen
	buffer_load_dwordx4 v[26:29], v18, s[12:15], s4 offen
	v_readlane_b32 s4, v8, s48
	s_bfe_u32 s4, s4, 0x100010
	s_lshl_b32 s4, s4, 10
	s_nop 2
	buffer_load_dwordx4 v[42:45], v18, s[8:11], s4 offen
	buffer_load_dwordx4 v[22:25], v18, s[12:15], s4 offen
	v_readlane_b32 s4, v8, s49
	s_bfe_u32 s4, s4, 0x100010
	s_lshl_b32 s4, s4, 10
	s_nop 2
	buffer_load_dwordx4 v[46:49], v18, s[8:11], s4 offen
	s_nop 0
	buffer_load_dwordx4 v[18:21], v18, s[12:15], s4 offen
	s_waitcnt vmcnt(11)
	v_mfma_f32_16x16x32_fp8_fp8 v[66:69], v[62:63], v[122:123], 0
	v_cmp_eq_u32_e32 vcc, 1, v100
	v_cmp_eq_u32_e64 s[94:95], 2, v100
	v_cmp_eq_u32_e64 s[96:97], 3, v100
	v_mfma_f32_16x16x32_fp8_fp8 v[62:65], v[64:65], v[124:125], v[66:69]
	s_waitcnt vmcnt(10)
	v_mfma_f32_16x16x32_fp8_fp8 v[66:69], v[58:59], v[122:123], 0
	v_mfma_f32_16x16x32_fp8_fp8 v[58:61], v[60:61], v[124:125], v[66:69]
	s_waitcnt vmcnt(9)
	v_mfma_f32_16x16x32_fp8_fp8 v[66:69], v[54:55], v[122:123], 0
	v_mfma_f32_16x16x32_fp8_fp8 v[54:57], v[56:57], v[124:125], v[66:69]
	s_waitcnt vmcnt(8)
	v_mfma_f32_16x16x32_fp8_fp8 v[66:69], v[50:51], v[122:123], 0
	v_cndmask_b32_e32 v51, v62, v63, vcc
	v_cndmask_b32_e64 v51, v51, v64, s[94:95]
	v_cndmask_b32_e64 v51, v51, v65, s[96:97]
	v_mfma_f32_16x16x32_fp8_fp8 v[66:69], v[52:53], v[124:125], v[66:69]
	v_cndmask_b32_e32 v52, v58, v59, vcc
	s_nop 0
	v_cndmask_b32_e32 v53, v54, v55, vcc
	v_cndmask_b32_e64 v52, v52, v60, s[94:95]
	v_cndmask_b32_e64 v53, v53, v56, s[94:95]
	v_cndmask_b32_e64 v52, v52, v61, s[96:97]
	s_nop 1
	v_cndmask_b32_e32 v54, v66, v67, vcc
	v_cndmask_b32_e64 v54, v54, v68, s[94:95]
	v_cndmask_b32_e64 v53, v53, v57, s[96:97]
	v_cndmask_b32_e64 v54, v54, v69, s[96:97]
	v_cndmask_b32_e64 v51, 0, v51, s[36:37]
	v_cndmask_b32_e64 v52, 0, v52, s[36:37]
	v_cndmask_b32_e64 v53, 0, v53, s[36:37]
	v_cndmask_b32_e64 v54, 0, v54, s[36:37]
	v_permlane32_swap_b32_e32 v51, v52
	s_nop 0
	v_permlane32_swap_b32_e32 v53, v54
	v_add_f32_e32 v51, v51, v52
	v_add_f32_e32 v52, v53, v54
	s_nop 1
	v_permlane16_swap_b32_e32 v51, v52
	ds_bpermute_b32 v50, v144, v7
	v_add_f32_e32 v51, v51, v52
	s_nop 1
	v_add_f32_dpp v51, v51, v51 quad_perm:[1,0,3,2] row_mask:0xf bank_mask:0xf bound_ctrl:1
	s_nop 1
	v_add_f32_dpp v51, v51, v51 quad_perm:[2,3,0,1] row_mask:0xf bank_mask:0xf bound_ctrl:1
	s_nop 1
	v_add_f32_dpp v51, v51, v51 row_half_mirror row_mask:0xf bank_mask:0xf bound_ctrl:1
	s_nop 1
	v_mov_b32_dpp v52, v51 row_mirror row_mask:0xf bank_mask:0xf bound_ctrl:1
	s_and_saveexec_b64 s[4:5], s[92:93]
	s_cbranch_execz .LBB0_221
	v_add_f32_e32 v51, v51, v52
	v_mul_f32_e32 v51, 0x3c800000, v51
	v_mul_f32_e32 v52, 0xbdd2d3e7, v51
	v_fmaak_f32 v52, v51, v52, 0xc0135761
	v_mul_f32_e32 v52, v51, v52
	v_exp_f32_e32 v52, v52
	s_waitcnt lgkmcnt(0)
	v_cvt_f32_f16_e32 v50, v50
	v_add_f32_e32 v52, 1.0, v52
	v_rcp_f32_e32 v52, v52
	s_nop 0
	v_mul_f32_e32 v51, v51, v52
	v_mul_f32_e32 v50, v51, v50
	v_mul_f32_e32 v50, 4.0, v50
	v_cvt_pk_f16_f32 v50, v50, v50
	ds_write_b32 v167, v50 offset:3584
.LBB0_221:
	s_or_b64 exec, exec, s[4:5]
	s_add_i32 s65, s43, -7
	v_readlane_b32 s4, v0, s65
	s_bfe_u32 s4, s4, 0x100010
	v_mov_b32_e32 v74, v92
	s_lshl_b32 s4, s4, 10
	s_mov_b32 s10, s14
	s_mov_b32 s11, s15
	s_add_i32 s80, s43, -6
	s_waitcnt lgkmcnt(0)
	buffer_load_dwordx4 v[50:53], v74, s[8:11], s4 offen
	v_readlane_b32 s4, v0, s80
	s_bfe_u32 s4, s4, 0x100010
	s_lshl_b32 s4, s4, 10
	s_add_i32 s81, s43, -5
	s_add_i32 s86, s43, -4
	s_waitcnt vmcnt(8)
	v_mfma_f32_16x16x32_fp8_fp8 v[54:57], v[34:35], v[126:127], 0
	buffer_load_dwordx4 v[58:61], v74, s[8:11], s4 offen
	v_readlane_b32 s4, v0, s81
	s_bfe_u32 s4, s4, 0x100010
	s_lshl_b32 s4, s4, 10
	ds_bpermute_b32 v34, v144, v8
	s_waitcnt vmcnt(7)
	v_mfma_f32_16x16x32_fp8_fp8 v[62:65], v[38:39], v[126:127], 0
	v_mov_b32_e32 v35, v92
	buffer_load_dwordx4 v[66:69], v74, s[8:11], s4 offen
	v_readlane_b32 s4, v0, s86
	s_bfe_u32 s4, s4, 0x100010
	s_lshl_b32 s4, s4, 10
	s_waitcnt vmcnt(6)
	v_mfma_f32_16x16x32_fp8_fp8 v[70:73], v[42:43], v[126:127], 0
	v_readlane_b32 s5, v1, s80
	v_readlane_b32 s46, v1, s81
	buffer_load_dwordx4 v[74:77], v74, s[8:11], s4 offen
	s_waitcnt vmcnt(5)
	v_mfma_f32_16x16x32_fp8_fp8 v[78:81], v[46:47], v[126:127], 0
	v_readlane_b32 s4, v1, s65
	v_readlane_b32 s47, v1, s86
	s_bfe_u32 s4, s4, 0x100010
	s_bfe_u32 s5, s5, 0x100010
	s_bfe_u32 s46, s46, 0x100010
	s_bfe_u32 s47, s47, 0x100010
	s_lshl_b32 s4, s4, 10
	v_mfma_f32_16x16x32_fp8_fp8 v[54:57], v[36:37], v[128:129], v[54:57]
	s_lshl_b32 s5, s5, 10
	s_lshl_b32 s46, s46, 10
	s_lshl_b32 s47, s47, 10
	v_mfma_f32_16x16x32_fp8_fp8 v[62:65], v[40:41], v[128:129], v[62:65]
	s_waitcnt lgkmcnt(0)
	v_cvt_f32_f16_e32 v146, v34
	v_cmp_eq_u32_e32 vcc, 1, v100
	v_cmp_eq_u32_e64 s[94:95], 2, v100
	v_mfma_f32_16x16x32_fp8_fp8 v[70:73], v[44:45], v[128:129], v[70:73]
	v_cndmask_b32_e32 v54, v54, v55, vcc
	s_nop 1
	v_cndmask_b32_e32 v55, v62, v63, vcc
	v_cndmask_b32_e64 v54, v54, v56, s[94:95]
	v_mfma_f32_16x16x32_fp8_fp8 v[78:81], v[48:49], v[128:129], v[78:81]
	buffer_load_dwordx4 v[46:49], v35, s[8:11], s4 offen
	buffer_load_dwordx4 v[42:45], v35, s[8:11], s5 offen
	buffer_load_dwordx4 v[38:41], v35, s[8:11], s46 offen
	s_nop 0
	buffer_load_dwordx4 v[34:37], v35, s[8:11], s47 offen
	v_cndmask_b32_e32 v62, v70, v71, vcc
	v_cndmask_b32_e64 v55, v55, v64, s[94:95]
	s_nop 0
	v_cndmask_b32_e32 v63, v78, v79, vcc
	v_cndmask_b32_e64 v56, v62, v72, s[94:95]
	v_cndmask_b32_e64 v62, v63, v80, s[94:95]
	v_cmp_eq_u32_e64 s[96:97], 3, v100
	s_nop 1
	v_cndmask_b32_e64 v54, v54, v57, s[96:97]
	v_cndmask_b32_e64 v55, v55, v65, s[96:97]
	v_cndmask_b32_e64 v56, v56, v73, s[96:97]
	v_cndmask_b32_e64 v57, v62, v81, s[96:97]
	v_cndmask_b32_e64 v54, 0, v54, s[36:37]
	v_cndmask_b32_e64 v55, 0, v55, s[36:37]
	v_cndmask_b32_e64 v56, 0, v56, s[36:37]
	v_cndmask_b32_e64 v57, 0, v57, s[36:37]
	v_permlane32_swap_b32_e32 v54, v55
	s_nop 0
	v_permlane32_swap_b32_e32 v56, v57
	v_add_f32_e32 v54, v54, v55
	v_add_f32_e32 v55, v56, v57
	s_nop 1
	v_permlane16_swap_b32_e32 v54, v55
	v_add_f32_e32 v54, v54, v55
	s_nop 1
	v_add_f32_dpp v54, v54, v54 quad_perm:[1,0,3,2] row_mask:0xf bank_mask:0xf bound_ctrl:1
	s_nop 1
	v_add_f32_dpp v54, v54, v54 quad_perm:[2,3,0,1] row_mask:0xf bank_mask:0xf bound_ctrl:1
	s_nop 1
	v_add_f32_dpp v62, v54, v54 row_half_mirror row_mask:0xf bank_mask:0xf bound_ctrl:1
	s_waitcnt vmcnt(7)
	v_mfma_f32_16x16x32_fp8_fp8 v[54:57], v[50:51], v[86:87], 0
	v_add_f32_dpp v50, v62, v62 row_mirror row_mask:0xf bank_mask:0xf bound_ctrl:1
	v_mul_f32_e32 v50, 0x3c800000, v50
	v_mul_f32_e32 v51, 0xbdd2d3e7, v50
	v_fmaak_f32 v51, v50, v51, 0xc0135761
	s_waitcnt vmcnt(6)
	v_mfma_f32_16x16x32_fp8_fp8 v[62:65], v[58:59], v[86:87], 0
	v_mul_f32_e32 v51, v50, v51
	v_exp_f32_e32 v51, v51
	v_mfma_f32_16x16x32_fp8_fp8 v[52:55], v[52:53], v[82:83], v[54:57]
	v_add_f32_e32 v51, 1.0, v51
	v_mfma_f32_16x16x32_fp8_fp8 v[56:59], v[60:61], v[82:83], v[62:65]
	v_rcp_f32_e32 v51, v51
	s_nop 0
	v_mul_f32_e32 v50, v50, v51
	s_waitcnt vmcnt(5)
	v_mfma_f32_16x16x32_fp8_fp8 v[60:63], v[66:67], v[86:87], 0
	s_nop 0
	v_cndmask_b32_e32 v51, v52, v53, vcc
	v_cndmask_b32_e64 v51, v51, v54, s[94:95]
	v_cndmask_b32_e32 v52, v56, v57, vcc
	s_waitcnt vmcnt(4)
	v_mfma_f32_16x16x32_fp8_fp8 v[64:67], v[74:75], v[86:87], 0
	v_cndmask_b32_e64 v52, v52, v58, s[94:95]
	v_cndmask_b32_e64 v51, v51, v55, s[96:97]
	v_cndmask_b32_e64 v52, v52, v59, s[96:97]
	v_mfma_f32_16x16x32_fp8_fp8 v[60:63], v[68:69], v[82:83], v[60:63]
	v_cndmask_b32_e64 v51, 0, v51, s[36:37]
	v_cndmask_b32_e64 v52, 0, v52, s[36:37]
	v_mul_f32_e32 v50, v50, v146
	v_mfma_f32_16x16x32_fp8_fp8 v[64:67], v[76:77], v[82:83], v[64:67]
	v_permlane32_swap_b32_e32 v51, v52
	s_nop 2
	v_cndmask_b32_e32 v53, v60, v61, vcc
	v_cndmask_b32_e64 v53, v53, v62, s[94:95]
	v_cndmask_b32_e64 v53, v53, v63, s[96:97]
	s_nop 0
	v_cndmask_b32_e32 v54, v64, v65, vcc
	v_cndmask_b32_e64 v54, v54, v66, s[94:95]
	v_cndmask_b32_e64 v54, v54, v67, s[96:97]
	v_cndmask_b32_e64 v53, 0, v53, s[36:37]
	v_cndmask_b32_e64 v54, 0, v54, s[36:37]
	s_nop 1
	v_permlane32_swap_b32_e32 v53, v54
	v_mul_f32_e32 v50, 4.0, v50
	v_add_f32_e32 v51, v51, v52
	v_add_f32_e32 v52, v53, v54
	v_cvt_pk_f16_f32 v50, v50, v50
	s_nop 0
	v_permlane16_swap_b32_e32 v51, v52
	v_readlane_b32 s49, v50, s54
	v_readlane_b32 s48, v50, s55
	v_readlane_b32 s47, v50, s56
	v_readlane_b32 s46, v50, s57
	ds_bpermute_b32 v50, v144, v0 offset:16
	v_add_f32_e32 v51, v51, v52
	s_nop 1
	v_add_f32_dpp v51, v51, v51 quad_perm:[1,0,3,2] row_mask:0xf bank_mask:0xf bound_ctrl:1
	s_nop 1
	v_add_f32_dpp v51, v51, v51 quad_perm:[2,3,0,1] row_mask:0xf bank_mask:0xf bound_ctrl:1
	s_nop 1
	v_add_f32_dpp v51, v51, v51 row_half_mirror row_mask:0xf bank_mask:0xf bound_ctrl:1
	s_nop 1
	v_mov_b32_dpp v52, v51 row_mirror row_mask:0xf bank_mask:0xf bound_ctrl:1
	s_and_saveexec_b64 s[4:5], s[92:93]
	s_cbranch_execz .LBB0_223
	v_add_f32_e32 v51, v51, v52
	v_mul_f32_e32 v51, 0x3c800000, v51
	v_mul_f32_e32 v52, 0xbdd2d3e7, v51
	v_fmaak_f32 v52, v51, v52, 0xc0135761
	v_mul_f32_e32 v52, v51, v52
	v_exp_f32_e32 v52, v52
	s_waitcnt lgkmcnt(0)
	v_cvt_f32_f16_e32 v50, v50
	v_add_f32_e32 v52, 1.0, v52
	v_rcp_f32_e32 v52, v52
	s_nop 0
	v_mul_f32_e32 v51, v51, v52
	v_mul_f32_e32 v50, v51, v50
	v_mul_f32_e32 v50, 4.0, v50
	v_cvt_pk_f16_f32 v50, v50, v50
	ds_write_b32 v167, v50 offset:16
.LBB0_223:
	s_or_b64 exec, exec, s[4:5]
	s_waitcnt vmcnt(2)
	v_mfma_f32_16x16x32_fp8_fp8 v[58:61], v[42:43], v[84:85], 0
	v_readlane_b32 s4, v2, s65
	v_mov_b32_e32 v66, v92
	s_bfe_u32 s4, s4, 0x100010
	s_waitcnt lgkmcnt(0)
	v_mfma_f32_16x16x32_fp8_fp8 v[50:53], v[46:47], v[84:85], 0
	v_readlane_b32 s5, v2, s80
	s_lshl_b32 s4, s4, 10
	s_bfe_u32 s5, s5, 0x100010
	v_mfma_f32_16x16x32_fp8_fp8 v[58:61], v[44:45], v[88:89], v[58:61]
	s_lshl_b32 s5, s5, 10
	v_cmp_eq_u32_e32 vcc, 1, v100
	v_cmp_eq_u32_e64 s[94:95], 2, v100
	s_waitcnt vmcnt(1)
	v_mfma_f32_16x16x32_fp8_fp8 v[42:45], v[38:39], v[84:85], 0
	v_cmp_eq_u32_e64 s[96:97], 3, v100
	v_add_u32_e32 v168, 16, v144
	v_mfma_f32_16x16x32_fp8_fp8 v[54:57], v[48:49], v[88:89], v[50:53]
	s_nop 2
	buffer_load_dwordx4 v[50:53], v66, s[8:11], s4 offen
	buffer_load_dwordx4 v[46:49], v66, s[8:11], s5 offen
	v_readlane_b32 s4, v2, s81
	s_bfe_u32 s4, s4, 0x100010
	v_readlane_b32 s5, v2, s86
	s_lshl_b32 s4, s4, 10
	s_bfe_u32 s5, s5, 0x100010
	s_lshl_b32 s5, s5, 10
	v_mfma_f32_16x16x32_fp8_fp8 v[62:65], v[40:41], v[88:89], v[42:45]
	s_nop 2
	buffer_load_dwordx4 v[42:45], v66, s[8:11], s4 offen
	buffer_load_dwordx4 v[38:41], v66, s[8:11], s5 offen
	s_waitcnt vmcnt(4)
	v_mfma_f32_16x16x32_fp8_fp8 v[66:69], v[34:35], v[84:85], 0
	v_cndmask_b32_e32 v35, v54, v55, vcc
	v_cndmask_b32_e64 v35, v35, v56, s[94:95]
	v_cndmask_b32_e64 v35, v35, v57, s[96:97]
	v_mfma_f32_16x16x32_fp8_fp8 v[66:69], v[36:37], v[88:89], v[66:69]
	v_cndmask_b32_e32 v36, v58, v59, vcc
	v_cndmask_b32_e32 v37, v62, v63, vcc
	v_cndmask_b32_e64 v36, v36, v60, s[94:95]
	v_cndmask_b32_e64 v37, v37, v64, s[94:95]
	v_cndmask_b32_e64 v36, v36, v61, s[96:97]
	s_nop 2
	v_cndmask_b32_e32 v54, v66, v67, vcc
	v_cndmask_b32_e64 v54, v54, v68, s[94:95]
	v_cndmask_b32_e64 v37, v37, v65, s[96:97]
	v_cndmask_b32_e64 v54, v54, v69, s[96:97]
	v_cndmask_b32_e64 v35, 0, v35, s[36:37]
	v_cndmask_b32_e64 v36, 0, v36, s[36:37]
	v_cndmask_b32_e64 v37, 0, v37, s[36:37]
	v_cndmask_b32_e64 v54, 0, v54, s[36:37]
	v_permlane32_swap_b32_e32 v35, v36
	s_nop 0
	v_permlane32_swap_b32_e32 v37, v54
	v_add_f32_e32 v35, v35, v36
	v_add_f32_e32 v36, v37, v54
	s_nop 1
	v_permlane16_swap_b32_e32 v35, v36
	ds_bpermute_b32 v34, v168, v1
	v_add_f32_e32 v35, v35, v36
	s_nop 1
	v_add_f32_dpp v35, v35, v35 quad_perm:[1,0,3,2] row_mask:0xf bank_mask:0xf bound_ctrl:1
	s_nop 1
	v_add_f32_dpp v35, v35, v35 quad_perm:[2,3,0,1] row_mask:0xf bank_mask:0xf bound_ctrl:1
	s_nop 1
	v_add_f32_dpp v35, v35, v35 row_half_mirror row_mask:0xf bank_mask:0xf bound_ctrl:1
	s_nop 1
	v_mov_b32_dpp v36, v35 row_mirror row_mask:0xf bank_mask:0xf bound_ctrl:1
	s_and_saveexec_b64 s[4:5], s[92:93]
	s_cbranch_execz .LBB0_225
	v_add_f32_e32 v35, v35, v36
	v_mul_f32_e32 v35, 0x3c800000, v35
	v_mul_f32_e32 v36, 0xbdd2d3e7, v35
	v_fmaak_f32 v36, v35, v36, 0xc0135761
	v_mul_f32_e32 v36, v35, v36
	v_exp_f32_e32 v36, v36
	s_waitcnt lgkmcnt(0)
	v_cvt_f32_f16_e32 v34, v34
	v_add_f32_e32 v36, 1.0, v36
	v_rcp_f32_e32 v36, v36
	s_nop 0
	v_mul_f32_e32 v35, v35, v36
	v_mul_f32_e32 v34, v35, v34
	v_mul_f32_e32 v34, 4.0, v34
	v_cvt_pk_f16_f32 v34, v34, v34
	ds_write_b32 v167, v34 offset:528
.LBB0_225:
	s_or_b64 exec, exec, s[4:5]
	s_waitcnt vmcnt(3) lgkmcnt(0)
	v_mfma_f32_16x16x32_fp8_fp8 v[34:37], v[50:51], v[102:103], 0
	v_readlane_b32 s4, v3, s65
	v_mov_b32_e32 v66, v92
	s_bfe_u32 s4, s4, 0x100010
	v_mfma_f32_16x16x32_fp8_fp8 v[58:61], v[52:53], v[104:105], v[34:37]
	v_readlane_b32 s5, v3, s80
	s_lshl_b32 s4, s4, 10
	s_waitcnt vmcnt(2)
	v_mfma_f32_16x16x32_fp8_fp8 v[34:37], v[46:47], v[102:103], 0
	s_mov_b32 s10, s14
	s_mov_b32 s11, s15
	s_bfe_u32 s5, s5, 0x100010
	v_mfma_f32_16x16x32_fp8_fp8 v[62:65], v[48:49], v[104:105], v[34:37]
	s_lshl_b32 s5, s5, 10
	buffer_load_dwordx4 v[54:57], v66, s[8:11], s4 offen
	buffer_load_dwordx4 v[50:53], v66, s[8:11], s5 offen
	v_readlane_b32 s4, v3, s81
	s_waitcnt vmcnt(3)
	v_mfma_f32_16x16x32_fp8_fp8 v[34:37], v[42:43], v[102:103], 0
	s_bfe_u32 s4, s4, 0x100010
	v_readlane_b32 s5, v3, s86
	s_lshl_b32 s4, s4, 10
	s_bfe_u32 s5, s5, 0x100010
	s_lshl_b32 s5, s5, 10
	v_mfma_f32_16x16x32_fp8_fp8 v[42:45], v[44:45], v[104:105], v[34:37]
	buffer_load_dwordx4 v[46:49], v66, s[8:11], s4 offen
	s_nop 1
	buffer_load_dwordx4 v[34:37], v66, s[8:11], s5 offen
	v_cmp_eq_u32_e32 vcc, 1, v100
	v_cmp_eq_u32_e64 s[94:95], 2, v100
	s_waitcnt vmcnt(4)
	v_mfma_f32_16x16x32_fp8_fp8 v[66:69], v[38:39], v[102:103], 0
	v_cndmask_b32_e32 v39, v58, v59, vcc
	v_cndmask_b32_e64 v39, v39, v60, s[94:95]
	v_cmp_eq_u32_e64 s[96:97], 3, v100
	v_mfma_f32_16x16x32_fp8_fp8 v[66:69], v[40:41], v[104:105], v[66:69]
	v_cndmask_b32_e32 v40, v62, v63, vcc
	v_cndmask_b32_e32 v41, v42, v43, vcc
	v_cndmask_b32_e64 v40, v40, v64, s[94:95]
	v_cndmask_b32_e64 v41, v41, v44, s[94:95]
	v_cndmask_b32_e64 v39, v39, v61, s[96:97]
	s_nop 2
	v_cndmask_b32_e32 v42, v66, v67, vcc
	v_cndmask_b32_e64 v42, v42, v68, s[94:95]
	v_cndmask_b32_e64 v40, v40, v65, s[96:97]
	v_cndmask_b32_e64 v41, v41, v45, s[96:97]
	v_cndmask_b32_e64 v42, v42, v69, s[96:97]
	v_cndmask_b32_e64 v39, 0, v39, s[36:37]
	v_cndmask_b32_e64 v40, 0, v40, s[36:37]
	v_cndmask_b32_e64 v41, 0, v41, s[36:37]
	v_cndmask_b32_e64 v42, 0, v42, s[36:37]
	v_permlane32_swap_b32_e32 v39, v40
	s_nop 0
	v_permlane32_swap_b32_e32 v41, v42
	v_add_f32_e32 v39, v39, v40
	v_add_f32_e32 v40, v41, v42
	s_nop 1
	v_permlane16_swap_b32_e32 v39, v40
	ds_bpermute_b32 v38, v168, v2
	v_add_f32_e32 v39, v39, v40
	s_nop 1
	v_add_f32_dpp v39, v39, v39 quad_perm:[1,0,3,2] row_mask:0xf bank_mask:0xf bound_ctrl:1
	s_nop 1
	v_add_f32_dpp v39, v39, v39 quad_perm:[2,3,0,1] row_mask:0xf bank_mask:0xf bound_ctrl:1
	s_nop 1
	v_add_f32_dpp v39, v39, v39 row_half_mirror row_mask:0xf bank_mask:0xf bound_ctrl:1
	s_nop 1
	v_mov_b32_dpp v40, v39 row_mirror row_mask:0xf bank_mask:0xf bound_ctrl:1
	s_and_saveexec_b64 s[4:5], s[92:93]
	s_cbranch_execz .LBB0_227
	v_add_f32_e32 v39, v39, v40
	v_mul_f32_e32 v39, 0x3c800000, v39
	v_mul_f32_e32 v40, 0xbdd2d3e7, v39
	v_fmaak_f32 v40, v39, v40, 0xc0135761
	v_mul_f32_e32 v40, v39, v40
	v_exp_f32_e32 v40, v40
	s_waitcnt lgkmcnt(0)
	v_cvt_f32_f16_e32 v38, v38
	v_add_f32_e32 v40, 1.0, v40
	v_rcp_f32_e32 v40, v40
	s_nop 0
	v_mul_f32_e32 v39, v39, v40
	v_mul_f32_e32 v38, v39, v38
	v_mul_f32_e32 v38, 4.0, v38
	v_cvt_pk_f16_f32 v38, v38, v38
	ds_write_b32 v167, v38 offset:1040
.LBB0_227:
	s_or_b64 exec, exec, s[4:5]
	s_waitcnt vmcnt(3) lgkmcnt(0)
	v_mfma_f32_16x16x32_fp8_fp8 v[38:41], v[54:55], v[106:107], 0
	v_readlane_b32 s4, v4, s65
	v_mov_b32_e32 v70, v92
	s_bfe_u32 s4, s4, 0x100010
	v_mfma_f32_16x16x32_fp8_fp8 v[58:61], v[56:57], v[108:109], v[38:41]
	v_readlane_b32 s5, v4, s80
	s_lshl_b32 s4, s4, 10
	s_waitcnt vmcnt(2)
	v_mfma_f32_16x16x32_fp8_fp8 v[38:41], v[50:51], v[106:107], 0
	s_bfe_u32 s5, s5, 0x100010
	s_lshl_b32 s5, s5, 10
	buffer_load_dwordx4 v[54:57], v70, s[8:11], s4 offen
	buffer_load_dwordx4 v[42:45], v70, s[8:11], s5 offen
	v_mfma_f32_16x16x32_fp8_fp8 v[62:65], v[52:53], v[108:109], v[38:41]
	v_readlane_b32 s4, v4, s81
	s_bfe_u32 s4, s4, 0x100010
	v_readlane_b32 s5, v4, s86
	s_waitcnt vmcnt(3)
	v_mfma_f32_16x16x32_fp8_fp8 v[38:41], v[46:47], v[106:107], 0
	s_lshl_b32 s4, s4, 10
	s_bfe_u32 s5, s5, 0x100010
	s_lshl_b32 s5, s5, 10
	v_mfma_f32_16x16x32_fp8_fp8 v[66:69], v[48:49], v[108:109], v[38:41]
	buffer_load_dwordx4 v[46:49], v70, s[8:11], s4 offen
	s_nop 2
	buffer_load_dwordx4 v[38:41], v70, s[8:11], s5 offen
	v_cmp_eq_u32_e32 vcc, 1, v100
	v_cmp_eq_u32_e64 s[94:95], 2, v100
	s_waitcnt vmcnt(4)
	v_mfma_f32_16x16x32_fp8_fp8 v[70:73], v[34:35], v[106:107], 0
	v_cndmask_b32_e32 v34, v58, v59, vcc
	v_cndmask_b32_e64 v51, v34, v60, s[94:95]
	v_cndmask_b32_e32 v52, v62, v63, vcc
	v_mfma_f32_16x16x32_fp8_fp8 v[34:37], v[36:37], v[108:109], v[70:73]
	v_cndmask_b32_e32 v53, v66, v67, vcc
	v_cmp_eq_u32_e64 s[96:97], 3, v100
	v_cndmask_b32_e64 v52, v52, v64, s[94:95]
	v_cndmask_b32_e64 v53, v53, v68, s[94:95]
	v_cndmask_b32_e64 v51, v51, v61, s[96:97]
	s_nop 2
	v_cndmask_b32_e32 v34, v34, v35, vcc
	v_cndmask_b32_e64 v34, v34, v36, s[94:95]
	v_cndmask_b32_e64 v52, v52, v65, s[96:97]
	v_cndmask_b32_e64 v53, v53, v69, s[96:97]
	v_cndmask_b32_e64 v34, v34, v37, s[96:97]
	v_cndmask_b32_e64 v51, 0, v51, s[36:37]
	v_cndmask_b32_e64 v52, 0, v52, s[36:37]
	v_cndmask_b32_e64 v53, 0, v53, s[36:37]
	v_cndmask_b32_e64 v34, 0, v34, s[36:37]
	v_permlane32_swap_b32_e32 v51, v52
	s_nop 0
	v_permlane32_swap_b32_e32 v53, v34
	v_add_f32_e32 v35, v51, v52
	v_add_f32_e32 v34, v53, v34
	s_nop 1
	v_permlane16_swap_b32_e32 v35, v34
	ds_bpermute_b32 v50, v168, v3
	v_add_f32_e32 v34, v35, v34
	s_nop 1
	v_add_f32_dpp v34, v34, v34 quad_perm:[1,0,3,2] row_mask:0xf bank_mask:0xf bound_ctrl:1
	s_nop 1
	v_add_f32_dpp v34, v34, v34 quad_perm:[2,3,0,1] row_mask:0xf bank_mask:0xf bound_ctrl:1
	s_nop 1
	v_add_f32_dpp v34, v34, v34 row_half_mirror row_mask:0xf bank_mask:0xf bound_ctrl:1
	s_nop 1
	v_mov_b32_dpp v35, v34 row_mirror row_mask:0xf bank_mask:0xf bound_ctrl:1
	s_and_saveexec_b64 s[4:5], s[92:93]
	s_cbranch_execz .LBB0_229
	v_add_f32_e32 v34, v34, v35
	v_mul_f32_e32 v34, 0x3c800000, v34
	v_mul_f32_e32 v35, 0xbdd2d3e7, v34
	v_fmaak_f32 v35, v34, v35, 0xc0135761
	v_mul_f32_e32 v35, v34, v35
	v_exp_f32_e32 v35, v35
	s_waitcnt lgkmcnt(0)
	v_cvt_f32_f16_e32 v36, v50
	v_add_f32_e32 v35, 1.0, v35
	v_rcp_f32_e32 v35, v35
	s_nop 0
	v_mul_f32_e32 v34, v34, v35
	v_mul_f32_e32 v34, v34, v36
	v_mul_f32_e32 v34, 4.0, v34
	v_cvt_pk_f16_f32 v34, v34, v34
	ds_write_b32 v167, v34 offset:1552
.LBB0_229:
	s_or_b64 exec, exec, s[4:5]
	s_waitcnt vmcnt(3)
	v_mfma_f32_16x16x32_fp8_fp8 v[34:37], v[54:55], v[110:111], 0
	v_readlane_b32 s4, v5, s65
	v_mov_b32_e32 v70, v92
	s_bfe_u32 s4, s4, 0x100010
	v_mfma_f32_16x16x32_fp8_fp8 v[58:61], v[56:57], v[112:113], v[34:37]
	v_readlane_b32 s5, v5, s80
	s_lshl_b32 s4, s4, 10
	s_waitcnt vmcnt(2)
	v_mfma_f32_16x16x32_fp8_fp8 v[34:37], v[42:43], v[110:111], 0
	s_mov_b32 s10, s14
	s_mov_b32 s11, s15
	s_bfe_u32 s5, s5, 0x100010
	v_mfma_f32_16x16x32_fp8_fp8 v[62:65], v[44:45], v[112:113], v[34:37]
	s_lshl_b32 s5, s5, 10
	buffer_load_dwordx4 v[54:57], v70, s[8:11], s4 offen
	s_waitcnt lgkmcnt(0)
	buffer_load_dwordx4 v[50:53], v70, s[8:11], s5 offen
	v_readlane_b32 s4, v5, s81
	s_waitcnt vmcnt(3)
	v_mfma_f32_16x16x32_fp8_fp8 v[34:37], v[46:47], v[110:111], 0
	s_bfe_u32 s4, s4, 0x100010
	v_readlane_b32 s5, v5, s86
	s_lshl_b32 s4, s4, 10
	s_bfe_u32 s5, s5, 0x100010
	s_lshl_b32 s5, s5, 10
	v_mfma_f32_16x16x32_fp8_fp8 v[66:69], v[48:49], v[112:113], v[34:37]
	buffer_load_dwordx4 v[44:47], v70, s[8:11], s4 offen
	s_nop 1
	buffer_load_dwordx4 v[34:37], v70, s[8:11], s5 offen
	v_cmp_eq_u32_e32 vcc, 1, v100
	v_cmp_eq_u32_e64 s[94:95], 2, v100
	s_waitcnt vmcnt(4)
	v_mfma_f32_16x16x32_fp8_fp8 v[70:73], v[38:39], v[110:111], 0
	v_cndmask_b32_e32 v39, v58, v59, vcc
	v_cndmask_b32_e32 v48, v62, v63, vcc
	v_cndmask_b32_e32 v49, v66, v67, vcc
	v_mfma_f32_16x16x32_fp8_fp8 v[40:43], v[40:41], v[112:113], v[70:73]
	v_cndmask_b32_e64 v39, v39, v60, s[94:95]
	v_cmp_eq_u32_e64 s[96:97], 3, v100
	v_cndmask_b32_e64 v48, v48, v64, s[94:95]
	v_cndmask_b32_e64 v49, v49, v68, s[94:95]
	v_cndmask_b32_e64 v39, v39, v61, s[96:97]
	s_nop 2
	v_cndmask_b32_e32 v40, v40, v41, vcc
	v_cndmask_b32_e64 v40, v40, v42, s[94:95]
	v_cndmask_b32_e64 v48, v48, v65, s[96:97]
	v_cndmask_b32_e64 v49, v49, v69, s[96:97]
	v_cndmask_b32_e64 v40, v40, v43, s[96:97]
	v_cndmask_b32_e64 v39, 0, v39, s[36:37]
	v_cndmask_b32_e64 v48, 0, v48, s[36:37]
	v_cndmask_b32_e64 v49, 0, v49, s[36:37]
	v_cndmask_b32_e64 v40, 0, v40, s[36:37]
	v_permlane32_swap_b32_e32 v39, v48
	s_nop 0
	v_permlane32_swap_b32_e32 v49, v40
	v_add_f32_e32 v39, v39, v48
	v_add_f32_e32 v40, v49, v40
	s_nop 1
	v_permlane16_swap_b32_e32 v39, v40
	ds_bpermute_b32 v38, v168, v4
	v_add_f32_e32 v39, v39, v40
	s_nop 1
	v_add_f32_dpp v39, v39, v39 quad_perm:[1,0,3,2] row_mask:0xf bank_mask:0xf bound_ctrl:1
	s_nop 1
	v_add_f32_dpp v39, v39, v39 quad_perm:[2,3,0,1] row_mask:0xf bank_mask:0xf bound_ctrl:1
	s_nop 1
	v_add_f32_dpp v39, v39, v39 row_half_mirror row_mask:0xf bank_mask:0xf bound_ctrl:1
	s_nop 1
	v_mov_b32_dpp v40, v39 row_mirror row_mask:0xf bank_mask:0xf bound_ctrl:1
	s_and_saveexec_b64 s[4:5], s[92:93]
	s_cbranch_execz .LBB0_231
	v_add_f32_e32 v39, v39, v40
	v_mul_f32_e32 v39, 0x3c800000, v39
	v_mul_f32_e32 v40, 0xbdd2d3e7, v39
	v_fmaak_f32 v40, v39, v40, 0xc0135761
	v_mul_f32_e32 v40, v39, v40
	v_exp_f32_e32 v40, v40
	s_waitcnt lgkmcnt(0)
	v_cvt_f32_f16_e32 v38, v38
	v_add_f32_e32 v40, 1.0, v40
	v_rcp_f32_e32 v40, v40
	s_nop 0
	v_mul_f32_e32 v39, v39, v40
	v_mul_f32_e32 v38, v39, v38
	v_mul_f32_e32 v38, 4.0, v38
	v_cvt_pk_f16_f32 v38, v38, v38
	ds_write_b32 v167, v38 offset:2064
.LBB0_231:
	s_or_b64 exec, exec, s[4:5]
	s_waitcnt vmcnt(2)
	v_mfma_f32_16x16x32_fp8_fp8 v[48:51], v[50:51], v[114:115], 0
	v_readlane_b32 s4, v6, s65
	v_mov_b32_e32 v70, v92
	s_bfe_u32 s4, s4, 0x100010
	s_waitcnt lgkmcnt(0)
	v_mfma_f32_16x16x32_fp8_fp8 v[38:41], v[54:55], v[114:115], 0
	v_readlane_b32 s5, v6, s80
	s_lshl_b32 s4, s4, 10
	s_bfe_u32 s5, s5, 0x100010
	v_mfma_f32_16x16x32_fp8_fp8 v[62:65], v[52:53], v[116:117], v[48:51]
	s_lshl_b32 s5, s5, 10
	v_cmp_eq_u32_e32 vcc, 1, v100
	v_cmp_eq_u32_e64 s[94:95], 2, v100
	s_waitcnt vmcnt(1)
	v_mfma_f32_16x16x32_fp8_fp8 v[48:51], v[44:45], v[114:115], 0
	v_cmp_eq_u32_e64 s[96:97], 3, v100
	v_mfma_f32_16x16x32_fp8_fp8 v[58:61], v[56:57], v[116:117], v[38:41]
	buffer_load_dwordx4 v[54:57], v70, s[8:11], s4 offen
	s_nop 1
	buffer_load_dwordx4 v[40:43], v70, s[8:11], s5 offen
	v_readlane_b32 s4, v6, s81
	s_bfe_u32 s4, s4, 0x100010
	v_readlane_b32 s5, v6, s86
	s_lshl_b32 s4, s4, 10
	s_bfe_u32 s5, s5, 0x100010
	s_lshl_b32 s5, s5, 10
	v_mfma_f32_16x16x32_fp8_fp8 v[66:69], v[46:47], v[116:117], v[48:51]
	buffer_load_dwordx4 v[44:47], v70, s[8:11], s4 offen
	s_nop 1
	buffer_load_dwordx4 v[50:53], v70, s[8:11], s5 offen
	v_cndmask_b32_e32 v48, v62, v63, vcc
	v_cndmask_b32_e64 v48, v48, v64, s[94:95]
	s_waitcnt vmcnt(4)
	v_mfma_f32_16x16x32_fp8_fp8 v[70:73], v[34:35], v[114:115], 0
	v_cndmask_b32_e32 v34, v58, v59, vcc
	v_cndmask_b32_e64 v39, v34, v60, s[94:95]
	v_cndmask_b32_e32 v49, v66, v67, vcc
	v_mfma_f32_16x16x32_fp8_fp8 v[34:37], v[36:37], v[116:117], v[70:73]
	v_cndmask_b32_e64 v49, v49, v68, s[94:95]
	v_cndmask_b32_e64 v39, v39, v61, s[96:97]
	v_cndmask_b32_e64 v48, v48, v65, s[96:97]
	v_cndmask_b32_e64 v49, v49, v69, s[96:97]
	v_cndmask_b32_e64 v39, 0, v39, s[36:37]
	s_nop 2
	v_cndmask_b32_e32 v34, v34, v35, vcc
	v_cndmask_b32_e64 v34, v34, v36, s[94:95]
	v_cndmask_b32_e64 v34, v34, v37, s[96:97]
	v_cndmask_b32_e64 v48, 0, v48, s[36:37]
	v_cndmask_b32_e64 v49, 0, v49, s[36:37]
	v_cndmask_b32_e64 v34, 0, v34, s[36:37]
	v_permlane32_swap_b32_e32 v39, v48
	s_nop 0
	v_permlane32_swap_b32_e32 v49, v34
	v_add_f32_e32 v35, v39, v48
	v_add_f32_e32 v34, v49, v34
	s_nop 1
	v_permlane16_swap_b32_e32 v35, v34
	ds_bpermute_b32 v38, v168, v5
	v_add_f32_e32 v34, v35, v34
	s_nop 1
	v_add_f32_dpp v34, v34, v34 quad_perm:[1,0,3,2] row_mask:0xf bank_mask:0xf bound_ctrl:1
	s_nop 1
	v_add_f32_dpp v34, v34, v34 quad_perm:[2,3,0,1] row_mask:0xf bank_mask:0xf bound_ctrl:1
	s_nop 1
	v_add_f32_dpp v34, v34, v34 row_half_mirror row_mask:0xf bank_mask:0xf bound_ctrl:1
	s_nop 1
	v_mov_b32_dpp v35, v34 row_mirror row_mask:0xf bank_mask:0xf bound_ctrl:1
	s_and_saveexec_b64 s[4:5], s[92:93]
	s_cbranch_execz .LBB0_233
	v_add_f32_e32 v34, v34, v35
	v_mul_f32_e32 v34, 0x3c800000, v34
	v_mul_f32_e32 v35, 0xbdd2d3e7, v34
	v_fmaak_f32 v35, v34, v35, 0xc0135761
	v_mul_f32_e32 v35, v34, v35
	v_exp_f32_e32 v35, v35
	s_waitcnt lgkmcnt(0)
	v_cvt_f32_f16_e32 v36, v38
	v_add_f32_e32 v35, 1.0, v35
	v_rcp_f32_e32 v35, v35
	s_nop 0
	v_mul_f32_e32 v34, v34, v35
	v_mul_f32_e32 v34, v34, v36
	v_mul_f32_e32 v34, 4.0, v34
	v_cvt_pk_f16_f32 v34, v34, v34
	ds_write_b32 v167, v34 offset:2576
.LBB0_233:
	s_or_b64 exec, exec, s[4:5]
	s_waitcnt vmcnt(2)
	v_mfma_f32_16x16x32_fp8_fp8 v[58:61], v[40:41], v[118:119], 0
	v_readlane_b32 s4, v7, s65
	v_mov_b32_e32 v48, v92
	s_bfe_u32 s4, s4, 0x100010
	v_mfma_f32_16x16x32_fp8_fp8 v[34:37], v[54:55], v[118:119], 0
	v_readlane_b32 s5, v7, s80
	s_lshl_b32 s4, s4, 10
	s_mov_b32 s10, s14
	s_mov_b32 s11, s15
	s_bfe_u32 s5, s5, 0x100010
	v_mfma_f32_16x16x32_fp8_fp8 v[58:61], v[42:43], v[120:121], v[58:61]
	s_lshl_b32 s5, s5, 10
	v_cmp_eq_u32_e32 vcc, 1, v100
	v_cmp_eq_u32_e64 s[94:95], 2, v100
	s_waitcnt vmcnt(1)
	v_mfma_f32_16x16x32_fp8_fp8 v[42:45], v[44:45], v[118:119], 0
	v_cmp_eq_u32_e64 s[96:97], 3, v100
	v_mfma_f32_16x16x32_fp8_fp8 v[54:57], v[56:57], v[120:121], v[34:37]
	s_nop 2
	buffer_load_dwordx4 v[34:37], v48, s[8:11], s4 offen
	s_waitcnt lgkmcnt(0)
	buffer_load_dwordx4 v[38:41], v48, s[8:11], s5 offen
	v_readlane_b32 s4, v7, s81
	s_bfe_u32 s4, s4, 0x100010
	v_readlane_b32 s5, v7, s86
	s_lshl_b32 s4, s4, 10
	s_bfe_u32 s5, s5, 0x100010
	s_lshl_b32 s5, s5, 10
	v_mfma_f32_16x16x32_fp8_fp8 v[62:65], v[46:47], v[120:121], v[42:45]
	s_nop 2
	buffer_load_dwordx4 v[42:45], v48, s[8:11], s4 offen
	s_nop 0
	buffer_load_dwordx4 v[46:49], v48, s[8:11], s5 offen
	s_waitcnt vmcnt(4)
	v_mfma_f32_16x16x32_fp8_fp8 v[66:69], v[50:51], v[118:119], 0
	v_cndmask_b32_e32 v51, v54, v55, vcc
	v_cndmask_b32_e64 v51, v51, v56, s[94:95]
	v_cndmask_b32_e64 v51, v51, v57, s[96:97]
	v_mfma_f32_16x16x32_fp8_fp8 v[52:55], v[52:53], v[120:121], v[66:69]
	v_cndmask_b32_e32 v56, v58, v59, vcc
	v_cndmask_b32_e32 v57, v62, v63, vcc
	v_cndmask_b32_e64 v56, v56, v60, s[94:95]
	v_cndmask_b32_e64 v57, v57, v64, s[94:95]
	v_cndmask_b32_e64 v56, v56, v61, s[96:97]
	s_nop 2
	v_cndmask_b32_e32 v52, v52, v53, vcc
	v_cndmask_b32_e64 v52, v52, v54, s[94:95]
	v_cndmask_b32_e64 v57, v57, v65, s[96:97]
	v_cndmask_b32_e64 v52, v52, v55, s[96:97]
	v_cndmask_b32_e64 v51, 0, v51, s[36:37]
	v_cndmask_b32_e64 v56, 0, v56, s[36:37]
	v_cndmask_b32_e64 v57, 0, v57, s[36:37]
	v_cndmask_b32_e64 v52, 0, v52, s[36:37]
	v_permlane32_swap_b32_e32 v51, v56
	s_nop 0
	v_permlane32_swap_b32_e32 v57, v52
	v_add_f32_e32 v51, v51, v56
	v_add_f32_e32 v52, v57, v52
	s_nop 1
	v_permlane16_swap_b32_e32 v51, v52
	ds_bpermute_b32 v50, v168, v6
	v_add_f32_e32 v51, v51, v52
	s_nop 1
	v_add_f32_dpp v51, v51, v51 quad_perm:[1,0,3,2] row_mask:0xf bank_mask:0xf bound_ctrl:1
	s_nop 1
	v_add_f32_dpp v51, v51, v51 quad_perm:[2,3,0,1] row_mask:0xf bank_mask:0xf bound_ctrl:1
	s_nop 1
	v_add_f32_dpp v51, v51, v51 row_half_mirror row_mask:0xf bank_mask:0xf bound_ctrl:1
	s_nop 1
	v_mov_b32_dpp v52, v51 row_mirror row_mask:0xf bank_mask:0xf bound_ctrl:1
	s_and_saveexec_b64 s[4:5], s[92:93]
	s_cbranch_execz .LBB0_235
	v_add_f32_e32 v51, v51, v52
	v_mul_f32_e32 v51, 0x3c800000, v51
	v_mul_f32_e32 v52, 0xbdd2d3e7, v51
	v_fmaak_f32 v52, v51, v52, 0xc0135761
	v_mul_f32_e32 v52, v51, v52
	v_exp_f32_e32 v52, v52
	s_waitcnt lgkmcnt(0)
	v_cvt_f32_f16_e32 v50, v50
	v_add_f32_e32 v52, 1.0, v52
	v_rcp_f32_e32 v52, v52
	s_nop 0
	v_mul_f32_e32 v51, v51, v52
	v_mul_f32_e32 v50, v51, v50
	v_mul_f32_e32 v50, 4.0, v50
	v_cvt_pk_f16_f32 v50, v50, v50
	ds_write_b32 v167, v50 offset:3088
.LBB0_235:
	s_or_b64 exec, exec, s[4:5]
	v_readlane_b32 s4, v8, s65
	s_waitcnt lgkmcnt(0)
	v_mov_b32_e32 v50, v92
	s_bfe_u32 s4, s4, 0x100010
	s_lshl_b32 s4, s4, 10
	s_nop 0
	buffer_load_dwordx4 v[78:81], v50, s[8:11], s4 offen
	buffer_load_dwordx4 v[62:65], v50, s[12:15], s4 offen
	v_readlane_b32 s4, v8, s80
	s_bfe_u32 s4, s4, 0x100010
	s_lshl_b32 s4, s4, 10
	s_nop 2
	buffer_load_dwordx4 v[74:77], v50, s[8:11], s4 offen
	buffer_load_dwordx4 v[58:61], v50, s[12:15], s4 offen
	v_readlane_b32 s4, v8, s81
	s_bfe_u32 s4, s4, 0x100010
	s_lshl_b32 s4, s4, 10
	s_nop 2
	buffer_load_dwordx4 v[70:73], v50, s[8:11], s4 offen
	buffer_load_dwordx4 v[54:57], v50, s[12:15], s4 offen
	v_readlane_b32 s4, v8, s86
	s_bfe_u32 s4, s4, 0x100010
	s_lshl_b32 s4, s4, 10
	s_nop 2
	buffer_load_dwordx4 v[66:69], v50, s[8:11], s4 offen
	s_nop 0
	buffer_load_dwordx4 v[50:53], v50, s[12:15], s4 offen
	s_waitcnt vmcnt(11)
	v_mfma_f32_16x16x32_fp8_fp8 v[146:149], v[34:35], v[122:123], 0
	v_cmp_eq_u32_e32 vcc, 1, v100
	v_cmp_eq_u32_e64 s[94:95], 2, v100
	v_cmp_eq_u32_e64 s[96:97], 3, v100
	s_waitcnt vmcnt(10)
	v_mfma_f32_16x16x32_fp8_fp8 v[150:153], v[38:39], v[122:123], 0
	ds_bpermute_b32 v169, v168, v7
	s_waitcnt vmcnt(9)
	v_mfma_f32_16x16x32_fp8_fp8 v[154:157], v[42:43], v[122:123], 0
	s_waitcnt vmcnt(8)
	v_mfma_f32_16x16x32_fp8_fp8 v[170:173], v[46:47], v[122:123], 0
	v_mfma_f32_16x16x32_fp8_fp8 v[146:149], v[36:37], v[124:125], v[146:149]
	v_mfma_f32_16x16x32_fp8_fp8 v[150:153], v[40:41], v[124:125], v[150:153]
	v_mfma_f32_16x16x32_fp8_fp8 v[154:157], v[44:45], v[124:125], v[154:157]
	s_nop 5
	v_cndmask_b32_e32 v146, v146, v147, vcc
	v_cndmask_b32_e64 v146, v146, v148, s[94:95]
	v_cndmask_b32_e64 v146, v146, v149, s[96:97]
	v_mfma_f32_16x16x32_fp8_fp8 v[170:173], v[48:49], v[124:125], v[170:173]
	v_cndmask_b32_e32 v147, v150, v151, vcc
	v_cndmask_b32_e32 v148, v154, v155, vcc
	v_cndmask_b32_e64 v147, v147, v152, s[94:95]
	v_cndmask_b32_e64 v148, v148, v156, s[94:95]
	v_cndmask_b32_e64 v147, v147, v153, s[96:97]
	s_nop 2
	v_cndmask_b32_e32 v149, v170, v171, vcc
	v_cndmask_b32_e64 v149, v149, v172, s[94:95]
	v_cndmask_b32_e64 v148, v148, v157, s[96:97]
	v_cndmask_b32_e64 v149, v149, v173, s[96:97]
	v_cndmask_b32_e64 v146, 0, v146, s[36:37]
	v_cndmask_b32_e64 v147, 0, v147, s[36:37]
	v_cndmask_b32_e64 v148, 0, v148, s[36:37]
	v_cndmask_b32_e64 v149, 0, v149, s[36:37]
	v_permlane32_swap_b32_e32 v146, v147
	s_nop 0
	v_permlane32_swap_b32_e32 v148, v149
	v_add_f32_e32 v146, v146, v147
	v_add_f32_e32 v147, v148, v149
	s_nop 1
	v_permlane16_swap_b32_e32 v146, v147
	v_add_f32_e32 v146, v146, v147
	s_nop 1
	v_add_f32_dpp v146, v146, v146 quad_perm:[1,0,3,2] row_mask:0xf bank_mask:0xf bound_ctrl:1
	s_nop 1
	v_add_f32_dpp v146, v146, v146 quad_perm:[2,3,0,1] row_mask:0xf bank_mask:0xf bound_ctrl:1
	s_nop 1
	v_add_f32_dpp v170, v146, v146 row_half_mirror row_mask:0xf bank_mask:0xf bound_ctrl:1
	s_nop 1
	v_mov_b32_dpp v171, v170 row_mirror row_mask:0xf bank_mask:0xf bound_ctrl:1
	s_and_saveexec_b64 s[4:5], s[92:93]
	s_cbranch_execz .LBB0_237
	v_add_f32_e32 v146, v170, v171
	v_mul_f32_e32 v146, 0x3c800000, v146
	v_mul_f32_e32 v147, 0xbdd2d3e7, v146
	v_fmaak_f32 v147, v146, v147, 0xc0135761
	v_mul_f32_e32 v147, v146, v147
	v_exp_f32_e32 v147, v147
	s_waitcnt lgkmcnt(0)
	v_cvt_f32_f16_e32 v148, v169
	v_add_f32_e32 v147, 1.0, v147
	v_rcp_f32_e32 v147, v147
	s_nop 0
	v_mul_f32_e32 v146, v146, v147
	v_mul_f32_e32 v146, v146, v148
	v_mul_f32_e32 v146, 4.0, v146
	v_cvt_pk_f16_f32 v146, v146, v146
	ds_write_b32 v167, v146 offset:3600

.LBB0_245:
	s_waitcnt vmcnt(3)
	v_mfma_f32_16x16x32_fp8_fp8 v[34:37], v[18:19], v[86:87], 0
	s_add_i32 s43, s42, -7
	v_readlane_b32 s4, v1, s43
	s_add_i32 s46, s42, -6
	s_waitcnt lgkmcnt(0)
	v_mfma_f32_16x16x32_fp8_fp8 v[42:45], v[20:21], v[82:83], v[34:37]
	v_mov_b32_e32 v54, v92
	s_bfe_u32 s4, s4, 0x100010
	v_readlane_b32 s5, v1, s46
	s_waitcnt vmcnt(2)
	v_mfma_f32_16x16x32_fp8_fp8 v[18:21], v[22:23], v[86:87], 0
	s_lshl_b32 s4, s4, 10
	s_mov_b32 s10, s14
	s_mov_b32 s11, s15
	s_bfe_u32 s5, s5, 0x100010
	v_mfma_f32_16x16x32_fp8_fp8 v[46:49], v[24:25], v[82:83], v[18:21]
	s_add_i32 s47, s42, -5
	s_lshl_b32 s5, s5, 10
	buffer_load_dwordx4 v[34:37], v54, s[8:11], s4 offen
	buffer_load_dwordx4 v[22:25], v54, s[8:11], s5 offen
	s_waitcnt vmcnt(3)
	v_mfma_f32_16x16x32_fp8_fp8 v[18:21], v[26:27], v[86:87], 0
	v_readlane_b32 s4, v1, s47
	s_add_i32 s48, s42, -4
	s_bfe_u32 s4, s4, 0x100010
	v_readlane_b32 s5, v1, s48
	s_lshl_b32 s4, s4, 10
	s_bfe_u32 s5, s5, 0x100010
	v_mfma_f32_16x16x32_fp8_fp8 v[50:53], v[28:29], v[82:83], v[18:21]
	s_lshl_b32 s5, s5, 10
	buffer_load_dwordx4 v[38:41], v54, s[8:11], s4 offen
	s_nop 0
	buffer_load_dwordx4 v[18:21], v54, s[8:11], s5 offen
	v_cmp_eq_u32_e32 vcc, 1, v100
	s_waitcnt vmcnt(4)
	v_mfma_f32_16x16x32_fp8_fp8 v[26:29], v[30:31], v[86:87], 0
	v_cmp_eq_u32_e64 s[94:95], 2, v100
	v_cmp_eq_u32_e64 s[96:97], 3, v100
	v_mfma_f32_16x16x32_fp8_fp8 v[28:31], v[32:33], v[82:83], v[26:29]
	v_cndmask_b32_e32 v32, v46, v47, vcc
	v_cndmask_b32_e32 v33, v50, v51, vcc
	v_cndmask_b32_e64 v32, v32, v48, s[94:95]
	s_nop 1
	v_cndmask_b32_e32 v27, v42, v43, vcc
	v_cndmask_b32_e64 v27, v27, v44, s[94:95]
	s_nop 0
	v_cndmask_b32_e32 v28, v28, v29, vcc
	v_cndmask_b32_e64 v33, v33, v52, s[94:95]
	v_cndmask_b32_e64 v28, v28, v30, s[94:95]
	v_cndmask_b32_e64 v27, v27, v45, s[96:97]
	v_cndmask_b32_e64 v32, v32, v49, s[96:97]
	v_cndmask_b32_e64 v33, v33, v53, s[96:97]
	v_cndmask_b32_e64 v28, v28, v31, s[96:97]
	v_cndmask_b32_e64 v27, 0, v27, s[36:37]
	v_cndmask_b32_e64 v32, 0, v32, s[36:37]
	v_cndmask_b32_e64 v33, 0, v33, s[36:37]
	v_cndmask_b32_e64 v28, 0, v28, s[36:37]
	v_permlane32_swap_b32_e32 v27, v32
	s_nop 0
	v_permlane32_swap_b32_e32 v33, v28
	v_add_f32_e32 v27, v27, v32
	v_add_f32_e32 v28, v33, v28
	s_nop 1
	v_permlane16_swap_b32_e32 v27, v28
	ds_bpermute_b32 v26, v8, v0
	v_add_f32_e32 v27, v27, v28
	v_add_u32_e32 v50, s26, v8
	s_nop 0
	v_add_f32_dpp v27, v27, v27 quad_perm:[1,0,3,2] row_mask:0xf bank_mask:0xf bound_ctrl:1
	s_nop 1
	v_add_f32_dpp v27, v27, v27 quad_perm:[2,3,0,1] row_mask:0xf bank_mask:0xf bound_ctrl:1
	s_nop 1
	v_add_f32_dpp v27, v27, v27 row_half_mirror row_mask:0xf bank_mask:0xf bound_ctrl:1
	s_nop 1
	v_mov_b32_dpp v28, v27 row_mirror row_mask:0xf bank_mask:0xf bound_ctrl:1
	s_and_saveexec_b64 s[4:5], s[92:93]
	s_cbranch_execz .LBB0_247
	v_add_f32_e32 v27, v27, v28
	v_mul_f32_e32 v27, 0x3c800000, v27
	v_mul_f32_e32 v28, 0xbdd2d3e7, v27
	v_fmaak_f32 v28, v27, v28, 0xc0135761
	v_mul_f32_e32 v28, v27, v28
	v_exp_f32_e32 v28, v28
	s_waitcnt lgkmcnt(0)
	v_cvt_f32_f16_e32 v26, v26
	v_add_f32_e32 v28, 1.0, v28
	v_rcp_f32_e32 v28, v28
	s_nop 0
	v_mul_f32_e32 v27, v27, v28
	v_mul_f32_e32 v26, v27, v26
	v_mul_f32_e32 v26, 4.0, v26
	v_cvt_pk_f16_f32 v26, v26, v26
	ds_write_b32 v50, v26
.LBB0_247:
	s_or_b64 exec, exec, s[4:5]
	s_waitcnt vmcnt(2)
	v_mfma_f32_16x16x32_fp8_fp8 v[30:33], v[22:23], v[84:85], 0
	v_readlane_b32 s4, v2, s43
	v_mov_b32_e32 v51, v92
	s_bfe_u32 s4, s4, 0x100010
	s_waitcnt lgkmcnt(0)
	v_mfma_f32_16x16x32_fp8_fp8 v[26:29], v[34:35], v[84:85], 0
	v_readlane_b32 s5, v2, s46
	s_lshl_b32 s4, s4, 10
	s_bfe_u32 s5, s5, 0x100010
	v_mfma_f32_16x16x32_fp8_fp8 v[46:49], v[24:25], v[88:89], v[30:33]
	s_lshl_b32 s5, s5, 10
	v_cmp_eq_u32_e32 vcc, 1, v100
	v_cmp_eq_u32_e64 s[94:95], 2, v100
	s_waitcnt vmcnt(1)
	v_mfma_f32_16x16x32_fp8_fp8 v[22:25], v[38:39], v[84:85], 0
	v_cmp_eq_u32_e64 s[96:97], 3, v100
	ds_bpermute_b32 v38, v8, v1
	v_mfma_f32_16x16x32_fp8_fp8 v[42:45], v[36:37], v[88:89], v[26:29]
	buffer_load_dwordx4 v[34:37], v51, s[8:11], s4 offen
	s_nop 1
	buffer_load_dwordx4 v[26:29], v51, s[8:11], s5 offen
	v_readlane_b32 s4, v2, s47
	s_bfe_u32 s4, s4, 0x100010
	v_readlane_b32 s5, v2, s48
	s_lshl_b32 s4, s4, 10
	s_bfe_u32 s5, s5, 0x100010
	s_lshl_b32 s5, s5, 10
	v_mfma_f32_16x16x32_fp8_fp8 v[52:55], v[40:41], v[88:89], v[22:25]
	buffer_load_dwordx4 v[30:33], v51, s[8:11], s4 offen
	s_nop 1
	buffer_load_dwordx4 v[22:25], v51, s[8:11], s5 offen
	v_cndmask_b32_e32 v40, v46, v47, vcc
	v_cndmask_b32_e64 v40, v40, v48, s[94:95]
	s_waitcnt vmcnt(4)
	v_mfma_f32_16x16x32_fp8_fp8 v[56:59], v[18:19], v[84:85], 0
	v_cndmask_b32_e32 v18, v42, v43, vcc
	v_cndmask_b32_e64 v39, v18, v44, s[94:95]
	v_cndmask_b32_e32 v41, v52, v53, vcc
	v_mfma_f32_16x16x32_fp8_fp8 v[18:21], v[20:21], v[88:89], v[56:59]
	v_cndmask_b32_e64 v41, v41, v54, s[94:95]
	v_cndmask_b32_e64 v39, v39, v45, s[96:97]
	v_cndmask_b32_e64 v40, v40, v49, s[96:97]
	v_cndmask_b32_e64 v41, v41, v55, s[96:97]
	v_cndmask_b32_e64 v39, 0, v39, s[36:37]
	s_nop 2
	v_cndmask_b32_e32 v18, v18, v19, vcc
	v_cndmask_b32_e64 v18, v18, v20, s[94:95]
	v_cndmask_b32_e64 v18, v18, v21, s[96:97]
	v_cndmask_b32_e64 v40, 0, v40, s[36:37]
	v_cndmask_b32_e64 v41, 0, v41, s[36:37]
	v_cndmask_b32_e64 v18, 0, v18, s[36:37]
	v_permlane32_swap_b32_e32 v39, v40
	s_nop 0
	v_permlane32_swap_b32_e32 v41, v18
	v_add_f32_e32 v19, v39, v40
	v_add_f32_e32 v18, v41, v18
	s_nop 1
	v_permlane16_swap_b32_e32 v19, v18
	v_add_f32_e32 v18, v19, v18
	s_nop 1
	v_add_f32_dpp v18, v18, v18 quad_perm:[1,0,3,2] row_mask:0xf bank_mask:0xf bound_ctrl:1
	s_nop 1
	v_add_f32_dpp v18, v18, v18 quad_perm:[2,3,0,1] row_mask:0xf bank_mask:0xf bound_ctrl:1
	s_nop 1
	v_add_f32_dpp v18, v18, v18 row_half_mirror row_mask:0xf bank_mask:0xf bound_ctrl:1
	s_nop 1
	v_mov_b32_dpp v19, v18 row_mirror row_mask:0xf bank_mask:0xf bound_ctrl:1
	s_and_saveexec_b64 s[4:5], s[92:93]
	s_cbranch_execz .LBB0_249
	v_add_f32_e32 v18, v18, v19
	v_mul_f32_e32 v18, 0x3c800000, v18
	v_mul_f32_e32 v19, 0xbdd2d3e7, v18
	v_fmaak_f32 v19, v18, v19, 0xc0135761
	v_mul_f32_e32 v19, v18, v19
	v_exp_f32_e32 v19, v19
	s_waitcnt lgkmcnt(0)
	v_cvt_f32_f16_e32 v20, v38
	v_add_f32_e32 v19, 1.0, v19
	v_rcp_f32_e32 v19, v19
	s_nop 0
	v_mul_f32_e32 v18, v18, v19
	v_mul_f32_e32 v18, v18, v20
	v_mul_f32_e32 v18, 4.0, v18
	v_cvt_pk_f16_f32 v18, v18, v18
	ds_write_b32 v50, v18 offset:512
.LBB0_249:
	s_or_b64 exec, exec, s[4:5]
	s_waitcnt vmcnt(3)
	v_mfma_f32_16x16x32_fp8_fp8 v[18:21], v[34:35], v[102:103], 0
	v_readlane_b32 s4, v3, s43
	v_mov_b32_e32 v51, v92
	s_bfe_u32 s4, s4, 0x100010
	v_mfma_f32_16x16x32_fp8_fp8 v[42:45], v[36:37], v[104:105], v[18:21]
	v_readlane_b32 s5, v3, s46
	s_lshl_b32 s4, s4, 10
	s_waitcnt vmcnt(2)
	v_mfma_f32_16x16x32_fp8_fp8 v[18:21], v[26:27], v[102:103], 0
	s_mov_b32 s10, s14
	s_mov_b32 s11, s15
	s_bfe_u32 s5, s5, 0x100010
	v_mfma_f32_16x16x32_fp8_fp8 v[26:29], v[28:29], v[104:105], v[18:21]
	s_lshl_b32 s5, s5, 10
	s_waitcnt lgkmcnt(0)
	buffer_load_dwordx4 v[38:41], v51, s[8:11], s4 offen
	buffer_load_dwordx4 v[34:37], v51, s[8:11], s5 offen
	v_readlane_b32 s4, v3, s47
	s_waitcnt vmcnt(3)
	v_mfma_f32_16x16x32_fp8_fp8 v[18:21], v[30:31], v[102:103], 0
	s_bfe_u32 s4, s4, 0x100010
	v_readlane_b32 s5, v3, s48
	s_lshl_b32 s4, s4, 10
	s_bfe_u32 s5, s5, 0x100010
	s_lshl_b32 s5, s5, 10
	v_mfma_f32_16x16x32_fp8_fp8 v[46:49], v[32:33], v[104:105], v[18:21]
	buffer_load_dwordx4 v[30:33], v51, s[8:11], s4 offen
	s_nop 1
	buffer_load_dwordx4 v[18:21], v51, s[8:11], s5 offen
	v_cmp_eq_u32_e32 vcc, 1, v100
	v_cmp_eq_u32_e64 s[94:95], 2, v100
	s_waitcnt vmcnt(4)
	v_mfma_f32_16x16x32_fp8_fp8 v[52:55], v[22:23], v[102:103], 0
	v_cndmask_b32_e32 v23, v42, v43, vcc
	v_cndmask_b32_e64 v23, v23, v44, s[94:95]
	v_cmp_eq_u32_e64 s[96:97], 3, v100
	v_mfma_f32_16x16x32_fp8_fp8 v[52:55], v[24:25], v[104:105], v[52:55]
	v_cndmask_b32_e32 v24, v26, v27, vcc
	v_cndmask_b32_e32 v25, v46, v47, vcc
	v_cndmask_b32_e64 v24, v24, v28, s[94:95]
	v_cndmask_b32_e64 v25, v25, v48, s[94:95]
	v_cndmask_b32_e64 v23, v23, v45, s[96:97]
	s_nop 2
	v_cndmask_b32_e32 v26, v52, v53, vcc
	v_cndmask_b32_e64 v26, v26, v54, s[94:95]
	v_cndmask_b32_e64 v24, v24, v29, s[96:97]
	v_cndmask_b32_e64 v25, v25, v49, s[96:97]
	v_cndmask_b32_e64 v26, v26, v55, s[96:97]
	v_cndmask_b32_e64 v23, 0, v23, s[36:37]
	v_cndmask_b32_e64 v24, 0, v24, s[36:37]
	v_cndmask_b32_e64 v25, 0, v25, s[36:37]
	v_cndmask_b32_e64 v26, 0, v26, s[36:37]
	v_permlane32_swap_b32_e32 v23, v24
	s_nop 0
	v_permlane32_swap_b32_e32 v25, v26
	v_add_f32_e32 v23, v23, v24
	v_add_f32_e32 v24, v25, v26
	s_nop 1
	v_permlane16_swap_b32_e32 v23, v24
	ds_bpermute_b32 v22, v8, v2
	v_add_f32_e32 v23, v23, v24
	s_nop 1
	v_add_f32_dpp v23, v23, v23 quad_perm:[1,0,3,2] row_mask:0xf bank_mask:0xf bound_ctrl:1
	s_nop 1
	v_add_f32_dpp v23, v23, v23 quad_perm:[2,3,0,1] row_mask:0xf bank_mask:0xf bound_ctrl:1
	s_nop 1
	v_add_f32_dpp v23, v23, v23 row_half_mirror row_mask:0xf bank_mask:0xf bound_ctrl:1
	s_nop 1
	v_mov_b32_dpp v24, v23 row_mirror row_mask:0xf bank_mask:0xf bound_ctrl:1
	s_and_saveexec_b64 s[4:5], s[92:93]
	s_cbranch_execz .LBB0_251
	v_add_f32_e32 v23, v23, v24
	v_mul_f32_e32 v23, 0x3c800000, v23
	v_mul_f32_e32 v24, 0xbdd2d3e7, v23
	v_fmaak_f32 v24, v23, v24, 0xc0135761
	v_mul_f32_e32 v24, v23, v24
	v_exp_f32_e32 v24, v24
	s_waitcnt lgkmcnt(0)
	v_cvt_f32_f16_e32 v22, v22
	v_add_f32_e32 v24, 1.0, v24
	v_rcp_f32_e32 v24, v24
	s_nop 0
	v_mul_f32_e32 v23, v23, v24
	v_mul_f32_e32 v22, v23, v22
	v_mul_f32_e32 v22, 4.0, v22
	v_cvt_pk_f16_f32 v22, v22, v22
	ds_write_b32 v50, v22 offset:1024
.LBB0_251:
	s_or_b64 exec, exec, s[4:5]
	s_waitcnt vmcnt(3) lgkmcnt(0)
	v_mfma_f32_16x16x32_fp8_fp8 v[22:25], v[38:39], v[106:107], 0
	v_readlane_b32 s4, v4, s43
	v_mov_b32_e32 v51, v92
	s_bfe_u32 s4, s4, 0x100010
	v_mfma_f32_16x16x32_fp8_fp8 v[42:45], v[40:41], v[108:109], v[22:25]
	v_readlane_b32 s5, v4, s46
	s_lshl_b32 s4, s4, 10
	s_waitcnt vmcnt(2)
	v_mfma_f32_16x16x32_fp8_fp8 v[22:25], v[34:35], v[106:107], 0
	s_bfe_u32 s5, s5, 0x100010
	s_lshl_b32 s5, s5, 10
	buffer_load_dwordx4 v[38:41], v51, s[8:11], s4 offen
	buffer_load_dwordx4 v[26:29], v51, s[8:11], s5 offen
	v_mfma_f32_16x16x32_fp8_fp8 v[46:49], v[36:37], v[108:109], v[22:25]
	v_readlane_b32 s4, v4, s47
	s_bfe_u32 s4, s4, 0x100010
	v_readlane_b32 s5, v4, s48
	s_waitcnt vmcnt(3)
	v_mfma_f32_16x16x32_fp8_fp8 v[22:25], v[30:31], v[106:107], 0
	s_lshl_b32 s4, s4, 10
	s_bfe_u32 s5, s5, 0x100010
	s_lshl_b32 s5, s5, 10
	v_mfma_f32_16x16x32_fp8_fp8 v[52:55], v[32:33], v[108:109], v[22:25]
	buffer_load_dwordx4 v[30:33], v51, s[8:11], s4 offen
	s_nop 2
	buffer_load_dwordx4 v[22:25], v51, s[8:11], s5 offen
	v_cmp_eq_u32_e32 vcc, 1, v100
	v_cmp_eq_u32_e64 s[94:95], 2, v100
	s_waitcnt vmcnt(4)
	v_mfma_f32_16x16x32_fp8_fp8 v[56:59], v[18:19], v[106:107], 0
	v_cndmask_b32_e32 v18, v42, v43, vcc
	v_cndmask_b32_e64 v35, v18, v44, s[94:95]
	v_cndmask_b32_e32 v36, v46, v47, vcc
	v_mfma_f32_16x16x32_fp8_fp8 v[18:21], v[20:21], v[108:109], v[56:59]
	v_cndmask_b32_e32 v37, v52, v53, vcc
	v_cmp_eq_u32_e64 s[96:97], 3, v100
	v_cndmask_b32_e64 v36, v36, v48, s[94:95]
	v_cndmask_b32_e64 v37, v37, v54, s[94:95]
	v_cndmask_b32_e64 v35, v35, v45, s[96:97]
	s_nop 2
	v_cndmask_b32_e32 v18, v18, v19, vcc
	v_cndmask_b32_e64 v18, v18, v20, s[94:95]
	v_cndmask_b32_e64 v36, v36, v49, s[96:97]
	v_cndmask_b32_e64 v37, v37, v55, s[96:97]
	v_cndmask_b32_e64 v18, v18, v21, s[96:97]
	v_cndmask_b32_e64 v35, 0, v35, s[36:37]
	v_cndmask_b32_e64 v36, 0, v36, s[36:37]
	v_cndmask_b32_e64 v37, 0, v37, s[36:37]
	v_cndmask_b32_e64 v18, 0, v18, s[36:37]
	v_permlane32_swap_b32_e32 v35, v36
	s_nop 0
	v_permlane32_swap_b32_e32 v37, v18
	v_add_f32_e32 v19, v35, v36
	v_add_f32_e32 v18, v37, v18
	s_nop 1
	v_permlane16_swap_b32_e32 v19, v18
	ds_bpermute_b32 v34, v8, v3
	v_add_f32_e32 v18, v19, v18
	s_nop 1
	v_add_f32_dpp v18, v18, v18 quad_perm:[1,0,3,2] row_mask:0xf bank_mask:0xf bound_ctrl:1
	s_nop 1
	v_add_f32_dpp v18, v18, v18 quad_perm:[2,3,0,1] row_mask:0xf bank_mask:0xf bound_ctrl:1
	s_nop 1
	v_add_f32_dpp v18, v18, v18 row_half_mirror row_mask:0xf bank_mask:0xf bound_ctrl:1
	s_nop 1
	v_mov_b32_dpp v19, v18 row_mirror row_mask:0xf bank_mask:0xf bound_ctrl:1
	s_and_saveexec_b64 s[4:5], s[92:93]
	s_cbranch_execz .LBB0_253
	v_add_f32_e32 v18, v18, v19
	v_mul_f32_e32 v18, 0x3c800000, v18
	v_mul_f32_e32 v19, 0xbdd2d3e7, v18
	v_fmaak_f32 v19, v18, v19, 0xc0135761
	v_mul_f32_e32 v19, v18, v19
	v_exp_f32_e32 v19, v19
	s_waitcnt lgkmcnt(0)
	v_cvt_f32_f16_e32 v20, v34
	v_add_f32_e32 v19, 1.0, v19
	v_rcp_f32_e32 v19, v19
	s_nop 0
	v_mul_f32_e32 v18, v18, v19
	v_mul_f32_e32 v18, v18, v20
	v_mul_f32_e32 v18, 4.0, v18
	v_cvt_pk_f16_f32 v18, v18, v18
	ds_write_b32 v50, v18 offset:1536
.LBB0_253:
	s_or_b64 exec, exec, s[4:5]
	s_waitcnt vmcnt(2) lgkmcnt(0)
	v_mfma_f32_16x16x32_fp8_fp8 v[34:37], v[26:27], v[110:111], 0
	v_readlane_b32 s4, v5, s43
	v_mov_b32_e32 v51, v92
	s_bfe_u32 s4, s4, 0x100010
	v_mfma_f32_16x16x32_fp8_fp8 v[18:21], v[38:39], v[110:111], 0
	v_readlane_b32 s5, v5, s46
	s_lshl_b32 s4, s4, 10
	s_mov_b32 s10, s14
	s_mov_b32 s11, s15
	s_bfe_u32 s5, s5, 0x100010
	v_mfma_f32_16x16x32_fp8_fp8 v[46:49], v[28:29], v[112:113], v[34:37]
	s_lshl_b32 s5, s5, 10
	v_cmp_eq_u32_e32 vcc, 1, v100
	v_cmp_eq_u32_e64 s[94:95], 2, v100
	s_waitcnt vmcnt(1)
	v_mfma_f32_16x16x32_fp8_fp8 v[26:29], v[30:31], v[110:111], 0
	v_cmp_eq_u32_e64 s[96:97], 3, v100
	v_mfma_f32_16x16x32_fp8_fp8 v[42:45], v[40:41], v[112:113], v[18:21]
	s_nop 2
	buffer_load_dwordx4 v[18:21], v51, s[8:11], s4 offen
	buffer_load_dwordx4 v[38:41], v51, s[8:11], s5 offen
	v_readlane_b32 s4, v5, s47
	s_bfe_u32 s4, s4, 0x100010
	v_readlane_b32 s5, v5, s48
	s_lshl_b32 s4, s4, 10
	s_bfe_u32 s5, s5, 0x100010
	s_lshl_b32 s5, s5, 10
	v_mfma_f32_16x16x32_fp8_fp8 v[30:33], v[32:33], v[112:113], v[26:29]
	s_nop 2
	buffer_load_dwordx4 v[26:29], v51, s[8:11], s4 offen
	buffer_load_dwordx4 v[34:37], v51, s[8:11], s5 offen
	s_waitcnt vmcnt(4)
	v_mfma_f32_16x16x32_fp8_fp8 v[52:55], v[22:23], v[110:111], 0
	v_cndmask_b32_e32 v23, v42, v43, vcc
	v_cndmask_b32_e64 v23, v23, v44, s[94:95]
	v_cndmask_b32_e64 v23, v23, v45, s[96:97]
	v_mfma_f32_16x16x32_fp8_fp8 v[52:55], v[24:25], v[112:113], v[52:55]
	v_cndmask_b32_e32 v24, v46, v47, vcc
	v_cndmask_b32_e32 v25, v30, v31, vcc
	v_cndmask_b32_e64 v24, v24, v48, s[94:95]
	v_cndmask_b32_e64 v25, v25, v32, s[94:95]
	v_cndmask_b32_e64 v24, v24, v49, s[96:97]
	s_nop 2
	v_cndmask_b32_e32 v30, v52, v53, vcc
	v_cndmask_b32_e64 v30, v30, v54, s[94:95]
	v_cndmask_b32_e64 v25, v25, v33, s[96:97]
	v_cndmask_b32_e64 v30, v30, v55, s[96:97]
	v_cndmask_b32_e64 v23, 0, v23, s[36:37]
	v_cndmask_b32_e64 v24, 0, v24, s[36:37]
	v_cndmask_b32_e64 v25, 0, v25, s[36:37]
	v_cndmask_b32_e64 v30, 0, v30, s[36:37]
	v_permlane32_swap_b32_e32 v23, v24
	s_nop 0
	v_permlane32_swap_b32_e32 v25, v30
	v_add_f32_e32 v23, v23, v24
	v_add_f32_e32 v24, v25, v30
	s_nop 1
	v_permlane16_swap_b32_e32 v23, v24
	ds_bpermute_b32 v22, v8, v4
	v_add_f32_e32 v23, v23, v24
	s_nop 1
	v_add_f32_dpp v23, v23, v23 quad_perm:[1,0,3,2] row_mask:0xf bank_mask:0xf bound_ctrl:1
	s_nop 1
	v_add_f32_dpp v23, v23, v23 quad_perm:[2,3,0,1] row_mask:0xf bank_mask:0xf bound_ctrl:1
	s_nop 1
	v_add_f32_dpp v23, v23, v23 row_half_mirror row_mask:0xf bank_mask:0xf bound_ctrl:1
	s_nop 1
	v_mov_b32_dpp v24, v23 row_mirror row_mask:0xf bank_mask:0xf bound_ctrl:1
	s_and_saveexec_b64 s[4:5], s[92:93]
	s_cbranch_execz .LBB0_255
	v_add_f32_e32 v23, v23, v24
	v_mul_f32_e32 v23, 0x3c800000, v23
	v_mul_f32_e32 v24, 0xbdd2d3e7, v23
	v_fmaak_f32 v24, v23, v24, 0xc0135761
	v_mul_f32_e32 v24, v23, v24
	v_exp_f32_e32 v24, v24
	s_waitcnt lgkmcnt(0)
	v_cvt_f32_f16_e32 v22, v22
	v_add_f32_e32 v24, 1.0, v24
	v_rcp_f32_e32 v24, v24
	s_nop 0
	v_mul_f32_e32 v23, v23, v24
	v_mul_f32_e32 v22, v23, v22
	v_mul_f32_e32 v22, 4.0, v22
	v_cvt_pk_f16_f32 v22, v22, v22
	ds_write_b32 v50, v22 offset:2048
.LBB0_255:
	s_or_b64 exec, exec, s[4:5]
	s_waitcnt vmcnt(2)
	v_mfma_f32_16x16x32_fp8_fp8 v[30:33], v[38:39], v[114:115], 0
	v_readlane_b32 s4, v6, s43
	v_mov_b32_e32 v51, v92
	s_bfe_u32 s4, s4, 0x100010
	s_waitcnt lgkmcnt(0)
	v_mfma_f32_16x16x32_fp8_fp8 v[22:25], v[18:19], v[114:115], 0
	v_readlane_b32 s5, v6, s46
	s_lshl_b32 s4, s4, 10
	s_bfe_u32 s5, s5, 0x100010
	v_mfma_f32_16x16x32_fp8_fp8 v[46:49], v[40:41], v[116:117], v[30:33]
	s_lshl_b32 s5, s5, 10
	v_cmp_eq_u32_e32 vcc, 1, v100
	v_cmp_eq_u32_e64 s[94:95], 2, v100
	s_waitcnt vmcnt(1)
	v_mfma_f32_16x16x32_fp8_fp8 v[30:33], v[26:27], v[114:115], 0
	v_cmp_eq_u32_e64 s[96:97], 3, v100
	s_nop 1
	v_cndmask_b32_e32 v40, v46, v47, vcc
	v_cndmask_b32_e64 v40, v40, v48, s[94:95]
	v_mfma_f32_16x16x32_fp8_fp8 v[42:45], v[20:21], v[116:117], v[22:25]
	buffer_load_dwordx4 v[18:21], v51, s[8:11], s4 offen
	s_nop 1
	buffer_load_dwordx4 v[22:25], v51, s[8:11], s5 offen
	v_readlane_b32 s4, v6, s47
	s_bfe_u32 s4, s4, 0x100010
	v_readlane_b32 s5, v6, s48
	s_lshl_b32 s4, s4, 10
	s_bfe_u32 s5, s5, 0x100010
	s_lshl_b32 s5, s5, 10
	v_mfma_f32_16x16x32_fp8_fp8 v[52:55], v[28:29], v[116:117], v[30:33]
	buffer_load_dwordx4 v[26:29], v51, s[8:11], s4 offen
	s_nop 1
	buffer_load_dwordx4 v[30:33], v51, s[8:11], s5 offen
	v_cndmask_b32_e64 v40, v40, v49, s[96:97]
	v_cndmask_b32_e64 v40, 0, v40, s[36:37]
	s_waitcnt vmcnt(4)
	v_mfma_f32_16x16x32_fp8_fp8 v[56:59], v[34:35], v[114:115], 0
	v_cndmask_b32_e32 v34, v42, v43, vcc
	v_cndmask_b32_e64 v39, v34, v44, s[94:95]
	v_cndmask_b32_e32 v41, v52, v53, vcc
	v_mfma_f32_16x16x32_fp8_fp8 v[34:37], v[36:37], v[116:117], v[56:59]
	v_cndmask_b32_e64 v41, v41, v54, s[94:95]
	v_cndmask_b32_e64 v39, v39, v45, s[96:97]
	v_cndmask_b32_e64 v41, v41, v55, s[96:97]
	v_cndmask_b32_e64 v39, 0, v39, s[36:37]
	v_cndmask_b32_e64 v41, 0, v41, s[36:37]
	s_nop 2
	v_cndmask_b32_e32 v34, v34, v35, vcc
	v_cndmask_b32_e64 v34, v34, v36, s[94:95]
	v_cndmask_b32_e64 v34, v34, v37, s[96:97]
	v_cndmask_b32_e64 v34, 0, v34, s[36:37]
	v_permlane32_swap_b32_e32 v39, v40
	s_nop 0
	v_permlane32_swap_b32_e32 v41, v34
	v_add_f32_e32 v35, v39, v40
	v_add_f32_e32 v34, v41, v34
	s_nop 1
	v_permlane16_swap_b32_e32 v35, v34
	ds_bpermute_b32 v38, v8, v5
	v_add_f32_e32 v34, v35, v34
	s_nop 1
	v_add_f32_dpp v34, v34, v34 quad_perm:[1,0,3,2] row_mask:0xf bank_mask:0xf bound_ctrl:1
	s_nop 1
	v_add_f32_dpp v34, v34, v34 quad_perm:[2,3,0,1] row_mask:0xf bank_mask:0xf bound_ctrl:1
	s_nop 1
	v_add_f32_dpp v34, v34, v34 row_half_mirror row_mask:0xf bank_mask:0xf bound_ctrl:1
	s_nop 1
	v_mov_b32_dpp v35, v34 row_mirror row_mask:0xf bank_mask:0xf bound_ctrl:1
	s_and_saveexec_b64 s[4:5], s[92:93]
	s_cbranch_execz .LBB0_257
	v_add_f32_e32 v34, v34, v35
	v_mul_f32_e32 v34, 0x3c800000, v34
	v_mul_f32_e32 v35, 0xbdd2d3e7, v34
	v_fmaak_f32 v35, v34, v35, 0xc0135761
	v_mul_f32_e32 v35, v34, v35
	v_exp_f32_e32 v35, v35
	s_waitcnt lgkmcnt(0)
	v_cvt_f32_f16_e32 v36, v38
	v_add_f32_e32 v35, 1.0, v35
	v_rcp_f32_e32 v35, v35
	s_nop 0
	v_mul_f32_e32 v34, v34, v35
	v_mul_f32_e32 v34, v34, v36
	v_mul_f32_e32 v34, 4.0, v34
	v_cvt_pk_f16_f32 v34, v34, v34
	ds_write_b32 v50, v34 offset:2560
.LBB0_257:
	s_or_b64 exec, exec, s[4:5]
	v_readlane_b32 s4, v7, s43
	s_bfe_u32 s4, s4, 0x100010
	v_mov_b32_e32 v34, v92
	s_lshl_b32 s4, s4, 10
	s_mov_b32 s10, s14
	s_mov_b32 s11, s15
	buffer_load_dwordx4 v[46:49], v34, s[8:11], s4 offen
	v_readlane_b32 s4, v7, s46
	s_bfe_u32 s4, s4, 0x100010
	s_lshl_b32 s4, s4, 10
	s_waitcnt vmcnt(4)
	v_mfma_f32_16x16x32_fp8_fp8 v[52:55], v[18:19], v[118:119], 0
	v_cmp_eq_u32_e32 vcc, 1, v100
	v_cmp_eq_u32_e64 s[94:95], 2, v100
	buffer_load_dwordx4 v[42:45], v34, s[8:11], s4 offen
	v_readlane_b32 s4, v7, s47
	s_bfe_u32 s4, s4, 0x100010
	s_lshl_b32 s4, s4, 10
	s_waitcnt vmcnt(4)
	v_mfma_f32_16x16x32_fp8_fp8 v[56:59], v[22:23], v[118:119], 0
	v_cmp_eq_u32_e64 s[96:97], 3, v100
	ds_bpermute_b32 v51, v8, v6
	s_waitcnt lgkmcnt(1)
	buffer_load_dwordx4 v[38:41], v34, s[8:11], s4 offen
	v_readlane_b32 s4, v7, s48
	s_bfe_u32 s4, s4, 0x100010
	s_lshl_b32 s4, s4, 10
	s_waitcnt vmcnt(4)
	v_mfma_f32_16x16x32_fp8_fp8 v[60:63], v[26:27], v[118:119], 0
	s_nop 0
	buffer_load_dwordx4 v[34:37], v34, s[8:11], s4 offen
	s_waitcnt vmcnt(4)
	v_mfma_f32_16x16x32_fp8_fp8 v[64:67], v[30:31], v[118:119], 0
	v_mfma_f32_16x16x32_fp8_fp8 v[52:55], v[20:21], v[120:121], v[52:55]
	v_mfma_f32_16x16x32_fp8_fp8 v[56:59], v[24:25], v[120:121], v[56:59]
	v_mfma_f32_16x16x32_fp8_fp8 v[60:63], v[28:29], v[120:121], v[60:63]
	s_nop 5
	v_cndmask_b32_e32 v52, v52, v53, vcc
	v_cndmask_b32_e64 v52, v52, v54, s[94:95]
	v_cndmask_b32_e64 v52, v52, v55, s[96:97]
	v_mfma_f32_16x16x32_fp8_fp8 v[64:67], v[32:33], v[120:121], v[64:67]
	v_cndmask_b32_e32 v53, v56, v57, vcc
	v_cndmask_b32_e32 v54, v60, v61, vcc
	v_cndmask_b32_e64 v53, v53, v58, s[94:95]
	v_cndmask_b32_e64 v54, v54, v62, s[94:95]
	v_cndmask_b32_e64 v53, v53, v59, s[96:97]
	s_nop 2
	v_cndmask_b32_e32 v55, v64, v65, vcc
	v_cndmask_b32_e64 v55, v55, v66, s[94:95]
	v_cndmask_b32_e64 v54, v54, v63, s[96:97]
	v_cndmask_b32_e64 v55, v55, v67, s[96:97]
	v_cndmask_b32_e64 v52, 0, v52, s[36:37]
	v_cndmask_b32_e64 v53, 0, v53, s[36:37]
	v_cndmask_b32_e64 v54, 0, v54, s[36:37]
	v_cndmask_b32_e64 v55, 0, v55, s[36:37]
	v_permlane32_swap_b32_e32 v52, v53
	s_nop 0
	v_permlane32_swap_b32_e32 v54, v55
	v_add_f32_e32 v52, v52, v53
	v_add_f32_e32 v53, v54, v55
	s_nop 1
	v_permlane16_swap_b32_e32 v52, v53
	v_add_f32_e32 v52, v52, v53
	s_nop 1
	v_add_f32_dpp v52, v52, v52 quad_perm:[1,0,3,2] row_mask:0xf bank_mask:0xf bound_ctrl:1
	s_nop 1
	v_add_f32_dpp v52, v52, v52 quad_perm:[2,3,0,1] row_mask:0xf bank_mask:0xf bound_ctrl:1
	s_nop 1
	v_add_f32_dpp v52, v52, v52 row_half_mirror row_mask:0xf bank_mask:0xf bound_ctrl:1
	s_nop 1
	v_mov_b32_dpp v53, v52 row_mirror row_mask:0xf bank_mask:0xf bound_ctrl:1
	s_and_saveexec_b64 s[4:5], s[92:93]
	s_cbranch_execz .LBB0_259
	v_add_f32_e32 v52, v52, v53
	v_mul_f32_e32 v52, 0x3c800000, v52
	v_mul_f32_e32 v53, 0xbdd2d3e7, v52
	v_fmaak_f32 v53, v52, v53, 0xc0135761
	v_mul_f32_e32 v53, v52, v53
	v_exp_f32_e32 v53, v53
	s_waitcnt lgkmcnt(0)
	v_cvt_f32_f16_e32 v51, v51
	v_add_f32_e32 v53, 1.0, v53
	v_rcp_f32_e32 v53, v53
	s_nop 0
	v_mul_f32_e32 v52, v52, v53
	v_mul_f32_e32 v51, v52, v51
	v_mul_f32_e32 v51, 4.0, v51
	v_cvt_pk_f16_f32 v51, v51, v51
	ds_write_b32 v50, v51 offset:3072

.LBB0_261:
	s_waitcnt vmcnt(3)
	v_mfma_f32_16x16x32_fp8_fp8 v[52:55], v[46:47], v[122:123], 0
	v_cmp_eq_u32_e32 vcc, 1, v100
	v_cmp_eq_u32_e64 s[94:95], 2, v100
	v_cmp_eq_u32_e64 s[96:97], 3, v100
	v_mfma_f32_16x16x32_fp8_fp8 v[46:49], v[48:49], v[124:125], v[52:55]
	s_waitcnt vmcnt(2)
	v_mfma_f32_16x16x32_fp8_fp8 v[52:55], v[42:43], v[122:123], 0
	ds_bpermute_b32 v42, v8, v7
	s_nop 4
	v_cndmask_b32_e32 v43, v46, v47, vcc
	v_cndmask_b32_e64 v43, v43, v48, s[94:95]
	v_mfma_f32_16x16x32_fp8_fp8 v[44:47], v[44:45], v[124:125], v[52:55]
	v_cndmask_b32_e64 v43, v43, v49, s[96:97]
	v_cndmask_b32_e64 v43, 0, v43, s[36:37]
	s_waitcnt vmcnt(1)
	v_mfma_f32_16x16x32_fp8_fp8 v[52:55], v[38:39], v[122:123], 0
	s_nop 3
	v_cndmask_b32_e32 v38, v44, v45, vcc
	v_cndmask_b32_e64 v44, v38, v46, s[94:95]
	v_mfma_f32_16x16x32_fp8_fp8 v[38:41], v[40:41], v[124:125], v[52:55]
	v_cndmask_b32_e64 v44, v44, v47, s[96:97]
	v_cndmask_b32_e64 v48, 0, v44, s[36:37]
	s_nop 1
	v_permlane32_swap_b32_e32 v43, v48
	s_waitcnt vmcnt(0)
	v_mfma_f32_16x16x32_fp8_fp8 v[44:47], v[34:35], v[122:123], 0
	s_nop 0
	v_cndmask_b32_e32 v38, v38, v39, vcc
	v_cndmask_b32_e64 v34, v38, v40, s[94:95]
	v_cndmask_b32_e64 v34, v34, v41, s[96:97]
	v_cndmask_b32_e64 v38, 0, v34, s[36:37]
	v_mfma_f32_16x16x32_fp8_fp8 v[34:37], v[36:37], v[124:125], v[44:47]
	s_nop 7
	v_cndmask_b32_e32 v34, v34, v35, vcc
	v_cndmask_b32_e64 v34, v34, v36, s[94:95]
	v_cndmask_b32_e64 v34, v34, v37, s[96:97]
	v_cndmask_b32_e64 v34, 0, v34, s[36:37]
	s_nop 1
	v_permlane32_swap_b32_e32 v38, v34
	v_add_f32_e32 v35, v43, v48
	v_add_f32_e32 v34, v38, v34
	s_nop 1
	v_permlane16_swap_b32_e32 v35, v34
	v_add_f32_e32 v34, v35, v34
	s_nop 1
	v_add_f32_dpp v34, v34, v34 quad_perm:[1,0,3,2] row_mask:0xf bank_mask:0xf bound_ctrl:1
	s_nop 1
	v_add_f32_dpp v34, v34, v34 quad_perm:[2,3,0,1] row_mask:0xf bank_mask:0xf bound_ctrl:1
	s_nop 1
	v_add_f32_dpp v34, v34, v34 row_half_mirror row_mask:0xf bank_mask:0xf bound_ctrl:1
	s_nop 1
	v_mov_b32_dpp v35, v34 row_mirror row_mask:0xf bank_mask:0xf bound_ctrl:1
	s_and_saveexec_b64 s[4:5], s[92:93]
	s_cbranch_execz .LBB0_242
	v_add_f32_e32 v34, v34, v35
	v_mul_f32_e32 v34, 0x3c800000, v34
	v_mul_f32_e32 v35, 0xbdd2d3e7, v34
	v_fmaak_f32 v35, v34, v35, 0xc0135761
	v_mul_f32_e32 v35, v34, v35
	v_exp_f32_e32 v35, v35
	s_waitcnt lgkmcnt(0)
	v_cvt_f32_f16_e32 v36, v42
	v_add_f32_e32 v35, 1.0, v35
	v_rcp_f32_e32 v35, v35
	s_nop 0
	v_mul_f32_e32 v34, v34, v35
	v_mul_f32_e32 v34, v34, v36
	v_mul_f32_e32 v34, 4.0, v34
	v_cvt_pk_f16_f32 v34, v34, v34
	ds_write_b32 v50, v34 offset:3584
	s_branch .LBB0_242

.LBB0_628:
	s_lshl_b32 s5, s65, 8
	v_mov_b32_e32 v146, v159
	v_mov_b32_e32 v147, v176
	s_or_b32 s5, s5, s59
	s_lshl_b32 s4, s38, 8
	v_lshl_add_u32 v170, v147, 3, s5
	v_ashrrev_i32_e32 v171, 31, v170
	v_lshl_add_u64 v[36:37], v[170:171], 2, s[12:13]
	global_load_dwordx4 v[40:43], v[36:37], off offset:16
	global_load_dwordx4 v[44:47], v[36:37], off
	global_load_dwordx4 v[32:35], v[36:37], off offset:528
	s_nop 0
	global_load_dwordx4 v[36:39], v[36:37], off offset:512
	s_add_i32 s4, s4, s58
	v_add_u32_e32 v172, s4, v146
	v_lshlrev_b32_e32 v146, 2, v146
	v_lshl_add_u32 v146, v147, 6, v146
	v_xor_b32_e32 v180, 64, v146
	v_xor_b32_e32 v179, 0x80, v146
	s_cmp_gt_i32 s65, 7
	s_cselect_b64 s[52:53], -1, 0
	s_lshl_b32 s4, s65, 2
	s_sub_i32 s4, s4, 32
	v_ashrrev_i32_e32 v173, 31, v172
	s_ashr_i32 s5, s4, 31
	v_lshlrev_b64 v[174:175], 13, v[172:173]
	s_or_b64 s[50:51], s[4:5], s[30:31]
	s_cmp_lt_i32 s65, 8
	v_cmp_eq_u32_e64 s[38:39], 0, v147
	s_waitcnt vmcnt(0)
	v_pk_add_f32 v[136:137], v[136:137], v[40:41]
	v_pk_add_f32 v[140:141], v[140:141], v[44:45]
	v_pk_add_f32 v[142:143], v[142:143], v[46:47]
	v_mul_f32_e32 v146, 0xbdd2d3e7, v140
	v_fmaak_f32 v146, v140, v146, 0xc0135761
	v_mul_f32_e32 v146, v140, v146
	v_exp_f32_e32 v146, v146
	v_pk_add_f32 v[138:139], v[138:139], v[42:43]
	v_pk_add_f32 v[132:133], v[132:133], v[36:37]
	v_pk_add_f32 v[128:129], v[128:129], v[32:33]
	v_add_f32_e32 v146, 1.0, v146
	v_rcp_f32_e32 v146, v146
	v_pk_add_f32 v[134:135], v[134:135], v[38:39]
	v_pk_add_f32 v[130:131], v[130:131], v[34:35]
	v_mul_f32_e32 v140, v140, v146
	v_mul_f32_e32 v146, 0xbdd2d3e7, v136
	v_fmaak_f32 v146, v136, v146, 0xc0135761
	v_mul_f32_e32 v146, v136, v146
	v_exp_f32_e32 v146, v146
	s_nop 0
	v_add_f32_e32 v146, 1.0, v146
	v_rcp_f32_e32 v146, v146
	s_nop 0
	v_mul_f32_e32 v146, v136, v146
	v_mul_f32_e32 v136, 0xbdd2d3e7, v141
	v_fmaak_f32 v136, v141, v136, 0xc0135761
	v_mul_f32_e32 v136, v141, v136
	v_exp_f32_e32 v136, v136
	s_nop 0
	v_add_f32_e32 v136, 1.0, v136
	v_rcp_f32_e32 v136, v136
	s_nop 0
	v_mul_f32_e32 v136, v141, v136
	v_mul_f32_e32 v141, 0xbdd2d3e7, v137
	v_fmaak_f32 v141, v137, v141, 0xc0135761
	v_mul_f32_e32 v141, v137, v141
	v_exp_f32_e32 v141, v141
	v_cvt_pk_bf16_f32 v136, v140, v136
	v_add_f32_e32 v141, 1.0, v141
	v_rcp_f32_e32 v141, v141
	s_nop 0
	v_mul_f32_e32 v141, v137, v141
	v_mul_f32_e32 v137, 0xbdd2d3e7, v142
	v_fmaak_f32 v137, v142, v137, 0xc0135761
	v_mul_f32_e32 v137, v142, v137
	v_exp_f32_e32 v137, v137
	s_nop 0
	v_add_f32_e32 v137, 1.0, v137
	v_rcp_f32_e32 v137, v137
	s_nop 0
	v_mul_f32_e32 v137, v142, v137
	v_mul_f32_e32 v142, 0xbdd2d3e7, v138
	v_fmaak_f32 v142, v138, v142, 0xc0135761
	v_mul_f32_e32 v142, v138, v142
	v_exp_f32_e32 v142, v142
	s_nop 0
	v_add_f32_e32 v142, 1.0, v142
	v_rcp_f32_e32 v142, v142
	s_nop 0
	v_mul_f32_e32 v142, v138, v142
	v_mul_f32_e32 v138, 0xbdd2d3e7, v143
	v_fmaak_f32 v138, v143, v138, 0xc0135761
	v_mul_f32_e32 v138, v143, v138
	v_exp_f32_e32 v138, v138
	s_nop 0
	v_add_f32_e32 v138, 1.0, v138
	v_rcp_f32_e32 v138, v138
	s_nop 0
	v_mul_f32_e32 v138, v143, v138
	v_mul_f32_e32 v143, 0xbdd2d3e7, v139
	v_fmaak_f32 v143, v139, v143, 0xc0135761
	v_mul_f32_e32 v143, v139, v143
	v_exp_f32_e32 v143, v143
	v_cvt_pk_bf16_f32 v137, v137, v138
	v_cvt_pk_bf16_f32 v138, v146, v141
	v_lshl_add_u64 v[140:141], s[10:11], 0, v[174:175]
	v_add_f32_e32 v143, 1.0, v143
	v_rcp_f32_e32 v143, v143
	v_lshl_add_u64 v[140:141], v[170:171], 1, v[140:141]
	v_mul_f32_e32 v139, v139, v143
	v_cvt_pk_bf16_f32 v139, v142, v139
	v_mul_f32_e32 v142, 0xbdd2d3e7, v132
	v_fmaak_f32 v142, v132, v142, 0xc0135761
	v_mul_f32_e32 v142, v132, v142
	v_exp_f32_e32 v142, v142
	global_store_dwordx4 v[140:141], v[136:139], off
	v_add_f32_e32 v142, 1.0, v142
	v_rcp_f32_e32 v142, v142
	s_nop 0
	v_mul_f32_e32 v132, v132, v142
	v_mul_f32_e32 v142, 0xbdd2d3e7, v128
	v_fmaak_f32 v142, v128, v142, 0xc0135761
	v_mul_f32_e32 v142, v128, v142
	v_exp_f32_e32 v142, v142
	s_nop 0
	v_add_f32_e32 v142, 1.0, v142
	v_rcp_f32_e32 v142, v142
	s_nop 0
	v_mul_f32_e32 v142, v128, v142
	v_mul_f32_e32 v128, 0xbdd2d3e7, v133
	v_fmaak_f32 v128, v133, v128, 0xc0135761
	v_mul_f32_e32 v128, v133, v128
	v_exp_f32_e32 v128, v128
	s_nop 0
	v_add_f32_e32 v128, 1.0, v128
	v_rcp_f32_e32 v128, v128
	s_nop 0
	v_mul_f32_e32 v128, v133, v128
	v_mul_f32_e32 v133, 0xbdd2d3e7, v129
	v_fmaak_f32 v133, v129, v133, 0xc0135761
	v_mul_f32_e32 v133, v129, v133
	v_exp_f32_e32 v133, v133
	v_cvt_pk_bf16_f32 v128, v132, v128
	v_add_f32_e32 v133, 1.0, v133
	v_rcp_f32_e32 v133, v133
	s_nop 0
	v_mul_f32_e32 v133, v129, v133
	v_mul_f32_e32 v129, 0xbdd2d3e7, v134
	v_fmaak_f32 v129, v134, v129, 0xc0135761
	v_mul_f32_e32 v129, v134, v129
	v_exp_f32_e32 v129, v129
	s_nop 0
	v_add_f32_e32 v129, 1.0, v129
	v_rcp_f32_e32 v129, v129
	s_nop 0
	v_mul_f32_e32 v129, v134, v129
	v_mul_f32_e32 v134, 0xbdd2d3e7, v130
	v_fmaak_f32 v134, v130, v134, 0xc0135761
	v_mul_f32_e32 v134, v130, v134
	v_exp_f32_e32 v134, v134
	s_nop 0
	v_add_f32_e32 v134, 1.0, v134
	v_rcp_f32_e32 v134, v134
	s_nop 0
	v_mul_f32_e32 v134, v130, v134
	v_mul_f32_e32 v130, 0xbdd2d3e7, v135
	v_fmaak_f32 v130, v135, v130, 0xc0135761
	v_mul_f32_e32 v130, v135, v130
	v_exp_f32_e32 v130, v130
	s_nop 0
	v_add_f32_e32 v130, 1.0, v130
	v_rcp_f32_e32 v130, v130
	s_nop 0
	v_mul_f32_e32 v130, v135, v130
	v_mul_f32_e32 v135, 0xbdd2d3e7, v131
	v_fmaak_f32 v135, v131, v135, 0xc0135761
	v_mul_f32_e32 v135, v131, v135
	v_exp_f32_e32 v135, v135
	v_cvt_pk_bf16_f32 v129, v129, v130
	v_cvt_pk_bf16_f32 v130, v142, v133
	v_add_f32_e32 v135, 1.0, v135
	v_rcp_f32_e32 v135, v135
	s_nop 0
	v_mul_f32_e32 v131, v131, v135
	v_cvt_pk_bf16_f32 v131, v134, v131
	global_store_dwordx4 v[140:141], v[128:131], off offset:256
	s_cbranch_scc1 .LBB0_632
	v_lshlrev_b32_e32 v133, 16, v128
	v_and_b32_e32 v141, 0xffff0000, v128
	v_lshlrev_b32_e32 v132, 16, v136
	v_and_b32_e32 v134, 0xffff0000, v136
	v_lshlrev_b32_e32 v136, 16, v137
	v_and_b32_e32 v140, 0xffff0000, v137
	v_mov_b32_e32 v135, v133
	v_mov_b32_e32 v137, v141
	v_lshlrev_b32_e32 v143, 16, v129
	v_and_b32_e32 v147, 0xffff0000, v129
	v_pk_mul_f32 v[152:153], v[132:133], v[132:133]
	v_pk_mul_f32 v[154:155], v[134:135], v[134:135]
	v_pk_mul_f32 v[156:157], v[136:137], v[136:137]
	v_pk_mul_f32 v[174:175], v[140:141], v[140:141]
	v_pk_add_f32 v[134:135], v[132:133], v[134:135]
	v_pk_add_f32 v[136:137], v[140:141], v[136:137]
	v_lshlrev_b32_e32 v142, 16, v138
	v_and_b32_e32 v128, 0xffff0000, v138
	v_lshlrev_b32_e32 v138, 16, v139
	v_and_b32_e32 v146, 0xffff0000, v139
	v_mov_b32_e32 v129, v143
	v_mov_b32_e32 v139, v147
	v_mov_b32_e32 v135, v153
	v_mov_b32_e32 v137, v175
	v_pk_mul_f32 v[182:183], v[142:143], v[142:143]
	v_pk_mul_f32 v[184:185], v[128:129], v[128:129]
	v_pk_mul_f32 v[188:189], v[146:147], v[146:147]
	v_pk_add_f32 v[134:135], v[134:135], v[136:137]
	v_pk_add_f32 v[128:129], v[142:143], v[128:129]
	v_pk_add_f32 v[136:137], v[146:147], v[138:139]
	v_mov_b32_e32 v129, v183
	v_mov_b32_e32 v137, v189
	v_pk_add_f32 v[128:129], v[128:129], v[136:137]
	v_pk_mov_b32 v[132:133], v[132:133], v[152:153] op_sel:[1,0]
	v_pk_add_f32 v[128:129], v[134:135], v[128:129]
	v_pk_mov_b32 v[134:135], v[140:141], v[154:155] op_sel:[1,0]
	v_pk_mov_b32 v[136:137], v[146:147], v[174:175] op_sel:[1,0]
	v_pk_add_f32 v[132:133], v[132:133], v[134:135]
	v_pk_mov_b32 v[134:135], v[142:143], v[156:157] op_sel:[1,0]
	v_lshlrev_b32_e32 v149, 16, v131
	v_lshlrev_b32_e32 v148, 16, v130
	v_and_b32_e32 v131, 0xffff0000, v131
	v_and_b32_e32 v130, 0xffff0000, v130
	v_pk_add_f32 v[134:135], v[134:135], v[136:137]
	v_pk_mul_f32 v[150:151], v[130:131], v[130:131]
	v_pk_mul_f32 v[186:187], v[138:139], v[138:139]
	v_pk_add_f32 v[132:133], v[132:133], v[134:135]
	v_mov_b32_e32 v134, v148
	v_mov_b32_e32 v135, v182
	v_mov_b32_e32 v136, v130
	v_mov_b32_e32 v137, v184
	v_pk_fma_f32 v[150:151], v[148:149], v[148:149], v[150:151]
	v_pk_add_f32 v[134:135], v[134:135], v[136:137]
	v_pk_mov_b32 v[136:137], v[148:149], v[186:187] op_sel:[1,0]
	v_pk_mov_b32 v[130:131], v[130:131], v[188:189] op_sel:[1,0]
	v_pk_add_f32 v[150:151], v[150:151], v[150:151] op_sel_hi:[0,1]
	v_pk_add_f32 v[130:131], v[136:137], v[130:131]
	v_mov_b32_e32 v150, v145
	v_pk_add_f32 v[130:131], v[134:135], v[130:131]
	v_pk_add_f32 v[128:129], v[128:129], v[150:151]
	v_pk_add_f32 v[130:131], v[132:133], v[130:131]
	s_nop 0
	v_pk_add_f32 v[128:129], v[130:131], v[128:129]
	ds_bpermute_b32 v130, v180, v128
	ds_bpermute_b32 v131, v180, v129
	s_waitcnt lgkmcnt(0)
	v_pk_add_f32 v[128:129], v[128:129], v[130:131]
	ds_bpermute_b32 v130, v179, v128
	ds_bpermute_b32 v131, v179, v129
	s_and_saveexec_b64 s[4:5], s[38:39]
	s_cbranch_execz .LBB0_631
	v_lshlrev_b64 v[132:133], 8, v[172:173]
	s_waitcnt lgkmcnt(0)
	v_pk_add_f32 v[128:129], v[128:129], v[130:131]
	v_lshl_add_u64 v[130:131], s[16:17], 0, v[132:133]
	v_lshl_add_u64 v[130:131], s[50:51], 3, v[130:131]
	global_store_dwordx2 v[130:131], v[128:129], off

.LBB0_632:
	v_pk_add_f32 v[124:125], v[124:125], v[44:45]
	v_pk_add_f32 v[120:121], v[120:121], v[40:41]
	v_mul_f32_e32 v132, 0xbdd2d3e7, v124
	v_fmaak_f32 v132, v124, v132, 0xc0135761
	v_mul_f32_e32 v132, v124, v132
	v_exp_f32_e32 v132, v132
	v_pk_add_f32 v[126:127], v[126:127], v[46:47]
	v_pk_add_f32 v[122:123], v[122:123], v[42:43]
	v_pk_add_f32 v[116:117], v[116:117], v[36:37]
	v_add_f32_e32 v132, 1.0, v132
	v_rcp_f32_e32 v132, v132
	v_pk_add_f32 v[112:113], v[112:113], v[32:33]
	v_pk_add_f32 v[118:119], v[118:119], v[38:39]
	v_pk_add_f32 v[114:115], v[114:115], v[34:35]
	v_mul_f32_e32 v124, v124, v132
	v_mul_f32_e32 v132, 0xbdd2d3e7, v120
	v_fmaak_f32 v132, v120, v132, 0xc0135761
	v_mul_f32_e32 v132, v120, v132
	v_exp_f32_e32 v132, v132
	v_add_u32_e32 v128, 16, v172
	v_ashrrev_i32_e32 v129, 31, v128
	s_waitcnt lgkmcnt(0)
	v_lshlrev_b64 v[130:131], 13, v[128:129]
	v_add_f32_e32 v132, 1.0, v132
	v_rcp_f32_e32 v132, v132
	s_andn2_b64 vcc, exec, s[52:53]
	s_mov_b32 s70, 0x8000
	s_movk_i32 s72, 0x1000
	v_mul_f32_e32 v132, v120, v132
	v_mul_f32_e32 v120, 0xbdd2d3e7, v125
	v_fmaak_f32 v120, v125, v120, 0xc0135761
	v_mul_f32_e32 v120, v125, v120
	v_exp_f32_e32 v120, v120
	s_movk_i32 s69, 0x7fff
	s_mov_b32 s71, 0x88888889
	v_add_f32_e32 v120, 1.0, v120
	v_rcp_f32_e32 v120, v120
	s_nop 0
	v_mul_f32_e32 v120, v125, v120
	v_mul_f32_e32 v125, 0xbdd2d3e7, v121
	v_fmaak_f32 v125, v121, v125, 0xc0135761
	v_mul_f32_e32 v125, v121, v125
	v_exp_f32_e32 v125, v125
	v_cvt_pk_bf16_f32 v120, v124, v120
	v_add_f32_e32 v125, 1.0, v125
	v_rcp_f32_e32 v125, v125
	s_nop 0
	v_mul_f32_e32 v125, v121, v125
	v_mul_f32_e32 v121, 0xbdd2d3e7, v126
	v_fmaak_f32 v121, v126, v121, 0xc0135761
	v_mul_f32_e32 v121, v126, v121
	v_exp_f32_e32 v121, v121
	s_nop 0
	v_add_f32_e32 v121, 1.0, v121
	v_rcp_f32_e32 v121, v121
	s_nop 0
	v_mul_f32_e32 v121, v126, v121
	v_mul_f32_e32 v126, 0xbdd2d3e7, v122
	v_fmaak_f32 v126, v122, v126, 0xc0135761
	v_mul_f32_e32 v126, v122, v126
	v_exp_f32_e32 v126, v126
	s_nop 0
	v_add_f32_e32 v126, 1.0, v126
	v_rcp_f32_e32 v126, v126
	s_nop 0
	v_mul_f32_e32 v126, v122, v126
	v_mul_f32_e32 v122, 0xbdd2d3e7, v127
	v_fmaak_f32 v122, v127, v122, 0xc0135761
	v_mul_f32_e32 v122, v127, v122
	v_exp_f32_e32 v122, v122
	s_nop 0
	v_add_f32_e32 v122, 1.0, v122
	v_rcp_f32_e32 v122, v122
	s_nop 0
	v_mul_f32_e32 v122, v127, v122
	v_mul_f32_e32 v127, 0xbdd2d3e7, v123
	v_fmaak_f32 v127, v123, v127, 0xc0135761
	v_mul_f32_e32 v127, v123, v127
	v_exp_f32_e32 v127, v127
	v_cvt_pk_bf16_f32 v121, v121, v122
	v_cvt_pk_bf16_f32 v122, v132, v125
	v_lshl_add_u64 v[124:125], s[10:11], 0, v[130:131]
	v_add_f32_e32 v127, 1.0, v127
	v_rcp_f32_e32 v127, v127
	v_lshl_add_u64 v[124:125], v[170:171], 1, v[124:125]
	v_mul_f32_e32 v123, v123, v127
	v_cvt_pk_bf16_f32 v123, v126, v123
	v_mul_f32_e32 v126, 0xbdd2d3e7, v116
	v_fmaak_f32 v126, v116, v126, 0xc0135761
	v_mul_f32_e32 v126, v116, v126
	v_exp_f32_e32 v126, v126
	global_store_dwordx4 v[124:125], v[120:123], off
	v_add_f32_e32 v126, 1.0, v126
	v_rcp_f32_e32 v126, v126
	s_nop 0
	v_mul_f32_e32 v116, v116, v126
	v_mul_f32_e32 v126, 0xbdd2d3e7, v112
	v_fmaak_f32 v126, v112, v126, 0xc0135761
	v_mul_f32_e32 v126, v112, v126
	v_exp_f32_e32 v126, v126
	s_nop 0
	v_add_f32_e32 v126, 1.0, v126
	v_rcp_f32_e32 v126, v126
	s_nop 0
	v_mul_f32_e32 v126, v112, v126
	v_mul_f32_e32 v112, 0xbdd2d3e7, v117
	v_fmaak_f32 v112, v117, v112, 0xc0135761
	v_mul_f32_e32 v112, v117, v112
	v_exp_f32_e32 v112, v112
	s_nop 0
	v_add_f32_e32 v112, 1.0, v112
	v_rcp_f32_e32 v112, v112
	s_nop 0
	v_mul_f32_e32 v112, v117, v112
	v_mul_f32_e32 v117, 0xbdd2d3e7, v113
	v_fmaak_f32 v117, v113, v117, 0xc0135761
	v_mul_f32_e32 v117, v113, v117
	v_exp_f32_e32 v117, v117
	v_cvt_pk_bf16_f32 v112, v116, v112
	v_cndmask_b32_e64 v116, 0, 1, s[52:53]
	v_cmp_ne_u32_e64 s[40:41], 1, v116
	v_add_f32_e32 v117, 1.0, v117
	v_rcp_f32_e32 v117, v117
	s_nop 0
	v_mul_f32_e32 v117, v113, v117
	v_mul_f32_e32 v113, 0xbdd2d3e7, v118
	v_fmaak_f32 v113, v118, v113, 0xc0135761
	v_mul_f32_e32 v113, v118, v113
	v_exp_f32_e32 v113, v113
	s_nop 0
	v_add_f32_e32 v113, 1.0, v113
	v_rcp_f32_e32 v113, v113
	s_nop 0
	v_mul_f32_e32 v113, v118, v113
	v_mul_f32_e32 v118, 0xbdd2d3e7, v114
	v_fmaak_f32 v118, v114, v118, 0xc0135761
	v_mul_f32_e32 v118, v114, v118
	v_exp_f32_e32 v118, v118
	s_nop 0
	v_add_f32_e32 v118, 1.0, v118
	v_rcp_f32_e32 v118, v118
	s_nop 0
	v_mul_f32_e32 v118, v114, v118
	v_mul_f32_e32 v114, 0xbdd2d3e7, v119
	v_fmaak_f32 v114, v119, v114, 0xc0135761
	v_mul_f32_e32 v114, v119, v114
	v_exp_f32_e32 v114, v114
	s_nop 0
	v_add_f32_e32 v114, 1.0, v114
	v_rcp_f32_e32 v114, v114
	s_nop 0
	v_mul_f32_e32 v114, v119, v114
	v_mul_f32_e32 v119, 0xbdd2d3e7, v115
	v_fmaak_f32 v119, v115, v119, 0xc0135761
	v_mul_f32_e32 v119, v115, v119
	v_exp_f32_e32 v119, v119
	v_cvt_pk_bf16_f32 v113, v113, v114
	v_cvt_pk_bf16_f32 v114, v126, v117
	v_add_f32_e32 v119, 1.0, v119
	v_rcp_f32_e32 v119, v119
	s_nop 0
	v_mul_f32_e32 v115, v115, v119
	v_cvt_pk_bf16_f32 v115, v118, v115
	global_store_dwordx4 v[124:125], v[112:115], off offset:256
	s_cbranch_vccnz .LBB0_636
	v_lshlrev_b32_e32 v117, 16, v112
	v_and_b32_e32 v125, 0xffff0000, v112
	v_lshlrev_b32_e32 v116, 16, v120
	v_and_b32_e32 v118, 0xffff0000, v120
	v_lshlrev_b32_e32 v120, 16, v121
	v_and_b32_e32 v124, 0xffff0000, v121
	v_mov_b32_e32 v119, v117
	v_mov_b32_e32 v121, v125
	v_lshlrev_b32_e32 v127, 16, v113
	v_and_b32_e32 v131, 0xffff0000, v113
	v_pk_mul_f32 v[136:137], v[116:117], v[116:117]
	v_pk_mul_f32 v[138:139], v[118:119], v[118:119]
	v_pk_mul_f32 v[140:141], v[120:121], v[120:121]
	v_pk_mul_f32 v[142:143], v[124:125], v[124:125]
	v_pk_add_f32 v[118:119], v[116:117], v[118:119]
	v_pk_add_f32 v[120:121], v[124:125], v[120:121]
	v_lshlrev_b32_e32 v126, 16, v122
	v_and_b32_e32 v112, 0xffff0000, v122
	v_lshlrev_b32_e32 v122, 16, v123
	v_and_b32_e32 v130, 0xffff0000, v123
	v_mov_b32_e32 v113, v127
	v_mov_b32_e32 v123, v131
	v_mov_b32_e32 v119, v137
	v_mov_b32_e32 v121, v143
	v_pk_mul_f32 v[146:147], v[126:127], v[126:127]
	v_pk_mul_f32 v[148:149], v[112:113], v[112:113]
	v_pk_mul_f32 v[152:153], v[130:131], v[130:131]
	v_pk_add_f32 v[118:119], v[118:119], v[120:121]
	v_pk_add_f32 v[112:113], v[126:127], v[112:113]
	v_pk_add_f32 v[120:121], v[130:131], v[122:123]
	v_mov_b32_e32 v113, v147
	v_mov_b32_e32 v121, v153
	v_pk_add_f32 v[112:113], v[112:113], v[120:121]
	v_pk_mov_b32 v[116:117], v[116:117], v[136:137] op_sel:[1,0]
	v_pk_add_f32 v[112:113], v[118:119], v[112:113]
	v_pk_mov_b32 v[118:119], v[124:125], v[138:139] op_sel:[1,0]
	v_pk_mov_b32 v[120:121], v[130:131], v[142:143] op_sel:[1,0]
	v_pk_add_f32 v[116:117], v[116:117], v[118:119]
	v_pk_mov_b32 v[118:119], v[126:127], v[140:141] op_sel:[1,0]
	v_lshlrev_b32_e32 v133, 16, v115
	v_lshlrev_b32_e32 v132, 16, v114
	v_and_b32_e32 v115, 0xffff0000, v115
	v_and_b32_e32 v114, 0xffff0000, v114
	v_pk_add_f32 v[118:119], v[118:119], v[120:121]
	v_pk_mul_f32 v[134:135], v[114:115], v[114:115]
	v_pk_mul_f32 v[150:151], v[122:123], v[122:123]
	v_pk_add_f32 v[116:117], v[116:117], v[118:119]
	v_mov_b32_e32 v118, v132
	v_mov_b32_e32 v119, v146
	v_mov_b32_e32 v120, v114
	v_mov_b32_e32 v121, v148
	v_pk_fma_f32 v[134:135], v[132:133], v[132:133], v[134:135]
	v_pk_add_f32 v[118:119], v[118:119], v[120:121]
	v_pk_mov_b32 v[120:121], v[132:133], v[150:151] op_sel:[1,0]
	v_pk_mov_b32 v[114:115], v[114:115], v[152:153] op_sel:[1,0]
	v_pk_add_f32 v[134:135], v[134:135], v[134:135] op_sel_hi:[0,1]
	v_pk_add_f32 v[114:115], v[120:121], v[114:115]
	v_mov_b32_e32 v134, v145
	v_pk_add_f32 v[114:115], v[118:119], v[114:115]
	v_pk_add_f32 v[112:113], v[112:113], v[134:135]
	v_pk_add_f32 v[114:115], v[116:117], v[114:115]
	s_nop 0
	v_pk_add_f32 v[112:113], v[114:115], v[112:113]
	ds_bpermute_b32 v114, v180, v112
	ds_bpermute_b32 v115, v180, v113
	s_waitcnt lgkmcnt(0)
	v_pk_add_f32 v[112:113], v[112:113], v[114:115]
	ds_bpermute_b32 v114, v179, v112
	ds_bpermute_b32 v115, v179, v113
	s_and_saveexec_b64 s[4:5], s[38:39]
	s_cbranch_execz .LBB0_635
	v_lshlrev_b64 v[116:117], 8, v[128:129]
	s_waitcnt lgkmcnt(0)
	v_pk_add_f32 v[112:113], v[112:113], v[114:115]
	v_lshl_add_u64 v[114:115], s[16:17], 0, v[116:117]
	v_lshl_add_u64 v[114:115], s[50:51], 3, v[114:115]
	global_store_dwordx2 v[114:115], v[112:113], off

.LBB0_636:
	v_pk_add_f32 v[108:109], v[108:109], v[44:45]
	v_pk_add_f32 v[104:105], v[104:105], v[40:41]
	v_mul_f32_e32 v116, 0xbdd2d3e7, v108
	v_fmaak_f32 v116, v108, v116, 0xc0135761
	v_mul_f32_e32 v116, v108, v116
	v_exp_f32_e32 v116, v116
	v_pk_add_f32 v[110:111], v[110:111], v[46:47]
	v_pk_add_f32 v[106:107], v[106:107], v[42:43]
	v_pk_add_f32 v[100:101], v[100:101], v[36:37]
	v_add_f32_e32 v116, 1.0, v116
	v_rcp_f32_e32 v116, v116
	v_pk_add_f32 v[96:97], v[96:97], v[32:33]
	v_pk_add_f32 v[102:103], v[102:103], v[38:39]
	v_pk_add_f32 v[98:99], v[98:99], v[34:35]
	v_mul_f32_e32 v108, v108, v116
	v_mul_f32_e32 v116, 0xbdd2d3e7, v104
	v_fmaak_f32 v116, v104, v116, 0xc0135761
	v_mul_f32_e32 v116, v104, v116
	v_exp_f32_e32 v116, v116
	v_add_u32_e32 v112, 32, v172
	v_ashrrev_i32_e32 v113, 31, v112
	s_waitcnt lgkmcnt(0)
	v_lshlrev_b64 v[114:115], 13, v[112:113]
	v_add_f32_e32 v116, 1.0, v116
	v_rcp_f32_e32 v116, v116
	s_and_b64 vcc, exec, s[40:41]
	v_mul_f32_e32 v116, v104, v116
	v_mul_f32_e32 v104, 0xbdd2d3e7, v109
	v_fmaak_f32 v104, v109, v104, 0xc0135761
	v_mul_f32_e32 v104, v109, v104
	v_exp_f32_e32 v104, v104
	s_nop 0
	v_add_f32_e32 v104, 1.0, v104
	v_rcp_f32_e32 v104, v104
	s_nop 0
	v_mul_f32_e32 v104, v109, v104
	v_mul_f32_e32 v109, 0xbdd2d3e7, v105
	v_fmaak_f32 v109, v105, v109, 0xc0135761
	v_mul_f32_e32 v109, v105, v109
	v_exp_f32_e32 v109, v109
	v_cvt_pk_bf16_f32 v104, v108, v104
	v_add_f32_e32 v109, 1.0, v109
	v_rcp_f32_e32 v109, v109
	s_nop 0
	v_mul_f32_e32 v109, v105, v109
	v_mul_f32_e32 v105, 0xbdd2d3e7, v110
	v_fmaak_f32 v105, v110, v105, 0xc0135761
	v_mul_f32_e32 v105, v110, v105
	v_exp_f32_e32 v105, v105
	s_nop 0
	v_add_f32_e32 v105, 1.0, v105
	v_rcp_f32_e32 v105, v105
	s_nop 0
	v_mul_f32_e32 v105, v110, v105
	v_mul_f32_e32 v110, 0xbdd2d3e7, v106
	v_fmaak_f32 v110, v106, v110, 0xc0135761
	v_mul_f32_e32 v110, v106, v110
	v_exp_f32_e32 v110, v110
	s_nop 0
	v_add_f32_e32 v110, 1.0, v110
	v_rcp_f32_e32 v110, v110
	s_nop 0
	v_mul_f32_e32 v110, v106, v110
	v_mul_f32_e32 v106, 0xbdd2d3e7, v111
	v_fmaak_f32 v106, v111, v106, 0xc0135761
	v_mul_f32_e32 v106, v111, v106
	v_exp_f32_e32 v106, v106
	s_nop 0
	v_add_f32_e32 v106, 1.0, v106
	v_rcp_f32_e32 v106, v106
	s_nop 0
	v_mul_f32_e32 v106, v111, v106
	v_mul_f32_e32 v111, 0xbdd2d3e7, v107
	v_fmaak_f32 v111, v107, v111, 0xc0135761
	v_mul_f32_e32 v111, v107, v111
	v_exp_f32_e32 v111, v111
	v_cvt_pk_bf16_f32 v105, v105, v106
	v_cvt_pk_bf16_f32 v106, v116, v109
	v_lshl_add_u64 v[108:109], s[10:11], 0, v[114:115]
	v_add_f32_e32 v111, 1.0, v111
	v_rcp_f32_e32 v111, v111
	v_lshl_add_u64 v[108:109], v[170:171], 1, v[108:109]
	v_mul_f32_e32 v107, v107, v111
	v_cvt_pk_bf16_f32 v107, v110, v107
	v_mul_f32_e32 v110, 0xbdd2d3e7, v100
	v_fmaak_f32 v110, v100, v110, 0xc0135761
	v_mul_f32_e32 v110, v100, v110
	v_exp_f32_e32 v110, v110
	global_store_dwordx4 v[108:109], v[104:107], off
	v_add_f32_e32 v110, 1.0, v110
	v_rcp_f32_e32 v110, v110
	s_nop 0
	v_mul_f32_e32 v100, v100, v110
	v_mul_f32_e32 v110, 0xbdd2d3e7, v96
	v_fmaak_f32 v110, v96, v110, 0xc0135761
	v_mul_f32_e32 v110, v96, v110
	v_exp_f32_e32 v110, v110
	s_nop 0
	v_add_f32_e32 v110, 1.0, v110
	v_rcp_f32_e32 v110, v110
	s_nop 0
	v_mul_f32_e32 v110, v96, v110
	v_mul_f32_e32 v96, 0xbdd2d3e7, v101
	v_fmaak_f32 v96, v101, v96, 0xc0135761
	v_mul_f32_e32 v96, v101, v96
	v_exp_f32_e32 v96, v96
	s_nop 0
	v_add_f32_e32 v96, 1.0, v96
	v_rcp_f32_e32 v96, v96
	s_nop 0
	v_mul_f32_e32 v96, v101, v96
	v_mul_f32_e32 v101, 0xbdd2d3e7, v97
	v_fmaak_f32 v101, v97, v101, 0xc0135761
	v_mul_f32_e32 v101, v97, v101
	v_exp_f32_e32 v101, v101
	v_cvt_pk_bf16_f32 v96, v100, v96
	v_add_f32_e32 v101, 1.0, v101
	v_rcp_f32_e32 v101, v101
	s_nop 0
	v_mul_f32_e32 v101, v97, v101
	v_mul_f32_e32 v97, 0xbdd2d3e7, v102
	v_fmaak_f32 v97, v102, v97, 0xc0135761
	v_mul_f32_e32 v97, v102, v97
	v_exp_f32_e32 v97, v97
	s_nop 0
	v_add_f32_e32 v97, 1.0, v97
	v_rcp_f32_e32 v97, v97
	s_nop 0
	v_mul_f32_e32 v97, v102, v97
	v_mul_f32_e32 v102, 0xbdd2d3e7, v98
	v_fmaak_f32 v102, v98, v102, 0xc0135761
	v_mul_f32_e32 v102, v98, v102
	v_exp_f32_e32 v102, v102
	s_nop 0
	v_add_f32_e32 v102, 1.0, v102
	v_rcp_f32_e32 v102, v102
	s_nop 0
	v_mul_f32_e32 v102, v98, v102
	v_mul_f32_e32 v98, 0xbdd2d3e7, v103
	v_fmaak_f32 v98, v103, v98, 0xc0135761
	v_mul_f32_e32 v98, v103, v98
	v_exp_f32_e32 v98, v98
	s_nop 0
	v_add_f32_e32 v98, 1.0, v98
	v_rcp_f32_e32 v98, v98
	s_nop 0
	v_mul_f32_e32 v98, v103, v98
	v_mul_f32_e32 v103, 0xbdd2d3e7, v99
	v_fmaak_f32 v103, v99, v103, 0xc0135761
	v_mul_f32_e32 v103, v99, v103
	v_exp_f32_e32 v103, v103
	v_cvt_pk_bf16_f32 v97, v97, v98
	v_cvt_pk_bf16_f32 v98, v110, v101
	v_add_f32_e32 v103, 1.0, v103
	v_rcp_f32_e32 v103, v103
	s_nop 0
	v_mul_f32_e32 v99, v99, v103
	v_cvt_pk_bf16_f32 v99, v102, v99
	global_store_dwordx4 v[108:109], v[96:99], off offset:256
	s_cbranch_vccnz .LBB0_640
	v_lshlrev_b32_e32 v101, 16, v96
	v_and_b32_e32 v109, 0xffff0000, v96
	v_lshlrev_b32_e32 v100, 16, v104
	v_and_b32_e32 v102, 0xffff0000, v104
	v_lshlrev_b32_e32 v104, 16, v105
	v_and_b32_e32 v108, 0xffff0000, v105
	v_mov_b32_e32 v103, v101
	v_mov_b32_e32 v105, v109
	v_lshlrev_b32_e32 v111, 16, v97
	v_and_b32_e32 v115, 0xffff0000, v97
	v_pk_mul_f32 v[120:121], v[100:101], v[100:101]
	v_pk_mul_f32 v[122:123], v[102:103], v[102:103]
	v_pk_mul_f32 v[124:125], v[104:105], v[104:105]
	v_pk_mul_f32 v[126:127], v[108:109], v[108:109]
	v_pk_add_f32 v[102:103], v[100:101], v[102:103]
	v_pk_add_f32 v[104:105], v[108:109], v[104:105]
	v_lshlrev_b32_e32 v110, 16, v106
	v_and_b32_e32 v96, 0xffff0000, v106
	v_lshlrev_b32_e32 v106, 16, v107
	v_and_b32_e32 v114, 0xffff0000, v107
	v_mov_b32_e32 v97, v111
	v_mov_b32_e32 v107, v115
	v_mov_b32_e32 v103, v121
	v_mov_b32_e32 v105, v127
	v_pk_mul_f32 v[128:129], v[110:111], v[110:111]
	v_pk_mul_f32 v[130:131], v[96:97], v[96:97]
	v_pk_mul_f32 v[134:135], v[114:115], v[114:115]
	v_pk_add_f32 v[102:103], v[102:103], v[104:105]
	v_pk_add_f32 v[96:97], v[110:111], v[96:97]
	v_pk_add_f32 v[104:105], v[114:115], v[106:107]
	v_mov_b32_e32 v97, v129
	v_mov_b32_e32 v105, v135
	v_pk_add_f32 v[96:97], v[96:97], v[104:105]
	v_pk_mov_b32 v[100:101], v[100:101], v[120:121] op_sel:[1,0]
	v_pk_add_f32 v[96:97], v[102:103], v[96:97]
	v_pk_mov_b32 v[102:103], v[108:109], v[122:123] op_sel:[1,0]
	v_pk_mov_b32 v[104:105], v[114:115], v[126:127] op_sel:[1,0]
	v_pk_add_f32 v[100:101], v[100:101], v[102:103]
	v_pk_mov_b32 v[102:103], v[110:111], v[124:125] op_sel:[1,0]
	v_lshlrev_b32_e32 v117, 16, v99
	v_lshlrev_b32_e32 v116, 16, v98
	v_and_b32_e32 v99, 0xffff0000, v99
	v_and_b32_e32 v98, 0xffff0000, v98
	v_pk_add_f32 v[102:103], v[102:103], v[104:105]
	v_pk_mul_f32 v[118:119], v[98:99], v[98:99]
	v_pk_mul_f32 v[132:133], v[106:107], v[106:107]
	v_pk_add_f32 v[100:101], v[100:101], v[102:103]
	v_mov_b32_e32 v102, v116
	v_mov_b32_e32 v103, v128
	v_mov_b32_e32 v104, v98
	v_mov_b32_e32 v105, v130
	v_pk_fma_f32 v[118:119], v[116:117], v[116:117], v[118:119]
	v_pk_add_f32 v[102:103], v[102:103], v[104:105]
	v_pk_mov_b32 v[104:105], v[116:117], v[132:133] op_sel:[1,0]
	v_pk_mov_b32 v[98:99], v[98:99], v[134:135] op_sel:[1,0]
	v_pk_add_f32 v[118:119], v[118:119], v[118:119] op_sel_hi:[0,1]
	v_pk_add_f32 v[98:99], v[104:105], v[98:99]
	v_mov_b32_e32 v118, v145
	v_pk_add_f32 v[98:99], v[102:103], v[98:99]
	v_pk_add_f32 v[96:97], v[96:97], v[118:119]
	v_pk_add_f32 v[98:99], v[100:101], v[98:99]
	s_nop 0
	v_pk_add_f32 v[96:97], v[98:99], v[96:97]
	ds_bpermute_b32 v98, v180, v96
	ds_bpermute_b32 v99, v180, v97
	s_waitcnt lgkmcnt(0)
	v_pk_add_f32 v[96:97], v[96:97], v[98:99]
	ds_bpermute_b32 v98, v179, v96
	ds_bpermute_b32 v99, v179, v97
	s_and_saveexec_b64 s[4:5], s[38:39]
	s_cbranch_execz .LBB0_639
	v_lshlrev_b64 v[100:101], 8, v[112:113]
	s_waitcnt lgkmcnt(0)
	v_pk_add_f32 v[96:97], v[96:97], v[98:99]
	v_lshl_add_u64 v[98:99], s[16:17], 0, v[100:101]
	v_lshl_add_u64 v[98:99], s[50:51], 3, v[98:99]
	global_store_dwordx2 v[98:99], v[96:97], off

.LBB0_640:
	v_pk_add_f32 v[92:93], v[92:93], v[44:45]
	v_pk_add_f32 v[88:89], v[88:89], v[40:41]
	v_mul_f32_e32 v100, 0xbdd2d3e7, v92
	v_fmaak_f32 v100, v92, v100, 0xc0135761
	v_mul_f32_e32 v100, v92, v100
	v_exp_f32_e32 v100, v100
	v_pk_add_f32 v[94:95], v[94:95], v[46:47]
	v_pk_add_f32 v[90:91], v[90:91], v[42:43]
	v_pk_add_f32 v[84:85], v[84:85], v[36:37]
	v_add_f32_e32 v100, 1.0, v100
	v_rcp_f32_e32 v100, v100
	v_pk_add_f32 v[80:81], v[80:81], v[32:33]
	v_pk_add_f32 v[86:87], v[86:87], v[38:39]
	v_pk_add_f32 v[82:83], v[82:83], v[34:35]
	v_mul_f32_e32 v92, v92, v100
	v_mul_f32_e32 v100, 0xbdd2d3e7, v88
	v_fmaak_f32 v100, v88, v100, 0xc0135761
	v_mul_f32_e32 v100, v88, v100
	v_exp_f32_e32 v100, v100
	v_add_u32_e32 v96, 48, v172
	v_ashrrev_i32_e32 v97, 31, v96
	s_waitcnt lgkmcnt(0)
	v_lshlrev_b64 v[98:99], 13, v[96:97]
	v_add_f32_e32 v100, 1.0, v100
	v_rcp_f32_e32 v100, v100
	s_and_b64 vcc, exec, s[40:41]
	v_mul_f32_e32 v100, v88, v100
	v_mul_f32_e32 v88, 0xbdd2d3e7, v93
	v_fmaak_f32 v88, v93, v88, 0xc0135761
	v_mul_f32_e32 v88, v93, v88
	v_exp_f32_e32 v88, v88
	s_nop 0
	v_add_f32_e32 v88, 1.0, v88
	v_rcp_f32_e32 v88, v88
	s_nop 0
	v_mul_f32_e32 v88, v93, v88
	v_mul_f32_e32 v93, 0xbdd2d3e7, v89
	v_fmaak_f32 v93, v89, v93, 0xc0135761
	v_mul_f32_e32 v93, v89, v93
	v_exp_f32_e32 v93, v93
	v_cvt_pk_bf16_f32 v88, v92, v88
	v_add_f32_e32 v93, 1.0, v93
	v_rcp_f32_e32 v93, v93
	s_nop 0
	v_mul_f32_e32 v93, v89, v93
	v_mul_f32_e32 v89, 0xbdd2d3e7, v94
	v_fmaak_f32 v89, v94, v89, 0xc0135761
	v_mul_f32_e32 v89, v94, v89
	v_exp_f32_e32 v89, v89
	s_nop 0
	v_add_f32_e32 v89, 1.0, v89
	v_rcp_f32_e32 v89, v89
	s_nop 0
	v_mul_f32_e32 v89, v94, v89
	v_mul_f32_e32 v94, 0xbdd2d3e7, v90
	v_fmaak_f32 v94, v90, v94, 0xc0135761
	v_mul_f32_e32 v94, v90, v94
	v_exp_f32_e32 v94, v94
	s_nop 0
	v_add_f32_e32 v94, 1.0, v94
	v_rcp_f32_e32 v94, v94
	s_nop 0
	v_mul_f32_e32 v94, v90, v94
	v_mul_f32_e32 v90, 0xbdd2d3e7, v95
	v_fmaak_f32 v90, v95, v90, 0xc0135761
	v_mul_f32_e32 v90, v95, v90
	v_exp_f32_e32 v90, v90
	s_nop 0
	v_add_f32_e32 v90, 1.0, v90
	v_rcp_f32_e32 v90, v90
	s_nop 0
	v_mul_f32_e32 v90, v95, v90
	v_mul_f32_e32 v95, 0xbdd2d3e7, v91
	v_fmaak_f32 v95, v91, v95, 0xc0135761
	v_mul_f32_e32 v95, v91, v95
	v_exp_f32_e32 v95, v95
	v_cvt_pk_bf16_f32 v89, v89, v90
	v_cvt_pk_bf16_f32 v90, v100, v93
	v_lshl_add_u64 v[92:93], s[10:11], 0, v[98:99]
	v_add_f32_e32 v95, 1.0, v95
	v_rcp_f32_e32 v95, v95
	v_lshl_add_u64 v[92:93], v[170:171], 1, v[92:93]
	v_mul_f32_e32 v91, v91, v95
	v_cvt_pk_bf16_f32 v91, v94, v91
	v_mul_f32_e32 v94, 0xbdd2d3e7, v84
	v_fmaak_f32 v94, v84, v94, 0xc0135761
	v_mul_f32_e32 v94, v84, v94
	v_exp_f32_e32 v94, v94
	global_store_dwordx4 v[92:93], v[88:91], off
	v_add_f32_e32 v94, 1.0, v94
	v_rcp_f32_e32 v94, v94
	s_nop 0
	v_mul_f32_e32 v84, v84, v94
	v_mul_f32_e32 v94, 0xbdd2d3e7, v80
	v_fmaak_f32 v94, v80, v94, 0xc0135761
	v_mul_f32_e32 v94, v80, v94
	v_exp_f32_e32 v94, v94
	s_nop 0
	v_add_f32_e32 v94, 1.0, v94
	v_rcp_f32_e32 v94, v94
	s_nop 0
	v_mul_f32_e32 v94, v80, v94
	v_mul_f32_e32 v80, 0xbdd2d3e7, v85
	v_fmaak_f32 v80, v85, v80, 0xc0135761
	v_mul_f32_e32 v80, v85, v80
	v_exp_f32_e32 v80, v80
	s_nop 0
	v_add_f32_e32 v80, 1.0, v80
	v_rcp_f32_e32 v80, v80
	s_nop 0
	v_mul_f32_e32 v80, v85, v80
	v_mul_f32_e32 v85, 0xbdd2d3e7, v81
	v_fmaak_f32 v85, v81, v85, 0xc0135761
	v_mul_f32_e32 v85, v81, v85
	v_exp_f32_e32 v85, v85
	v_cvt_pk_bf16_f32 v80, v84, v80
	v_add_f32_e32 v85, 1.0, v85
	v_rcp_f32_e32 v85, v85
	s_nop 0
	v_mul_f32_e32 v85, v81, v85
	v_mul_f32_e32 v81, 0xbdd2d3e7, v86
	v_fmaak_f32 v81, v86, v81, 0xc0135761
	v_mul_f32_e32 v81, v86, v81
	v_exp_f32_e32 v81, v81
	s_nop 0
	v_add_f32_e32 v81, 1.0, v81
	v_rcp_f32_e32 v81, v81
	s_nop 0
	v_mul_f32_e32 v81, v86, v81
	v_mul_f32_e32 v86, 0xbdd2d3e7, v82
	v_fmaak_f32 v86, v82, v86, 0xc0135761
	v_mul_f32_e32 v86, v82, v86
	v_exp_f32_e32 v86, v86
	s_nop 0
	v_add_f32_e32 v86, 1.0, v86
	v_rcp_f32_e32 v86, v86
	s_nop 0
	v_mul_f32_e32 v86, v82, v86
	v_mul_f32_e32 v82, 0xbdd2d3e7, v87
	v_fmaak_f32 v82, v87, v82, 0xc0135761
	v_mul_f32_e32 v82, v87, v82
	v_exp_f32_e32 v82, v82
	s_nop 0
	v_add_f32_e32 v82, 1.0, v82
	v_rcp_f32_e32 v82, v82
	s_nop 0
	v_mul_f32_e32 v82, v87, v82
	v_mul_f32_e32 v87, 0xbdd2d3e7, v83
	v_fmaak_f32 v87, v83, v87, 0xc0135761
	v_mul_f32_e32 v87, v83, v87
	v_exp_f32_e32 v87, v87
	v_cvt_pk_bf16_f32 v81, v81, v82
	v_cvt_pk_bf16_f32 v82, v94, v85
	v_add_f32_e32 v87, 1.0, v87
	v_rcp_f32_e32 v87, v87
	s_nop 0
	v_mul_f32_e32 v83, v83, v87
	v_cvt_pk_bf16_f32 v83, v86, v83
	global_store_dwordx4 v[92:93], v[80:83], off offset:256
	s_cbranch_vccnz .LBB0_644
	v_lshlrev_b32_e32 v85, 16, v80
	v_and_b32_e32 v93, 0xffff0000, v80
	v_lshlrev_b32_e32 v84, 16, v88
	v_and_b32_e32 v86, 0xffff0000, v88
	v_lshlrev_b32_e32 v88, 16, v89
	v_and_b32_e32 v92, 0xffff0000, v89
	v_mov_b32_e32 v87, v85
	v_mov_b32_e32 v89, v93
	v_lshlrev_b32_e32 v95, 16, v81
	v_and_b32_e32 v99, 0xffff0000, v81
	v_pk_mul_f32 v[104:105], v[84:85], v[84:85]
	v_pk_mul_f32 v[106:107], v[86:87], v[86:87]
	v_pk_mul_f32 v[108:109], v[88:89], v[88:89]
	v_pk_mul_f32 v[110:111], v[92:93], v[92:93]
	v_pk_add_f32 v[86:87], v[84:85], v[86:87]
	v_pk_add_f32 v[88:89], v[92:93], v[88:89]
	v_lshlrev_b32_e32 v94, 16, v90
	v_and_b32_e32 v80, 0xffff0000, v90
	v_lshlrev_b32_e32 v90, 16, v91
	v_and_b32_e32 v98, 0xffff0000, v91
	v_mov_b32_e32 v81, v95
	v_mov_b32_e32 v91, v99
	v_mov_b32_e32 v87, v105
	v_mov_b32_e32 v89, v111
	v_pk_mul_f32 v[112:113], v[94:95], v[94:95]
	v_pk_mul_f32 v[114:115], v[80:81], v[80:81]
	v_pk_mul_f32 v[118:119], v[98:99], v[98:99]
	v_pk_add_f32 v[86:87], v[86:87], v[88:89]
	v_pk_add_f32 v[80:81], v[94:95], v[80:81]
	v_pk_add_f32 v[88:89], v[98:99], v[90:91]
	v_mov_b32_e32 v81, v113
	v_mov_b32_e32 v89, v119
	v_pk_add_f32 v[80:81], v[80:81], v[88:89]
	v_pk_mov_b32 v[84:85], v[84:85], v[104:105] op_sel:[1,0]
	v_pk_add_f32 v[80:81], v[86:87], v[80:81]
	v_pk_mov_b32 v[86:87], v[92:93], v[106:107] op_sel:[1,0]
	v_pk_mov_b32 v[88:89], v[98:99], v[110:111] op_sel:[1,0]
	v_pk_add_f32 v[84:85], v[84:85], v[86:87]
	v_pk_mov_b32 v[86:87], v[94:95], v[108:109] op_sel:[1,0]
	v_lshlrev_b32_e32 v101, 16, v83
	v_lshlrev_b32_e32 v100, 16, v82
	v_and_b32_e32 v83, 0xffff0000, v83
	v_and_b32_e32 v82, 0xffff0000, v82
	v_pk_add_f32 v[86:87], v[86:87], v[88:89]
	v_pk_mul_f32 v[102:103], v[82:83], v[82:83]
	v_pk_mul_f32 v[116:117], v[90:91], v[90:91]
	v_pk_add_f32 v[84:85], v[84:85], v[86:87]
	v_mov_b32_e32 v86, v100
	v_mov_b32_e32 v87, v112
	v_mov_b32_e32 v88, v82
	v_mov_b32_e32 v89, v114
	v_pk_fma_f32 v[102:103], v[100:101], v[100:101], v[102:103]
	v_pk_add_f32 v[86:87], v[86:87], v[88:89]
	v_pk_mov_b32 v[88:89], v[100:101], v[116:117] op_sel:[1,0]
	v_pk_mov_b32 v[82:83], v[82:83], v[118:119] op_sel:[1,0]
	v_pk_add_f32 v[102:103], v[102:103], v[102:103] op_sel_hi:[0,1]
	v_pk_add_f32 v[82:83], v[88:89], v[82:83]
	v_mov_b32_e32 v102, v145
	v_pk_add_f32 v[82:83], v[86:87], v[82:83]
	v_pk_add_f32 v[80:81], v[80:81], v[102:103]
	v_pk_add_f32 v[82:83], v[84:85], v[82:83]
	s_nop 0
	v_pk_add_f32 v[80:81], v[82:83], v[80:81]
	ds_bpermute_b32 v82, v180, v80
	ds_bpermute_b32 v83, v180, v81
	s_waitcnt lgkmcnt(0)
	v_pk_add_f32 v[80:81], v[80:81], v[82:83]
	ds_bpermute_b32 v82, v179, v80
	ds_bpermute_b32 v83, v179, v81
	s_and_saveexec_b64 s[4:5], s[38:39]
	s_cbranch_execz .LBB0_643
	v_lshlrev_b64 v[84:85], 8, v[96:97]
	s_waitcnt lgkmcnt(0)
	v_pk_add_f32 v[80:81], v[80:81], v[82:83]
	v_lshl_add_u64 v[82:83], s[16:17], 0, v[84:85]
	v_lshl_add_u64 v[82:83], s[50:51], 3, v[82:83]
	global_store_dwordx2 v[82:83], v[80:81], off

.LBB0_644:
	v_pk_add_f32 v[76:77], v[76:77], v[44:45]
	v_pk_add_f32 v[72:73], v[72:73], v[40:41]
	v_mul_f32_e32 v84, 0xbdd2d3e7, v76
	v_fmaak_f32 v84, v76, v84, 0xc0135761
	v_mul_f32_e32 v84, v76, v84
	v_exp_f32_e32 v84, v84
	v_pk_add_f32 v[78:79], v[78:79], v[46:47]
	v_pk_add_f32 v[74:75], v[74:75], v[42:43]
	v_pk_add_f32 v[68:69], v[68:69], v[36:37]
	v_add_f32_e32 v84, 1.0, v84
	v_rcp_f32_e32 v84, v84
	v_pk_add_f32 v[64:65], v[64:65], v[32:33]
	v_pk_add_f32 v[70:71], v[70:71], v[38:39]
	v_pk_add_f32 v[66:67], v[66:67], v[34:35]
	v_mul_f32_e32 v76, v76, v84
	v_mul_f32_e32 v84, 0xbdd2d3e7, v72
	v_fmaak_f32 v84, v72, v84, 0xc0135761
	v_mul_f32_e32 v84, v72, v84
	v_exp_f32_e32 v84, v84
	v_add_u32_e32 v80, 0x80, v172
	v_ashrrev_i32_e32 v81, 31, v80
	s_waitcnt lgkmcnt(0)
	v_lshlrev_b64 v[82:83], 13, v[80:81]
	v_add_f32_e32 v84, 1.0, v84
	v_rcp_f32_e32 v84, v84
	s_and_b64 vcc, exec, s[40:41]
	v_mul_f32_e32 v84, v72, v84
	v_mul_f32_e32 v72, 0xbdd2d3e7, v77
	v_fmaak_f32 v72, v77, v72, 0xc0135761
	v_mul_f32_e32 v72, v77, v72
	v_exp_f32_e32 v72, v72
	s_nop 0
	v_add_f32_e32 v72, 1.0, v72
	v_rcp_f32_e32 v72, v72
	s_nop 0
	v_mul_f32_e32 v72, v77, v72
	v_mul_f32_e32 v77, 0xbdd2d3e7, v73
	v_fmaak_f32 v77, v73, v77, 0xc0135761
	v_mul_f32_e32 v77, v73, v77
	v_exp_f32_e32 v77, v77
	v_cvt_pk_bf16_f32 v72, v76, v72
	v_add_f32_e32 v77, 1.0, v77
	v_rcp_f32_e32 v77, v77
	s_nop 0
	v_mul_f32_e32 v77, v73, v77
	v_mul_f32_e32 v73, 0xbdd2d3e7, v78
	v_fmaak_f32 v73, v78, v73, 0xc0135761
	v_mul_f32_e32 v73, v78, v73
	v_exp_f32_e32 v73, v73
	s_nop 0
	v_add_f32_e32 v73, 1.0, v73
	v_rcp_f32_e32 v73, v73
	s_nop 0
	v_mul_f32_e32 v73, v78, v73
	v_mul_f32_e32 v78, 0xbdd2d3e7, v74
	v_fmaak_f32 v78, v74, v78, 0xc0135761
	v_mul_f32_e32 v78, v74, v78
	v_exp_f32_e32 v78, v78
	s_nop 0
	v_add_f32_e32 v78, 1.0, v78
	v_rcp_f32_e32 v78, v78
	s_nop 0
	v_mul_f32_e32 v78, v74, v78
	v_mul_f32_e32 v74, 0xbdd2d3e7, v79
	v_fmaak_f32 v74, v79, v74, 0xc0135761
	v_mul_f32_e32 v74, v79, v74
	v_exp_f32_e32 v74, v74
	s_nop 0
	v_add_f32_e32 v74, 1.0, v74
	v_rcp_f32_e32 v74, v74
	s_nop 0
	v_mul_f32_e32 v74, v79, v74
	v_mul_f32_e32 v79, 0xbdd2d3e7, v75
	v_fmaak_f32 v79, v75, v79, 0xc0135761
	v_mul_f32_e32 v79, v75, v79
	v_exp_f32_e32 v79, v79
	v_cvt_pk_bf16_f32 v73, v73, v74
	v_cvt_pk_bf16_f32 v74, v84, v77
	v_lshl_add_u64 v[76:77], s[10:11], 0, v[82:83]
	v_add_f32_e32 v79, 1.0, v79
	v_rcp_f32_e32 v79, v79
	v_lshl_add_u64 v[76:77], v[170:171], 1, v[76:77]
	v_mul_f32_e32 v75, v75, v79
	v_cvt_pk_bf16_f32 v75, v78, v75
	v_mul_f32_e32 v78, 0xbdd2d3e7, v68
	v_fmaak_f32 v78, v68, v78, 0xc0135761
	v_mul_f32_e32 v78, v68, v78
	v_exp_f32_e32 v78, v78
	global_store_dwordx4 v[76:77], v[72:75], off
	v_add_f32_e32 v78, 1.0, v78
	v_rcp_f32_e32 v78, v78
	s_nop 0
	v_mul_f32_e32 v68, v68, v78
	v_mul_f32_e32 v78, 0xbdd2d3e7, v64
	v_fmaak_f32 v78, v64, v78, 0xc0135761
	v_mul_f32_e32 v78, v64, v78
	v_exp_f32_e32 v78, v78
	s_nop 0
	v_add_f32_e32 v78, 1.0, v78
	v_rcp_f32_e32 v78, v78
	s_nop 0
	v_mul_f32_e32 v78, v64, v78
	v_mul_f32_e32 v64, 0xbdd2d3e7, v69
	v_fmaak_f32 v64, v69, v64, 0xc0135761
	v_mul_f32_e32 v64, v69, v64
	v_exp_f32_e32 v64, v64
	s_nop 0
	v_add_f32_e32 v64, 1.0, v64
	v_rcp_f32_e32 v64, v64
	s_nop 0
	v_mul_f32_e32 v64, v69, v64
	v_mul_f32_e32 v69, 0xbdd2d3e7, v65
	v_fmaak_f32 v69, v65, v69, 0xc0135761
	v_mul_f32_e32 v69, v65, v69
	v_exp_f32_e32 v69, v69
	v_cvt_pk_bf16_f32 v64, v68, v64
	v_add_f32_e32 v69, 1.0, v69
	v_rcp_f32_e32 v69, v69
	s_nop 0
	v_mul_f32_e32 v69, v65, v69
	v_mul_f32_e32 v65, 0xbdd2d3e7, v70
	v_fmaak_f32 v65, v70, v65, 0xc0135761
	v_mul_f32_e32 v65, v70, v65
	v_exp_f32_e32 v65, v65
	s_nop 0
	v_add_f32_e32 v65, 1.0, v65
	v_rcp_f32_e32 v65, v65
	s_nop 0
	v_mul_f32_e32 v65, v70, v65
	v_mul_f32_e32 v70, 0xbdd2d3e7, v66
	v_fmaak_f32 v70, v66, v70, 0xc0135761
	v_mul_f32_e32 v70, v66, v70
	v_exp_f32_e32 v70, v70
	s_nop 0
	v_add_f32_e32 v70, 1.0, v70
	v_rcp_f32_e32 v70, v70
	s_nop 0
	v_mul_f32_e32 v70, v66, v70
	v_mul_f32_e32 v66, 0xbdd2d3e7, v71
	v_fmaak_f32 v66, v71, v66, 0xc0135761
	v_mul_f32_e32 v66, v71, v66
	v_exp_f32_e32 v66, v66
	s_nop 0
	v_add_f32_e32 v66, 1.0, v66
	v_rcp_f32_e32 v66, v66
	s_nop 0
	v_mul_f32_e32 v66, v71, v66
	v_mul_f32_e32 v71, 0xbdd2d3e7, v67
	v_fmaak_f32 v71, v67, v71, 0xc0135761
	v_mul_f32_e32 v71, v67, v71
	v_exp_f32_e32 v71, v71
	v_cvt_pk_bf16_f32 v65, v65, v66
	v_cvt_pk_bf16_f32 v66, v78, v69
	v_add_f32_e32 v71, 1.0, v71
	v_rcp_f32_e32 v71, v71
	s_nop 0
	v_mul_f32_e32 v67, v67, v71
	v_cvt_pk_bf16_f32 v67, v70, v67
	global_store_dwordx4 v[76:77], v[64:67], off offset:256
	s_cbranch_vccnz .LBB0_648
	v_lshlrev_b32_e32 v69, 16, v64
	v_and_b32_e32 v77, 0xffff0000, v64
	v_lshlrev_b32_e32 v68, 16, v72
	v_and_b32_e32 v70, 0xffff0000, v72
	v_lshlrev_b32_e32 v72, 16, v73
	v_and_b32_e32 v76, 0xffff0000, v73
	v_mov_b32_e32 v71, v69
	v_mov_b32_e32 v73, v77
	v_lshlrev_b32_e32 v79, 16, v65
	v_and_b32_e32 v83, 0xffff0000, v65
	v_pk_mul_f32 v[88:89], v[68:69], v[68:69]
	v_pk_mul_f32 v[90:91], v[70:71], v[70:71]
	v_pk_mul_f32 v[92:93], v[72:73], v[72:73]
	v_pk_mul_f32 v[94:95], v[76:77], v[76:77]
	v_pk_add_f32 v[70:71], v[68:69], v[70:71]
	v_pk_add_f32 v[72:73], v[76:77], v[72:73]
	v_lshlrev_b32_e32 v78, 16, v74
	v_and_b32_e32 v64, 0xffff0000, v74
	v_lshlrev_b32_e32 v74, 16, v75
	v_and_b32_e32 v82, 0xffff0000, v75
	v_mov_b32_e32 v65, v79
	v_mov_b32_e32 v75, v83
	v_mov_b32_e32 v71, v89
	v_mov_b32_e32 v73, v95
	v_pk_mul_f32 v[96:97], v[78:79], v[78:79]
	v_pk_mul_f32 v[98:99], v[64:65], v[64:65]
	v_pk_mul_f32 v[102:103], v[82:83], v[82:83]
	v_pk_add_f32 v[70:71], v[70:71], v[72:73]
	v_pk_add_f32 v[64:65], v[78:79], v[64:65]
	v_pk_add_f32 v[72:73], v[82:83], v[74:75]
	v_mov_b32_e32 v65, v97
	v_mov_b32_e32 v73, v103
	v_pk_add_f32 v[64:65], v[64:65], v[72:73]
	v_pk_mov_b32 v[68:69], v[68:69], v[88:89] op_sel:[1,0]
	v_pk_add_f32 v[64:65], v[70:71], v[64:65]
	v_pk_mov_b32 v[70:71], v[76:77], v[90:91] op_sel:[1,0]
	v_pk_mov_b32 v[72:73], v[82:83], v[94:95] op_sel:[1,0]
	v_pk_add_f32 v[68:69], v[68:69], v[70:71]
	v_pk_mov_b32 v[70:71], v[78:79], v[92:93] op_sel:[1,0]
	v_lshlrev_b32_e32 v85, 16, v67
	v_lshlrev_b32_e32 v84, 16, v66
	v_and_b32_e32 v67, 0xffff0000, v67
	v_and_b32_e32 v66, 0xffff0000, v66
	v_pk_add_f32 v[70:71], v[70:71], v[72:73]
	v_pk_mul_f32 v[86:87], v[66:67], v[66:67]
	v_pk_mul_f32 v[100:101], v[74:75], v[74:75]
	v_pk_add_f32 v[68:69], v[68:69], v[70:71]
	v_mov_b32_e32 v70, v84
	v_mov_b32_e32 v71, v96
	v_mov_b32_e32 v72, v66
	v_mov_b32_e32 v73, v98
	v_pk_fma_f32 v[86:87], v[84:85], v[84:85], v[86:87]
	v_pk_add_f32 v[70:71], v[70:71], v[72:73]
	v_pk_mov_b32 v[72:73], v[84:85], v[100:101] op_sel:[1,0]
	v_pk_mov_b32 v[66:67], v[66:67], v[102:103] op_sel:[1,0]
	v_pk_add_f32 v[86:87], v[86:87], v[86:87] op_sel_hi:[0,1]
	v_pk_add_f32 v[66:67], v[72:73], v[66:67]
	v_mov_b32_e32 v86, v145
	v_pk_add_f32 v[66:67], v[70:71], v[66:67]
	v_pk_add_f32 v[64:65], v[64:65], v[86:87]
	v_pk_add_f32 v[66:67], v[68:69], v[66:67]
	s_nop 0
	v_pk_add_f32 v[64:65], v[66:67], v[64:65]
	ds_bpermute_b32 v66, v180, v64
	ds_bpermute_b32 v67, v180, v65
	s_waitcnt lgkmcnt(0)
	v_pk_add_f32 v[64:65], v[64:65], v[66:67]
	ds_bpermute_b32 v66, v179, v64
	ds_bpermute_b32 v67, v179, v65
	s_and_saveexec_b64 s[4:5], s[38:39]
	s_cbranch_execz .LBB0_647
	v_lshlrev_b64 v[68:69], 8, v[80:81]
	s_waitcnt lgkmcnt(0)
	v_pk_add_f32 v[64:65], v[64:65], v[66:67]
	v_lshl_add_u64 v[66:67], s[16:17], 0, v[68:69]
	v_lshl_add_u64 v[66:67], s[50:51], 3, v[66:67]
	global_store_dwordx2 v[66:67], v[64:65], off

.LBB0_648:
	v_pk_add_f32 v[60:61], v[60:61], v[44:45]
	v_pk_add_f32 v[56:57], v[56:57], v[40:41]
	v_mul_f32_e32 v68, 0xbdd2d3e7, v60
	v_fmaak_f32 v68, v60, v68, 0xc0135761
	v_mul_f32_e32 v68, v60, v68
	v_exp_f32_e32 v68, v68
	v_pk_add_f32 v[62:63], v[62:63], v[46:47]
	v_pk_add_f32 v[58:59], v[58:59], v[42:43]
	v_pk_add_f32 v[52:53], v[52:53], v[36:37]
	v_add_f32_e32 v68, 1.0, v68
	v_rcp_f32_e32 v68, v68
	v_pk_add_f32 v[48:49], v[48:49], v[32:33]
	v_pk_add_f32 v[54:55], v[54:55], v[38:39]
	v_pk_add_f32 v[50:51], v[50:51], v[34:35]
	v_mul_f32_e32 v60, v60, v68
	v_mul_f32_e32 v68, 0xbdd2d3e7, v56
	v_fmaak_f32 v68, v56, v68, 0xc0135761
	v_mul_f32_e32 v68, v56, v68
	v_exp_f32_e32 v68, v68
	v_add_u32_e32 v64, 0x90, v172
	v_ashrrev_i32_e32 v65, 31, v64
	s_waitcnt lgkmcnt(0)
	v_lshlrev_b64 v[66:67], 13, v[64:65]
	v_add_f32_e32 v68, 1.0, v68
	v_rcp_f32_e32 v68, v68
	s_and_b64 vcc, exec, s[40:41]
	v_mul_f32_e32 v68, v56, v68
	v_mul_f32_e32 v56, 0xbdd2d3e7, v61
	v_fmaak_f32 v56, v61, v56, 0xc0135761
	v_mul_f32_e32 v56, v61, v56
	v_exp_f32_e32 v56, v56
	s_nop 0
	v_add_f32_e32 v56, 1.0, v56
	v_rcp_f32_e32 v56, v56
	s_nop 0
	v_mul_f32_e32 v56, v61, v56
	v_mul_f32_e32 v61, 0xbdd2d3e7, v57
	v_fmaak_f32 v61, v57, v61, 0xc0135761
	v_mul_f32_e32 v61, v57, v61
	v_exp_f32_e32 v61, v61
	v_cvt_pk_bf16_f32 v56, v60, v56
	v_add_f32_e32 v61, 1.0, v61
	v_rcp_f32_e32 v61, v61
	s_nop 0
	v_mul_f32_e32 v61, v57, v61
	v_mul_f32_e32 v57, 0xbdd2d3e7, v62
	v_fmaak_f32 v57, v62, v57, 0xc0135761
	v_mul_f32_e32 v57, v62, v57
	v_exp_f32_e32 v57, v57
	s_nop 0
	v_add_f32_e32 v57, 1.0, v57
	v_rcp_f32_e32 v57, v57
	s_nop 0
	v_mul_f32_e32 v57, v62, v57
	v_mul_f32_e32 v62, 0xbdd2d3e7, v58
	v_fmaak_f32 v62, v58, v62, 0xc0135761
	v_mul_f32_e32 v62, v58, v62
	v_exp_f32_e32 v62, v62
	s_nop 0
	v_add_f32_e32 v62, 1.0, v62
	v_rcp_f32_e32 v62, v62
	s_nop 0
	v_mul_f32_e32 v62, v58, v62
	v_mul_f32_e32 v58, 0xbdd2d3e7, v63
	v_fmaak_f32 v58, v63, v58, 0xc0135761
	v_mul_f32_e32 v58, v63, v58
	v_exp_f32_e32 v58, v58
	s_nop 0
	v_add_f32_e32 v58, 1.0, v58
	v_rcp_f32_e32 v58, v58
	s_nop 0
	v_mul_f32_e32 v58, v63, v58
	v_mul_f32_e32 v63, 0xbdd2d3e7, v59
	v_fmaak_f32 v63, v59, v63, 0xc0135761
	v_mul_f32_e32 v63, v59, v63
	v_exp_f32_e32 v63, v63
	v_cvt_pk_bf16_f32 v57, v57, v58
	v_cvt_pk_bf16_f32 v58, v68, v61
	v_lshl_add_u64 v[60:61], s[10:11], 0, v[66:67]
	v_add_f32_e32 v63, 1.0, v63
	v_rcp_f32_e32 v63, v63
	v_lshl_add_u64 v[60:61], v[170:171], 1, v[60:61]
	v_mul_f32_e32 v59, v59, v63
	v_cvt_pk_bf16_f32 v59, v62, v59
	v_mul_f32_e32 v62, 0xbdd2d3e7, v52
	v_fmaak_f32 v62, v52, v62, 0xc0135761
	v_mul_f32_e32 v62, v52, v62
	v_exp_f32_e32 v62, v62
	global_store_dwordx4 v[60:61], v[56:59], off
	v_add_f32_e32 v62, 1.0, v62
	v_rcp_f32_e32 v62, v62
	s_nop 0
	v_mul_f32_e32 v52, v52, v62
	v_mul_f32_e32 v62, 0xbdd2d3e7, v48
	v_fmaak_f32 v62, v48, v62, 0xc0135761
	v_mul_f32_e32 v62, v48, v62
	v_exp_f32_e32 v62, v62
	s_nop 0
	v_add_f32_e32 v62, 1.0, v62
	v_rcp_f32_e32 v62, v62
	s_nop 0
	v_mul_f32_e32 v62, v48, v62
	v_mul_f32_e32 v48, 0xbdd2d3e7, v53
	v_fmaak_f32 v48, v53, v48, 0xc0135761
	v_mul_f32_e32 v48, v53, v48
	v_exp_f32_e32 v48, v48
	s_nop 0
	v_add_f32_e32 v48, 1.0, v48
	v_rcp_f32_e32 v48, v48
	s_nop 0
	v_mul_f32_e32 v48, v53, v48
	v_mul_f32_e32 v53, 0xbdd2d3e7, v49
	v_fmaak_f32 v53, v49, v53, 0xc0135761
	v_mul_f32_e32 v53, v49, v53
	v_exp_f32_e32 v53, v53
	v_cvt_pk_bf16_f32 v48, v52, v48
	v_add_f32_e32 v53, 1.0, v53
	v_rcp_f32_e32 v53, v53
	s_nop 0
	v_mul_f32_e32 v53, v49, v53
	v_mul_f32_e32 v49, 0xbdd2d3e7, v54
	v_fmaak_f32 v49, v54, v49, 0xc0135761
	v_mul_f32_e32 v49, v54, v49
	v_exp_f32_e32 v49, v49
	s_nop 0
	v_add_f32_e32 v49, 1.0, v49
	v_rcp_f32_e32 v49, v49
	s_nop 0
	v_mul_f32_e32 v49, v54, v49
	v_mul_f32_e32 v54, 0xbdd2d3e7, v50
	v_fmaak_f32 v54, v50, v54, 0xc0135761
	v_mul_f32_e32 v54, v50, v54
	v_exp_f32_e32 v54, v54
	s_nop 0
	v_add_f32_e32 v54, 1.0, v54
	v_rcp_f32_e32 v54, v54
	s_nop 0
	v_mul_f32_e32 v54, v50, v54
	v_mul_f32_e32 v50, 0xbdd2d3e7, v55
	v_fmaak_f32 v50, v55, v50, 0xc0135761
	v_mul_f32_e32 v50, v55, v50
	v_exp_f32_e32 v50, v50
	s_nop 0
	v_add_f32_e32 v50, 1.0, v50
	v_rcp_f32_e32 v50, v50
	s_nop 0
	v_mul_f32_e32 v50, v55, v50
	v_mul_f32_e32 v55, 0xbdd2d3e7, v51
	v_fmaak_f32 v55, v51, v55, 0xc0135761
	v_mul_f32_e32 v55, v51, v55
	v_exp_f32_e32 v55, v55
	v_cvt_pk_bf16_f32 v49, v49, v50
	v_cvt_pk_bf16_f32 v50, v62, v53
	v_add_f32_e32 v55, 1.0, v55
	v_rcp_f32_e32 v55, v55
	s_nop 0
	v_mul_f32_e32 v51, v51, v55
	v_cvt_pk_bf16_f32 v51, v54, v51
	global_store_dwordx4 v[60:61], v[48:51], off offset:256
	s_cbranch_vccnz .LBB0_652
	v_lshlrev_b32_e32 v53, 16, v48
	v_and_b32_e32 v61, 0xffff0000, v48
	v_lshlrev_b32_e32 v52, 16, v56
	v_and_b32_e32 v54, 0xffff0000, v56
	v_lshlrev_b32_e32 v56, 16, v57
	v_and_b32_e32 v60, 0xffff0000, v57
	v_mov_b32_e32 v55, v53
	v_mov_b32_e32 v57, v61
	v_lshlrev_b32_e32 v63, 16, v49
	v_and_b32_e32 v67, 0xffff0000, v49
	v_pk_mul_f32 v[72:73], v[52:53], v[52:53]
	v_pk_mul_f32 v[74:75], v[54:55], v[54:55]
	v_pk_mul_f32 v[76:77], v[56:57], v[56:57]
	v_pk_mul_f32 v[78:79], v[60:61], v[60:61]
	v_pk_add_f32 v[54:55], v[52:53], v[54:55]
	v_pk_add_f32 v[56:57], v[60:61], v[56:57]
	v_lshlrev_b32_e32 v62, 16, v58
	v_and_b32_e32 v48, 0xffff0000, v58
	v_lshlrev_b32_e32 v58, 16, v59
	v_and_b32_e32 v66, 0xffff0000, v59
	v_mov_b32_e32 v49, v63
	v_mov_b32_e32 v59, v67
	v_mov_b32_e32 v55, v73
	v_mov_b32_e32 v57, v79
	v_pk_mul_f32 v[80:81], v[62:63], v[62:63]
	v_pk_mul_f32 v[82:83], v[48:49], v[48:49]
	v_pk_mul_f32 v[86:87], v[66:67], v[66:67]
	v_pk_add_f32 v[54:55], v[54:55], v[56:57]
	v_pk_add_f32 v[48:49], v[62:63], v[48:49]
	v_pk_add_f32 v[56:57], v[66:67], v[58:59]
	v_mov_b32_e32 v49, v81
	v_mov_b32_e32 v57, v87
	v_pk_add_f32 v[48:49], v[48:49], v[56:57]
	v_pk_mov_b32 v[52:53], v[52:53], v[72:73] op_sel:[1,0]
	v_pk_add_f32 v[48:49], v[54:55], v[48:49]
	v_pk_mov_b32 v[54:55], v[60:61], v[74:75] op_sel:[1,0]
	v_pk_mov_b32 v[56:57], v[66:67], v[78:79] op_sel:[1,0]
	v_pk_add_f32 v[52:53], v[52:53], v[54:55]
	v_pk_mov_b32 v[54:55], v[62:63], v[76:77] op_sel:[1,0]
	v_lshlrev_b32_e32 v69, 16, v51
	v_lshlrev_b32_e32 v68, 16, v50
	v_and_b32_e32 v51, 0xffff0000, v51
	v_and_b32_e32 v50, 0xffff0000, v50
	v_pk_add_f32 v[54:55], v[54:55], v[56:57]
	v_pk_mul_f32 v[70:71], v[50:51], v[50:51]
	v_pk_mul_f32 v[84:85], v[58:59], v[58:59]
	v_pk_add_f32 v[52:53], v[52:53], v[54:55]
	v_mov_b32_e32 v54, v68
	v_mov_b32_e32 v55, v80
	v_mov_b32_e32 v56, v50
	v_mov_b32_e32 v57, v82
	v_pk_fma_f32 v[70:71], v[68:69], v[68:69], v[70:71]
	v_pk_add_f32 v[54:55], v[54:55], v[56:57]
	v_pk_mov_b32 v[56:57], v[68:69], v[84:85] op_sel:[1,0]
	v_pk_mov_b32 v[50:51], v[50:51], v[86:87] op_sel:[1,0]
	v_pk_add_f32 v[70:71], v[70:71], v[70:71] op_sel_hi:[0,1]
	v_pk_add_f32 v[50:51], v[56:57], v[50:51]
	v_mov_b32_e32 v70, v145
	v_pk_add_f32 v[50:51], v[54:55], v[50:51]
	v_pk_add_f32 v[48:49], v[48:49], v[70:71]
	v_pk_add_f32 v[50:51], v[52:53], v[50:51]
	s_nop 0
	v_pk_add_f32 v[48:49], v[50:51], v[48:49]
	ds_bpermute_b32 v50, v180, v48
	ds_bpermute_b32 v51, v180, v49
	s_waitcnt lgkmcnt(0)
	v_pk_add_f32 v[48:49], v[48:49], v[50:51]
	ds_bpermute_b32 v50, v179, v48
	ds_bpermute_b32 v51, v179, v49
	s_and_saveexec_b64 s[4:5], s[38:39]
	s_cbranch_execz .LBB0_651
	v_lshlrev_b64 v[52:53], 8, v[64:65]
	s_waitcnt lgkmcnt(0)
	v_pk_add_f32 v[48:49], v[48:49], v[50:51]
	v_lshl_add_u64 v[50:51], s[16:17], 0, v[52:53]
	v_lshl_add_u64 v[50:51], s[50:51], 3, v[50:51]
	global_store_dwordx2 v[50:51], v[48:49], off

.LBB0_652:
	v_pk_add_f32 v[28:29], v[28:29], v[44:45]
	v_pk_add_f32 v[24:25], v[24:25], v[40:41]
	v_mul_f32_e32 v52, 0xbdd2d3e7, v28
	v_fmaak_f32 v52, v28, v52, 0xc0135761
	v_mul_f32_e32 v52, v28, v52
	v_exp_f32_e32 v52, v52
	v_pk_add_f32 v[30:31], v[30:31], v[46:47]
	v_pk_add_f32 v[26:27], v[26:27], v[42:43]
	v_pk_add_f32 v[20:21], v[20:21], v[36:37]
	v_add_f32_e32 v52, 1.0, v52
	v_rcp_f32_e32 v52, v52
	v_pk_add_f32 v[16:17], v[16:17], v[32:33]
	v_pk_add_f32 v[22:23], v[22:23], v[38:39]
	v_pk_add_f32 v[18:19], v[18:19], v[34:35]
	v_mul_f32_e32 v28, v28, v52
	v_mul_f32_e32 v52, 0xbdd2d3e7, v24
	v_fmaak_f32 v52, v24, v52, 0xc0135761
	v_mul_f32_e32 v52, v24, v52
	v_exp_f32_e32 v52, v52
	v_add_u32_e32 v48, 0xa0, v172
	v_ashrrev_i32_e32 v49, 31, v48
	s_waitcnt lgkmcnt(0)
	v_lshlrev_b64 v[50:51], 13, v[48:49]
	v_add_f32_e32 v52, 1.0, v52
	v_rcp_f32_e32 v52, v52
	s_and_b64 vcc, exec, s[40:41]
	v_mul_f32_e32 v52, v24, v52
	v_mul_f32_e32 v24, 0xbdd2d3e7, v29
	v_fmaak_f32 v24, v29, v24, 0xc0135761
	v_mul_f32_e32 v24, v29, v24
	v_exp_f32_e32 v24, v24
	s_nop 0
	v_add_f32_e32 v24, 1.0, v24
	v_rcp_f32_e32 v24, v24
	s_nop 0
	v_mul_f32_e32 v24, v29, v24
	v_mul_f32_e32 v29, 0xbdd2d3e7, v25
	v_fmaak_f32 v29, v25, v29, 0xc0135761
	v_mul_f32_e32 v29, v25, v29
	v_exp_f32_e32 v29, v29
	v_cvt_pk_bf16_f32 v24, v28, v24
	v_add_f32_e32 v29, 1.0, v29
	v_rcp_f32_e32 v29, v29
	s_nop 0
	v_mul_f32_e32 v29, v25, v29
	v_mul_f32_e32 v25, 0xbdd2d3e7, v30
	v_fmaak_f32 v25, v30, v25, 0xc0135761
	v_mul_f32_e32 v25, v30, v25
	v_exp_f32_e32 v25, v25
	s_nop 0
	v_add_f32_e32 v25, 1.0, v25
	v_rcp_f32_e32 v25, v25
	s_nop 0
	v_mul_f32_e32 v25, v30, v25
	v_mul_f32_e32 v30, 0xbdd2d3e7, v26
	v_fmaak_f32 v30, v26, v30, 0xc0135761
	v_mul_f32_e32 v30, v26, v30
	v_exp_f32_e32 v30, v30
	s_nop 0
	v_add_f32_e32 v30, 1.0, v30
	v_rcp_f32_e32 v30, v30
	s_nop 0
	v_mul_f32_e32 v30, v26, v30
	v_mul_f32_e32 v26, 0xbdd2d3e7, v31
	v_fmaak_f32 v26, v31, v26, 0xc0135761
	v_mul_f32_e32 v26, v31, v26
	v_exp_f32_e32 v26, v26
	s_nop 0
	v_add_f32_e32 v26, 1.0, v26
	v_rcp_f32_e32 v26, v26
	s_nop 0
	v_mul_f32_e32 v26, v31, v26
	v_mul_f32_e32 v31, 0xbdd2d3e7, v27
	v_fmaak_f32 v31, v27, v31, 0xc0135761
	v_mul_f32_e32 v31, v27, v31
	v_exp_f32_e32 v31, v31
	v_cvt_pk_bf16_f32 v25, v25, v26
	v_cvt_pk_bf16_f32 v26, v52, v29
	v_lshl_add_u64 v[28:29], s[10:11], 0, v[50:51]
	v_add_f32_e32 v31, 1.0, v31
	v_rcp_f32_e32 v31, v31
	v_lshl_add_u64 v[28:29], v[170:171], 1, v[28:29]
	v_mul_f32_e32 v27, v27, v31
	v_cvt_pk_bf16_f32 v27, v30, v27
	v_mul_f32_e32 v30, 0xbdd2d3e7, v20
	v_fmaak_f32 v30, v20, v30, 0xc0135761
	v_mul_f32_e32 v30, v20, v30
	v_exp_f32_e32 v30, v30
	global_store_dwordx4 v[28:29], v[24:27], off
	v_add_f32_e32 v30, 1.0, v30
	v_rcp_f32_e32 v30, v30
	s_nop 0
	v_mul_f32_e32 v20, v20, v30
	v_mul_f32_e32 v30, 0xbdd2d3e7, v16
	v_fmaak_f32 v30, v16, v30, 0xc0135761
	v_mul_f32_e32 v30, v16, v30
	v_exp_f32_e32 v30, v30
	s_nop 0
	v_add_f32_e32 v30, 1.0, v30
	v_rcp_f32_e32 v30, v30
	s_nop 0
	v_mul_f32_e32 v30, v16, v30
	v_mul_f32_e32 v16, 0xbdd2d3e7, v21
	v_fmaak_f32 v16, v21, v16, 0xc0135761
	v_mul_f32_e32 v16, v21, v16
	v_exp_f32_e32 v16, v16
	s_nop 0
	v_add_f32_e32 v16, 1.0, v16
	v_rcp_f32_e32 v16, v16
	s_nop 0
	v_mul_f32_e32 v16, v21, v16
	v_mul_f32_e32 v21, 0xbdd2d3e7, v17
	v_fmaak_f32 v21, v17, v21, 0xc0135761
	v_mul_f32_e32 v21, v17, v21
	v_exp_f32_e32 v21, v21
	v_cvt_pk_bf16_f32 v16, v20, v16
	v_add_f32_e32 v21, 1.0, v21
	v_rcp_f32_e32 v21, v21
	s_nop 0
	v_mul_f32_e32 v21, v17, v21
	v_mul_f32_e32 v17, 0xbdd2d3e7, v22
	v_fmaak_f32 v17, v22, v17, 0xc0135761
	v_mul_f32_e32 v17, v22, v17
	v_exp_f32_e32 v17, v17
	s_nop 0
	v_add_f32_e32 v17, 1.0, v17
	v_rcp_f32_e32 v17, v17
	s_nop 0
	v_mul_f32_e32 v17, v22, v17
	v_mul_f32_e32 v22, 0xbdd2d3e7, v18
	v_fmaak_f32 v22, v18, v22, 0xc0135761
	v_mul_f32_e32 v22, v18, v22
	v_exp_f32_e32 v22, v22
	s_nop 0
	v_add_f32_e32 v22, 1.0, v22
	v_rcp_f32_e32 v22, v22
	s_nop 0
	v_mul_f32_e32 v22, v18, v22
	v_mul_f32_e32 v18, 0xbdd2d3e7, v23
	v_fmaak_f32 v18, v23, v18, 0xc0135761
	v_mul_f32_e32 v18, v23, v18
	v_exp_f32_e32 v18, v18
	s_nop 0
	v_add_f32_e32 v18, 1.0, v18
	v_rcp_f32_e32 v18, v18
	s_nop 0
	v_mul_f32_e32 v18, v23, v18
	v_mul_f32_e32 v23, 0xbdd2d3e7, v19
	v_fmaak_f32 v23, v19, v23, 0xc0135761
	v_mul_f32_e32 v23, v19, v23
	v_exp_f32_e32 v23, v23
	v_cvt_pk_bf16_f32 v17, v17, v18
	v_cvt_pk_bf16_f32 v18, v30, v21
	v_add_f32_e32 v23, 1.0, v23
	v_rcp_f32_e32 v23, v23
	s_nop 0
	v_mul_f32_e32 v19, v19, v23
	v_cvt_pk_bf16_f32 v19, v22, v19
	global_store_dwordx4 v[28:29], v[16:19], off offset:256
	s_cbranch_vccnz .LBB0_656
	v_lshlrev_b32_e32 v21, 16, v16
	v_and_b32_e32 v29, 0xffff0000, v16
	v_lshlrev_b32_e32 v20, 16, v24
	v_and_b32_e32 v22, 0xffff0000, v24
	v_lshlrev_b32_e32 v24, 16, v25
	v_and_b32_e32 v28, 0xffff0000, v25
	v_mov_b32_e32 v23, v21
	v_mov_b32_e32 v25, v29
	v_lshlrev_b32_e32 v31, 16, v17
	v_and_b32_e32 v51, 0xffff0000, v17
	v_pk_mul_f32 v[56:57], v[20:21], v[20:21]
	v_pk_mul_f32 v[58:59], v[22:23], v[22:23]
	v_pk_mul_f32 v[60:61], v[24:25], v[24:25]
	v_pk_mul_f32 v[62:63], v[28:29], v[28:29]
	v_pk_add_f32 v[22:23], v[20:21], v[22:23]
	v_pk_add_f32 v[24:25], v[28:29], v[24:25]
	v_lshlrev_b32_e32 v30, 16, v26
	v_and_b32_e32 v16, 0xffff0000, v26
	v_lshlrev_b32_e32 v26, 16, v27
	v_and_b32_e32 v50, 0xffff0000, v27
	v_mov_b32_e32 v17, v31
	v_mov_b32_e32 v27, v51
	v_mov_b32_e32 v23, v57
	v_mov_b32_e32 v25, v63
	v_pk_mul_f32 v[64:65], v[30:31], v[30:31]
	v_pk_mul_f32 v[66:67], v[16:17], v[16:17]
	v_pk_mul_f32 v[70:71], v[50:51], v[50:51]
	v_pk_add_f32 v[22:23], v[22:23], v[24:25]
	v_pk_add_f32 v[16:17], v[30:31], v[16:17]
	v_pk_add_f32 v[24:25], v[50:51], v[26:27]
	v_mov_b32_e32 v17, v65
	v_mov_b32_e32 v25, v71
	v_pk_add_f32 v[16:17], v[16:17], v[24:25]
	v_pk_mov_b32 v[20:21], v[20:21], v[56:57] op_sel:[1,0]
	v_pk_add_f32 v[16:17], v[22:23], v[16:17]
	v_pk_mov_b32 v[22:23], v[28:29], v[58:59] op_sel:[1,0]
	v_pk_mov_b32 v[24:25], v[50:51], v[62:63] op_sel:[1,0]
	v_pk_add_f32 v[20:21], v[20:21], v[22:23]
	v_pk_mov_b32 v[22:23], v[30:31], v[60:61] op_sel:[1,0]
	v_lshlrev_b32_e32 v53, 16, v19
	v_lshlrev_b32_e32 v52, 16, v18
	v_and_b32_e32 v19, 0xffff0000, v19
	v_and_b32_e32 v18, 0xffff0000, v18
	v_pk_add_f32 v[22:23], v[22:23], v[24:25]
	v_pk_mul_f32 v[54:55], v[18:19], v[18:19]
	v_pk_mul_f32 v[68:69], v[26:27], v[26:27]
	v_pk_add_f32 v[20:21], v[20:21], v[22:23]
	v_mov_b32_e32 v22, v52
	v_mov_b32_e32 v23, v64
	v_mov_b32_e32 v24, v18
	v_mov_b32_e32 v25, v66
	v_pk_fma_f32 v[54:55], v[52:53], v[52:53], v[54:55]
	v_pk_add_f32 v[22:23], v[22:23], v[24:25]
	v_pk_mov_b32 v[24:25], v[52:53], v[68:69] op_sel:[1,0]
	v_pk_mov_b32 v[18:19], v[18:19], v[70:71] op_sel:[1,0]
	v_pk_add_f32 v[54:55], v[54:55], v[54:55] op_sel_hi:[0,1]
	v_pk_add_f32 v[18:19], v[24:25], v[18:19]
	v_mov_b32_e32 v54, v145
	v_pk_add_f32 v[18:19], v[22:23], v[18:19]
	v_pk_add_f32 v[16:17], v[16:17], v[54:55]
	v_pk_add_f32 v[18:19], v[20:21], v[18:19]
	s_nop 0
	v_pk_add_f32 v[16:17], v[18:19], v[16:17]
	ds_bpermute_b32 v18, v180, v16
	ds_bpermute_b32 v19, v180, v17
	s_waitcnt lgkmcnt(0)
	v_pk_add_f32 v[16:17], v[16:17], v[18:19]
	ds_bpermute_b32 v18, v179, v16
	ds_bpermute_b32 v19, v179, v17
	s_and_saveexec_b64 s[4:5], s[38:39]
	s_cbranch_execz .LBB0_655
	v_lshlrev_b64 v[20:21], 8, v[48:49]
	s_waitcnt lgkmcnt(0)
	v_pk_add_f32 v[16:17], v[16:17], v[18:19]
	v_lshl_add_u64 v[18:19], s[16:17], 0, v[20:21]
	v_lshl_add_u64 v[18:19], s[50:51], 3, v[18:19]
	global_store_dwordx2 v[18:19], v[16:17], off

.LBB0_656:
	v_pk_add_f32 v[12:13], v[12:13], v[44:45]
	v_pk_add_f32 v[8:9], v[8:9], v[40:41]
	v_mul_f32_e32 v20, 0xbdd2d3e7, v12
	v_mul_f32_e32 v21, 0xbdd2d3e7, v8
	v_mul_f32_e32 v22, 0xbdd2d3e7, v13
	v_fmaak_f32 v20, v12, v20, 0xc0135761
	v_fmaak_f32 v21, v8, v21, 0xc0135761
	v_fmaak_f32 v22, v13, v22, 0xc0135761
	v_mul_f32_e32 v20, v12, v20
	v_mul_f32_e32 v21, v8, v21
	v_mul_f32_e32 v22, v13, v22
	v_exp_f32_e32 v20, v20
	v_exp_f32_e32 v21, v21
	v_exp_f32_e32 v22, v22
	v_mul_f32_e32 v23, 0xbdd2d3e7, v9
	v_add_f32_e32 v20, 1.0, v20
	v_add_f32_e32 v21, 1.0, v21
	v_add_f32_e32 v22, 1.0, v22
	v_rcp_f32_e32 v20, v20
	v_rcp_f32_e32 v21, v21
	v_rcp_f32_e32 v22, v22
	v_fmaak_f32 v23, v9, v23, 0xc0135761
	v_mul_f32_e32 v23, v9, v23
	v_pk_add_f32 v[14:15], v[14:15], v[46:47]
	v_pk_add_f32 v[10:11], v[10:11], v[42:43]
	v_exp_f32_e32 v23, v23
	v_mul_f32_e32 v12, v12, v20
	v_mul_f32_e32 v20, v8, v21
	v_mul_f32_e32 v8, v13, v22
	v_mul_f32_e32 v21, 0xbdd2d3e7, v14
	v_mul_f32_e32 v22, 0xbdd2d3e7, v10
	v_fmaak_f32 v21, v14, v21, 0xc0135761
	v_fmaak_f32 v22, v10, v22, 0xc0135761
	v_mul_f32_e32 v21, v14, v21
	v_mul_f32_e32 v22, v10, v22
	v_add_f32_e32 v13, 1.0, v23
	v_rcp_f32_e32 v13, v13
	v_exp_f32_e32 v21, v21
	v_exp_f32_e32 v22, v22
	v_mul_f32_e32 v23, 0xbdd2d3e7, v11
	v_mul_f32_e32 v13, v9, v13
	v_add_f32_e32 v9, 1.0, v21
	v_add_f32_e32 v21, 1.0, v22
	v_mul_f32_e32 v22, 0xbdd2d3e7, v15
	v_fmaak_f32 v22, v15, v22, 0xc0135761
	v_fmaak_f32 v23, v11, v23, 0xc0135761
	v_mul_f32_e32 v22, v15, v22
	v_mul_f32_e32 v23, v11, v23
	v_exp_f32_e32 v22, v22
	v_exp_f32_e32 v23, v23
	v_rcp_f32_e32 v9, v9
	v_rcp_f32_e32 v21, v21
	v_add_f32_e32 v22, 1.0, v22
	v_add_f32_e32 v23, 1.0, v23
	v_rcp_f32_e32 v22, v22
	v_rcp_f32_e32 v23, v23
	v_add_u32_e32 v16, 0xb0, v172
	v_ashrrev_i32_e32 v17, 31, v16
	s_waitcnt lgkmcnt(0)
	v_lshlrev_b64 v[18:19], 13, v[16:17]
	v_mul_f32_e32 v9, v14, v9
	v_mul_f32_e32 v14, v10, v21
	v_mul_f32_e32 v10, v15, v22
	v_mul_f32_e32 v11, v11, v23
	v_pk_add_f32 v[4:5], v[4:5], v[36:37]
	v_pk_add_f32 v[0:1], v[0:1], v[32:33]
	v_cvt_pk_bf16_f32 v8, v12, v8
	v_cvt_pk_bf16_f32 v9, v9, v10
	v_cvt_pk_bf16_f32 v10, v20, v13
	v_cvt_pk_bf16_f32 v11, v14, v11
	v_lshl_add_u64 v[12:13], s[10:11], 0, v[18:19]
	v_mul_f32_e32 v14, 0xbdd2d3e7, v4
	v_mul_f32_e32 v15, 0xbdd2d3e7, v0
	v_mul_f32_e32 v18, 0xbdd2d3e7, v5
	v_fmaak_f32 v14, v4, v14, 0xc0135761
	v_fmaak_f32 v15, v0, v15, 0xc0135761
	v_fmaak_f32 v18, v5, v18, 0xc0135761
	v_mul_f32_e32 v14, v4, v14
	v_mul_f32_e32 v15, v0, v15
	v_mul_f32_e32 v18, v5, v18
	v_exp_f32_e32 v14, v14
	v_exp_f32_e32 v15, v15
	v_exp_f32_e32 v18, v18
	v_mul_f32_e32 v19, 0xbdd2d3e7, v1
	v_add_f32_e32 v14, 1.0, v14
	v_add_f32_e32 v15, 1.0, v15
	v_add_f32_e32 v18, 1.0, v18
	v_rcp_f32_e32 v14, v14
	v_rcp_f32_e32 v15, v15
	v_rcp_f32_e32 v18, v18
	v_fmaak_f32 v19, v1, v19, 0xc0135761
	v_mul_f32_e32 v19, v1, v19
	v_pk_add_f32 v[6:7], v[6:7], v[38:39]
	v_pk_add_f32 v[2:3], v[2:3], v[34:35]
	v_exp_f32_e32 v19, v19
	v_mul_f32_e32 v4, v4, v14
	v_mul_f32_e32 v14, v0, v15
	v_mul_f32_e32 v0, v5, v18
	v_mul_f32_e32 v15, 0xbdd2d3e7, v6
	v_mul_f32_e32 v18, 0xbdd2d3e7, v2
	v_fmaak_f32 v15, v6, v15, 0xc0135761
	v_fmaak_f32 v18, v2, v18, 0xc0135761
	v_mul_f32_e32 v15, v6, v15
	v_mul_f32_e32 v18, v2, v18
	v_add_f32_e32 v5, 1.0, v19
	v_rcp_f32_e32 v5, v5
	v_exp_f32_e32 v15, v15
	v_exp_f32_e32 v18, v18
	v_mul_f32_e32 v19, 0xbdd2d3e7, v3
	v_mul_f32_e32 v5, v1, v5
	v_add_f32_e32 v1, 1.0, v15
	v_add_f32_e32 v15, 1.0, v18
	v_mul_f32_e32 v18, 0xbdd2d3e7, v7
	v_fmaak_f32 v18, v7, v18, 0xc0135761
	v_fmaak_f32 v19, v3, v19, 0xc0135761
	v_mul_f32_e32 v18, v7, v18
	v_mul_f32_e32 v19, v3, v19
	v_exp_f32_e32 v18, v18
	v_exp_f32_e32 v19, v19
	v_rcp_f32_e32 v1, v1
	v_rcp_f32_e32 v15, v15
	v_add_f32_e32 v18, 1.0, v18
	v_add_f32_e32 v19, 1.0, v19
	v_rcp_f32_e32 v18, v18
	v_rcp_f32_e32 v19, v19
	v_mul_f32_e32 v1, v6, v1
	v_mul_f32_e32 v6, v2, v15
	v_mul_f32_e32 v2, v7, v18
	v_mul_f32_e32 v3, v3, v19
	v_lshl_add_u64 v[12:13], v[170:171], 1, v[12:13]
	v_cvt_pk_bf16_f32 v0, v4, v0
	v_cvt_pk_bf16_f32 v1, v1, v2
	v_cvt_pk_bf16_f32 v2, v14, v5
	v_cvt_pk_bf16_f32 v3, v6, v3
	s_and_b64 vcc, exec, s[40:41]
	global_store_dwordx4 v[12:13], v[8:11], off
	global_store_dwordx4 v[12:13], v[0:3], off offset:256
	s_cbranch_vccnz .LBB0_660
	v_lshlrev_b32_e32 v5, 16, v0
	v_and_b32_e32 v13, 0xffff0000, v0
	v_lshlrev_b32_e32 v4, 16, v8
	v_and_b32_e32 v6, 0xffff0000, v8
	v_lshlrev_b32_e32 v8, 16, v9
	v_and_b32_e32 v12, 0xffff0000, v9
	v_mov_b32_e32 v7, v5
	v_mov_b32_e32 v9, v13
	v_lshlrev_b32_e32 v15, 16, v1
	v_and_b32_e32 v19, 0xffff0000, v1
	v_pk_mul_f32 v[24:25], v[4:5], v[4:5]
	v_pk_mul_f32 v[26:27], v[6:7], v[6:7]
	v_pk_mul_f32 v[28:29], v[8:9], v[8:9]
	v_pk_mul_f32 v[30:31], v[12:13], v[12:13]
	v_pk_add_f32 v[6:7], v[4:5], v[6:7]
	v_pk_add_f32 v[8:9], v[12:13], v[8:9]
	v_lshlrev_b32_e32 v14, 16, v10
	v_and_b32_e32 v0, 0xffff0000, v10
	v_lshlrev_b32_e32 v10, 16, v11
	v_and_b32_e32 v18, 0xffff0000, v11
	v_mov_b32_e32 v1, v15
	v_mov_b32_e32 v11, v19
	v_mov_b32_e32 v7, v25
	v_mov_b32_e32 v9, v31
	v_pk_mul_f32 v[32:33], v[14:15], v[14:15]
	v_pk_mul_f32 v[34:35], v[0:1], v[0:1]
	v_pk_mul_f32 v[38:39], v[18:19], v[18:19]
	v_pk_add_f32 v[6:7], v[6:7], v[8:9]
	v_pk_add_f32 v[0:1], v[14:15], v[0:1]
	v_pk_add_f32 v[8:9], v[18:19], v[10:11]
	v_mov_b32_e32 v1, v33
	v_mov_b32_e32 v9, v39
	v_pk_add_f32 v[0:1], v[0:1], v[8:9]
	v_pk_mov_b32 v[4:5], v[4:5], v[24:25] op_sel:[1,0]
	v_pk_add_f32 v[0:1], v[6:7], v[0:1]
	v_pk_mov_b32 v[6:7], v[12:13], v[26:27] op_sel:[1,0]
	v_pk_mov_b32 v[8:9], v[18:19], v[30:31] op_sel:[1,0]
	v_pk_add_f32 v[4:5], v[4:5], v[6:7]
	v_pk_mov_b32 v[6:7], v[14:15], v[28:29] op_sel:[1,0]
	v_lshlrev_b32_e32 v21, 16, v3
	v_lshlrev_b32_e32 v20, 16, v2
	v_and_b32_e32 v3, 0xffff0000, v3
	v_and_b32_e32 v2, 0xffff0000, v2
	v_pk_add_f32 v[6:7], v[6:7], v[8:9]
	v_pk_mul_f32 v[22:23], v[2:3], v[2:3]
	v_pk_mul_f32 v[36:37], v[10:11], v[10:11]
	v_pk_add_f32 v[4:5], v[4:5], v[6:7]
	v_mov_b32_e32 v6, v20
	v_mov_b32_e32 v7, v32
	v_mov_b32_e32 v8, v2
	v_mov_b32_e32 v9, v34
	v_pk_fma_f32 v[22:23], v[20:21], v[20:21], v[22:23]
	v_pk_add_f32 v[6:7], v[6:7], v[8:9]
	v_pk_mov_b32 v[8:9], v[20:21], v[36:37] op_sel:[1,0]
	v_pk_mov_b32 v[2:3], v[2:3], v[38:39] op_sel:[1,0]
	v_pk_add_f32 v[22:23], v[22:23], v[22:23] op_sel_hi:[0,1]
	v_pk_add_f32 v[2:3], v[8:9], v[2:3]
	v_mov_b32_e32 v22, v145
	v_pk_add_f32 v[2:3], v[6:7], v[2:3]
	v_pk_add_f32 v[0:1], v[0:1], v[22:23]
	v_pk_add_f32 v[2:3], v[4:5], v[2:3]
	s_nop 0
	v_pk_add_f32 v[0:1], v[2:3], v[0:1]
	ds_bpermute_b32 v2, v180, v0
	ds_bpermute_b32 v3, v180, v1
	s_waitcnt lgkmcnt(0)
	v_pk_add_f32 v[0:1], v[0:1], v[2:3]
	ds_bpermute_b32 v2, v179, v0
	ds_bpermute_b32 v3, v179, v1
	s_and_saveexec_b64 s[4:5], s[38:39]
	s_cbranch_execz .LBB0_659
	v_lshlrev_b64 v[4:5], 8, v[16:17]
	s_waitcnt lgkmcnt(0)
	v_pk_add_f32 v[0:1], v[0:1], v[2:3]
	v_lshl_add_u64 v[2:3], s[16:17], 0, v[4:5]
	v_lshl_add_u64 v[2:3], s[50:51], 3, v[2:3]
	global_store_dwordx2 v[2:3], v[0:1], off

.LBB0_777:
	s_andn2_b64 vcc, exec, s[4:5]
	s_cbranch_vccnz .LBB0_788
	v_ashrrev_i32_e32 v1, 3, v32
	v_and_b32_e32 v0, -4, v1
	v_or_b32_e32 v1, 3, v1
	s_movk_i32 s4, 0x800
	v_mul_lo_u32 v7, v1, s66
	v_ashrrev_i32_e32 v1, 31, v0
	v_cmp_gt_i32_e64 s[38:39], s4, v32
	v_mul_lo_u32 v6, v0, s66
	v_lshl_add_u64 v[0:1], v[0:1], 1, s[58:59]
	s_mov_b64 s[4:5], 0x2300000
	v_and_b32_e32 v2, 31, v58
	v_lshl_add_u64 v[4:5], v[0:1], 0, s[4:5]
	v_readlane_b32 s4, v254, 43
	v_cmp_gt_i32_e64 s[36:37], s72, v32
	v_mad_u32_u24 v3, v2, s66, 0
	v_lshl_add_u32 v22, v58, 2, s94
	v_lshlrev_b64 v[0:1], 4, v[32:33]
	v_add_u32_e32 v23, 0, v7
	v_add_u32_e32 v24, 0, v6
	s_mov_b32 s15, s4
	v_readlane_b32 s5, v254, 44
	v_and_b32_e32 v25, 31, v58
	v_lshrrev_b32_e32 v30, 5, v58
	s_lshr_b32 s4, s92, 6
	s_and_b32 s5, s4, 1
	s_lshr_b32 s4, s4, 1
	s_lshl_b32 s5, s5, 5
	s_lshl_b32 s4, s4, 5
	v_add_u32_e32 v31, s5, v25
	v_mul_u32_u24_e32 v31, 0x210, v31
	v_lshl_add_u32 v31, v30, 4, v31
	v_add_u32_e32 v31, s67, v31
	v_add_u32_e32 v72, s4, v25
	v_mul_u32_u24_e32 v73, 0x210, v72
	v_lshl_add_u32 v73, v30, 4, v73
	v_ashrrev_i32_e32 v130, 5, v32
	v_and_b32_e32 v131, 0x7c, v22
	v_mul_lo_u32 v124, v130, s66
	v_lshlrev_b32_e32 v131, 2, v131
	v_add3_u32 v125, s67, v124, v131
	v_add3_u32 v124, 0, v124, v131
	v_mov_b32_e32 v144, v131
	v_ashrrev_i32_e32 v131, 31, v130
	v_lshlrev_b64 v[132:133], 13, v[130:131]
	v_lshl_add_u64 v[132:133], v[132:133], 0, v[144:145]
	s_mov_b32 s26, 0
	s_load_dwordx2 s[4:5], s[0:1], 0xb0
	s_load_dwordx2 s[12:13], s[0:1], 0xb8
	s_lshr_b32 s17, s15, 4
	s_ashr_i32 s8, s15, 8
	s_and_b32 s9, s17, 1
	s_lshl_b32 s16, s8, 1
	s_or_b32 s24, s16, s9
	s_ashr_i32 s25, s24, 31
	s_waitcnt lgkmcnt(0)
	v_lshl_add_u64 v[126:127], s[12:13], 0, v[0:1]
	s_lshl_b64 s[12:13], s[24:25], 16
	v_lshl_add_u64 v[126:127], v[126:127], 0, s[12:13]
	s_mov_b64 s[24:25], 0x2000
	global_load_dwordx4 v[76:79], v[126:127], off
	v_lshl_add_u64 v[126:127], v[126:127], 0, s[24:25]
	global_load_dwordx4 v[80:83], v[126:127], off
	v_lshl_add_u64 v[126:127], v[126:127], 0, s[24:25]
	global_load_dwordx4 v[84:87], v[126:127], off
	v_lshl_add_u64 v[126:127], v[126:127], 0, s[24:25]
	global_load_dwordx4 v[88:91], v[126:127], off
	v_lshl_add_u64 v[126:127], v[126:127], 0, s[24:25]
	global_load_dwordx4 v[92:95], v[126:127], off
	v_lshl_add_u64 v[126:127], v[126:127], 0, s[24:25]
	global_load_dwordx4 v[96:99], v[126:127], off
	v_lshl_add_u64 v[126:127], v[126:127], 0, s[24:25]
	global_load_dwordx4 v[100:103], v[126:127], off
	v_lshl_add_u64 v[126:127], v[126:127], 0, s[24:25]
	global_load_dwordx4 v[104:107], v[126:127], off
	s_lshl_b32 s10, s15, 6
	s_and_b32 s16, s10, 0x3c0
	s_lshl_b32 s10, s17, 7
	s_ashr_i32 s9, s8, 31
	s_and_b32 s17, s10, 0x780
	s_lshl_b64 s[12:13], s[8:9], 23
	s_add_u32 s4, s4, s12
	s_addc_u32 s5, s5, s13
	s_lshl_b32 s12, s16, 13
	s_add_u32 s4, s4, s12
	s_addc_u32 s5, s5, 0
	s_lshl_b32 s12, s17, 2
	s_add_u32 s4, s4, s12
	s_addc_u32 s5, s5, 0
	v_lshl_add_u64 v[128:129], s[4:5], 0, v[132:133]
	s_mov_b64 s[24:25], 0x20000
	global_load_dwordx4 v[108:111], v[128:129], off
	v_lshl_add_u64 v[128:129], v[128:129], 0, s[24:25]
	global_load_dwordx4 v[112:115], v[128:129], off
	v_lshl_add_u64 v[128:129], v[128:129], 0, s[24:25]
	global_load_dwordx4 v[116:119], v[128:129], off
	v_lshl_add_u64 v[128:129], v[128:129], 0, s[24:25]
	global_load_dwordx4 v[120:123], v[128:129], off
.LBB0_779:
	s_waitcnt vmcnt(11)
	ds_write_b128 v124, v[76:79]
	s_waitcnt vmcnt(10)
	ds_write_b128 v124, v[80:83] offset:8448
	s_waitcnt vmcnt(9)
	ds_write_b128 v124, v[84:87] offset:16896
	s_waitcnt vmcnt(8)
	ds_write_b128 v124, v[88:91] offset:25344
	s_waitcnt vmcnt(7)
	ds_write_b128 v124, v[92:95] offset:33792
	s_waitcnt vmcnt(6)
	ds_write_b128 v124, v[96:99] offset:42240
	s_waitcnt vmcnt(5)
	ds_write_b128 v124, v[100:103] offset:50688
	s_waitcnt vmcnt(4)
	ds_write_b128 v124, v[104:107] offset:59136
	s_waitcnt vmcnt(3)
	ds_write_b128 v125, v[108:111]
	s_waitcnt vmcnt(2)
	ds_write_b128 v125, v[112:115] offset:8448
	s_waitcnt vmcnt(1)
	ds_write_b128 v125, v[116:119] offset:16896
	s_waitcnt vmcnt(0)
	ds_write_b128 v125, v[120:123] offset:25344
	s_cmp_eq_u32 s26, 0
	s_cbranch_scc1 .Lfold_nost
	global_store_dwordx2 v[74:75], v[46:47], off
	global_store_dwordx2 v[74:75], v[48:49], off offset:16
	global_store_dwordx2 v[74:75], v[50:51], off offset:32
	global_store_dwordx2 v[74:75], v[52:53], off offset:48
.Lfold_nost:
	s_mov_b32 s26, 1
	s_lshl_b64 s[4:5], s[8:9], 11
	s_or_b32 s4, s4, s17
	s_lshl_b32 s4, s4, 11
	s_lshl_b32 s5, s16, 1
	s_add_i32 s4, s4, s5
	s_lshr_b32 s5, s92, 6
	s_and_b32 s5, s5, 1
	s_lshl_b32 s5, s5, 6
	s_add_i32 s4, s4, s5
	s_add_u32 s24, s58, 0x2300000
	s_addc_u32 s25, s59, 0
	v_lshlrev_b32_e32 v74, 11, v72
	v_lshl_add_u32 v74, v30, 3, v74
	v_add_u32_e32 v74, s4, v74
	v_mov_b32_e32 v75, 0
	v_lshl_add_u64 v[74:75], s[24:25], 0, v[74:75]
	v_mov_b32_e32 v6, 0
	v_mov_b32_e32 v7, v6
	v_mov_b32_e32 v8, v6
	v_mov_b32_e32 v9, v6
	v_mov_b32_e32 v10, v6
	v_mov_b32_e32 v11, v6
	v_mov_b32_e32 v12, v6
	v_mov_b32_e32 v13, v6
	v_mov_b32_e32 v14, v6
	v_mov_b32_e32 v15, v6
	v_mov_b32_e32 v16, v6
	v_mov_b32_e32 v17, v6
	v_mov_b32_e32 v18, v6
	v_mov_b32_e32 v19, v6
	v_mov_b32_e32 v20, v6
	v_mov_b32_e32 v21, v6
	s_waitcnt lgkmcnt(0)
	s_barrier
	v_readlane_b32 s4, v254, 45
	s_nop 1
	s_add_i32 s15, s15, s4
	s_cmpk_gt_i32 s15, 0x3ff
	s_cbranch_scc1 .Lfold_noload
	s_load_dwordx2 s[4:5], s[0:1], 0xb0
	s_load_dwordx2 s[12:13], s[0:1], 0xb8
	s_lshr_b32 s17, s15, 4
	s_ashr_i32 s8, s15, 8
	s_and_b32 s9, s17, 1
	s_lshl_b32 s16, s8, 1
	s_or_b32 s24, s16, s9
	s_ashr_i32 s25, s24, 31
	s_waitcnt lgkmcnt(0)
	v_lshl_add_u64 v[126:127], s[12:13], 0, v[0:1]
	s_lshl_b64 s[12:13], s[24:25], 16
	v_lshl_add_u64 v[126:127], v[126:127], 0, s[12:13]
	s_mov_b64 s[24:25], 0x2000
	global_load_dwordx4 v[76:79], v[126:127], off
	v_lshl_add_u64 v[126:127], v[126:127], 0, s[24:25]
	global_load_dwordx4 v[80:83], v[126:127], off
	v_lshl_add_u64 v[126:127], v[126:127], 0, s[24:25]
	global_load_dwordx4 v[84:87], v[126:127], off
	v_lshl_add_u64 v[126:127], v[126:127], 0, s[24:25]
	global_load_dwordx4 v[88:91], v[126:127], off
	v_lshl_add_u64 v[126:127], v[126:127], 0, s[24:25]
	global_load_dwordx4 v[92:95], v[126:127], off
	v_lshl_add_u64 v[126:127], v[126:127], 0, s[24:25]
	global_load_dwordx4 v[96:99], v[126:127], off
	v_lshl_add_u64 v[126:127], v[126:127], 0, s[24:25]
	global_load_dwordx4 v[100:103], v[126:127], off
	v_lshl_add_u64 v[126:127], v[126:127], 0, s[24:25]
	global_load_dwordx4 v[104:107], v[126:127], off
	s_lshl_b32 s10, s15, 6
	s_and_b32 s16, s10, 0x3c0
	s_lshl_b32 s10, s17, 7
	s_ashr_i32 s9, s8, 31
	s_and_b32 s17, s10, 0x780
	s_lshl_b64 s[12:13], s[8:9], 23
	s_add_u32 s4, s4, s12
	s_addc_u32 s5, s5, s13
	s_lshl_b32 s12, s16, 13
	s_add_u32 s4, s4, s12
	s_addc_u32 s5, s5, 0
	s_lshl_b32 s12, s17, 2
	s_add_u32 s4, s4, s12
	s_addc_u32 s5, s5, 0
	v_lshl_add_u64 v[128:129], s[4:5], 0, v[132:133]
	s_mov_b64 s[24:25], 0x20000
	global_load_dwordx4 v[108:111], v[128:129], off
	v_lshl_add_u64 v[128:129], v[128:129], 0, s[24:25]
	global_load_dwordx4 v[112:115], v[128:129], off
	v_lshl_add_u64 v[128:129], v[128:129], 0, s[24:25]
	global_load_dwordx4 v[116:119], v[128:129], off
	v_lshl_add_u64 v[128:129], v[128:129], 0, s[24:25]
	global_load_dwordx4 v[120:123], v[128:129], off
.Lfold_noload:
	ds_read_b128 v[26:29], v31
	ds_read_b128 v[34:37], v73
	ds_read_b128 v[38:41], v31 offset:32
	ds_read_b128 v[42:45], v73 offset:32
	s_waitcnt lgkmcnt(2)
	v_mfma_f32_32x32x2_f32 v[6:21], v26, v34, v[6:21]
	v_mfma_f32_32x32x2_f32 v[6:21], v27, v35, v[6:21]
	v_mfma_f32_32x32x2_f32 v[6:21], v28, v36, v[6:21]
	v_mfma_f32_32x32x2_f32 v[6:21], v29, v37, v[6:21]
	ds_read_b128 v[26:29], v31 offset:64
	ds_read_b128 v[34:37], v73 offset:64
	s_waitcnt lgkmcnt(2)
	v_mfma_f32_32x32x2_f32 v[6:21], v38, v42, v[6:21]
	v_mfma_f32_32x32x2_f32 v[6:21], v39, v43, v[6:21]
	v_mfma_f32_32x32x2_f32 v[6:21], v40, v44, v[6:21]
	v_mfma_f32_32x32x2_f32 v[6:21], v41, v45, v[6:21]
	ds_read_b128 v[38:41], v31 offset:96
	ds_read_b128 v[42:45], v73 offset:96
	s_waitcnt lgkmcnt(2)
	v_mfma_f32_32x32x2_f32 v[6:21], v26, v34, v[6:21]
	v_mfma_f32_32x32x2_f32 v[6:21], v27, v35, v[6:21]
	v_mfma_f32_32x32x2_f32 v[6:21], v28, v36, v[6:21]
	v_mfma_f32_32x32x2_f32 v[6:21], v29, v37, v[6:21]
	ds_read_b128 v[26:29], v31 offset:128
	ds_read_b128 v[34:37], v73 offset:128
	s_waitcnt lgkmcnt(2)
	v_mfma_f32_32x32x2_f32 v[6:21], v38, v42, v[6:21]
	v_mfma_f32_32x32x2_f32 v[6:21], v39, v43, v[6:21]
	v_mfma_f32_32x32x2_f32 v[6:21], v40, v44, v[6:21]
	v_mfma_f32_32x32x2_f32 v[6:21], v41, v45, v[6:21]
	ds_read_b128 v[38:41], v31 offset:160
	ds_read_b128 v[42:45], v73 offset:160
	s_waitcnt lgkmcnt(2)
	v_mfma_f32_32x32x2_f32 v[6:21], v26, v34, v[6:21]
	v_mfma_f32_32x32x2_f32 v[6:21], v27, v35, v[6:21]
	v_mfma_f32_32x32x2_f32 v[6:21], v28, v36, v[6:21]
	v_mfma_f32_32x32x2_f32 v[6:21], v29, v37, v[6:21]
	ds_read_b128 v[26:29], v31 offset:192
	ds_read_b128 v[34:37], v73 offset:192
	s_waitcnt lgkmcnt(2)
	v_mfma_f32_32x32x2_f32 v[6:21], v38, v42, v[6:21]
	v_mfma_f32_32x32x2_f32 v[6:21], v39, v43, v[6:21]
	v_mfma_f32_32x32x2_f32 v[6:21], v40, v44, v[6:21]
	v_mfma_f32_32x32x2_f32 v[6:21], v41, v45, v[6:21]
	ds_read_b128 v[38:41], v31 offset:224
	ds_read_b128 v[42:45], v73 offset:224
	s_waitcnt lgkmcnt(2)
	v_mfma_f32_32x32x2_f32 v[6:21], v26, v34, v[6:21]
	v_mfma_f32_32x32x2_f32 v[6:21], v27, v35, v[6:21]
	v_mfma_f32_32x32x2_f32 v[6:21], v28, v36, v[6:21]
	v_mfma_f32_32x32x2_f32 v[6:21], v29, v37, v[6:21]
	ds_read_b128 v[26:29], v31 offset:256
	ds_read_b128 v[34:37], v73 offset:256
	s_waitcnt lgkmcnt(2)
	v_mfma_f32_32x32x2_f32 v[6:21], v38, v42, v[6:21]
	v_mfma_f32_32x32x2_f32 v[6:21], v39, v43, v[6:21]
	v_mfma_f32_32x32x2_f32 v[6:21], v40, v44, v[6:21]
	v_mfma_f32_32x32x2_f32 v[6:21], v41, v45, v[6:21]
	ds_read_b128 v[38:41], v31 offset:288
	ds_read_b128 v[42:45], v73 offset:288
	s_waitcnt lgkmcnt(2)
	v_mfma_f32_32x32x2_f32 v[6:21], v26, v34, v[6:21]
	v_mfma_f32_32x32x2_f32 v[6:21], v27, v35, v[6:21]
	v_mfma_f32_32x32x2_f32 v[6:21], v28, v36, v[6:21]
	v_mfma_f32_32x32x2_f32 v[6:21], v29, v37, v[6:21]
	ds_read_b128 v[26:29], v31 offset:320
	ds_read_b128 v[34:37], v73 offset:320
	s_waitcnt lgkmcnt(2)
	v_mfma_f32_32x32x2_f32 v[6:21], v38, v42, v[6:21]
	v_mfma_f32_32x32x2_f32 v[6:21], v39, v43, v[6:21]
	v_mfma_f32_32x32x2_f32 v[6:21], v40, v44, v[6:21]
	v_mfma_f32_32x32x2_f32 v[6:21], v41, v45, v[6:21]
	ds_read_b128 v[38:41], v31 offset:352
	ds_read_b128 v[42:45], v73 offset:352
	s_waitcnt lgkmcnt(2)
	v_mfma_f32_32x32x2_f32 v[6:21], v26, v34, v[6:21]
	v_mfma_f32_32x32x2_f32 v[6:21], v27, v35, v[6:21]
	v_mfma_f32_32x32x2_f32 v[6:21], v28, v36, v[6:21]
	v_mfma_f32_32x32x2_f32 v[6:21], v29, v37, v[6:21]
	ds_read_b128 v[26:29], v31 offset:384
	ds_read_b128 v[34:37], v73 offset:384
	s_waitcnt lgkmcnt(2)
	v_mfma_f32_32x32x2_f32 v[6:21], v38, v42, v[6:21]
	v_mfma_f32_32x32x2_f32 v[6:21], v39, v43, v[6:21]
	v_mfma_f32_32x32x2_f32 v[6:21], v40, v44, v[6:21]
	v_mfma_f32_32x32x2_f32 v[6:21], v41, v45, v[6:21]
	ds_read_b128 v[38:41], v31 offset:416
	ds_read_b128 v[42:45], v73 offset:416
	s_waitcnt lgkmcnt(2)
	v_mfma_f32_32x32x2_f32 v[6:21], v26, v34, v[6:21]
	v_mfma_f32_32x32x2_f32 v[6:21], v27, v35, v[6:21]
	v_mfma_f32_32x32x2_f32 v[6:21], v28, v36, v[6:21]
	v_mfma_f32_32x32x2_f32 v[6:21], v29, v37, v[6:21]
	ds_read_b128 v[26:29], v31 offset:448
	ds_read_b128 v[34:37], v73 offset:448
	s_waitcnt lgkmcnt(2)
	v_mfma_f32_32x32x2_f32 v[6:21], v38, v42, v[6:21]
	v_mfma_f32_32x32x2_f32 v[6:21], v39, v43, v[6:21]
	v_mfma_f32_32x32x2_f32 v[6:21], v40, v44, v[6:21]
	v_mfma_f32_32x32x2_f32 v[6:21], v41, v45, v[6:21]
	ds_read_b128 v[38:41], v31 offset:480
	ds_read_b128 v[42:45], v73 offset:480
	s_waitcnt lgkmcnt(2)
	v_mfma_f32_32x32x2_f32 v[6:21], v26, v34, v[6:21]
	v_mfma_f32_32x32x2_f32 v[6:21], v27, v35, v[6:21]
	v_mfma_f32_32x32x2_f32 v[6:21], v28, v36, v[6:21]
	v_mfma_f32_32x32x2_f32 v[6:21], v29, v37, v[6:21]
	s_waitcnt lgkmcnt(0)
	v_mfma_f32_32x32x2_f32 v[6:21], v38, v42, v[6:21]
	v_mfma_f32_32x32x2_f32 v[6:21], v39, v43, v[6:21]
	v_mfma_f32_32x32x2_f32 v[6:21], v40, v44, v[6:21]
	v_mfma_f32_32x32x2_f32 v[6:21], v41, v45, v[6:21]
	s_nop 7
	s_nop 7
	s_nop 7
	v_cvt_pk_bf16_f32 v46, v6, v7
	v_cvt_pk_bf16_f32 v47, v8, v9
	v_cvt_pk_bf16_f32 v48, v10, v11
	v_cvt_pk_bf16_f32 v49, v12, v13
	v_cvt_pk_bf16_f32 v50, v14, v15
	v_cvt_pk_bf16_f32 v51, v16, v17
	v_cvt_pk_bf16_f32 v52, v18, v19
	v_cvt_pk_bf16_f32 v53, v20, v21
	s_barrier
	s_cmpk_gt_i32 s15, 0x3ff
	s_cbranch_scc0 .LBB0_779
	global_store_dwordx2 v[74:75], v[46:47], off
	global_store_dwordx2 v[74:75], v[48:49], off offset:16
	global_store_dwordx2 v[74:75], v[50:51], off offset:32
	global_store_dwordx2 v[74:75], v[52:53], off offset:48
	v_readlane_b32 s5, v254, 46
